# MFMA issue order: the two K-halves of each accumulator issued back to back (accumulate chain, C forwarded from the previous D), accumulators walked in a snake over the fragment grid (w_in, w_out, down
# speedup vs baseline: 1.0160x; 1.0160x over previous
; #define PG8_STAGE(bufoff, gbase, voff) do { _Pragma("unroll") for (int _i = 0; _i < 2; ++_i) \
;         __builtin_amdgcn_global_load_lds((const unsigned*)((const char*)(gbase) + (voff)[_i]), (PG8_LAS unsigned*)(lds + (bufoff) + ldsw + _i * 8192), 16, 0, 0); } while (0)
; #define PG8_LDA(dst, b, h) do { _Pragma("unroll") for (int m = 0; m < 4; ++m) _Pragma("unroll") for (int k = 0; k < 2; ++k) dst[m][k] = *(const PG8_LAS bf16x8*)(lds + PG8_SA(b, h) + aoff + m * 2048 + k * 1024); } while (0)
; #define PG8_LDB(dst, b, h) do { _Pragma("unroll") for (int n = 0; n < 2; ++n) _Pragma("unroll") for (int k = 0; k < 2; ++k) dst[n][k] = *(const PG8_LAS bf16x8*)(lds + PG8_SB(b, h) + boff + n * 2048 + k * 1024); } while (0)
; #define PG8_WAIT_V(n) asm volatile("s_waitcnt vmcnt(" #n ")" ::: "memory")
; #define PG8_WAIT_L(n) asm volatile("s_waitcnt lgkmcnt(" #n ")" ::: "memory")
; #define PG8_BAR __builtin_amdgcn_s_barrier()
; #define PG8_SCHED __builtin_amdgcn_sched_barrier(0)
; template <class Epi, class Sched, bool ALIGN_EPI = false, bool SP2 = false>
; __device__ __forceinline__ void gemm_phase(PG8_LAS unsigned char* lds, const Gemm g, const Sched& S, const Epi& E) {
;     ...
;         const bool has_next = S.next(ui + 1, nxt);
;         const char* nA = has_next ? (const char*)g.A + (size_t)nxt.pm * tstep : cA; const char* nB = has_next ? (const char*)g.Bt + (size_t)nxt.pn * tstep : cB;
;         for (int t = 0; t < nt; t += 2) {
;             const bool last = (t == nt - 2);
;             const char* a1 = cA + (size_t)(t + 1) * kstep;
;             const char* a2 = last ? nA : cA + (size_t)(t + 2) * kstep; const char* b2 = last ? nB : cB + (size_t)(t + 2) * kstep;
;             const char* a3 = a2 + kstep; const char* b3 = b2 + kstep;
;             if (last && has_next) S.a_ready(nxt);
;             if constexpr (SP2) {
;             PG8_LDB(B0, 0, 0); PG8_LDB(B1, 0, 1); PG8_SCHED; PG8_LDA(At, 0, 0); PG8_STAGE(PG8_SA(1, 1), a1 + hstep, voffA);
;             PG8_WAIT_V(8); PG8_WAIT_L(0); PG8_BAR; PG8_MMA(0, 0, At, B0); PG8_MMA(0, 1, At, B1); PG8_BAR; PG8_SCHED;
;             PG8_LDA(At, 0, 1); PG8_STAGE(PG8_SB(0, 0), b2, voffB); PG8_STAGE(PG8_SB(0, 1), b2 + hstepB, voffB); PG8_STAGE(PG8_SA(0, 0), a2, voffA);
;             PG8_WAIT_V(8); PG8_WAIT_L(0); PG8_BAR; PG8_MMA(1, 0, At, B0); PG8_MMA(1, 1, At, B1); PG8_BAR; PG8_SCHED;
.LBB0_169:
	s_add_u32 s93, s46, 0x100
	s_addc_u32 s94, s47, 0
	s_ashr_i32 s69, s68, 31
	s_lshl_b64 s[4:5], s[68:69], 20
	s_add_u32 s76, s52, s4
	s_addc_u32 s77, s53, s5
	s_and_b64 s[4:5], s[38:39], exec
	s_cselect_b32 s4, s77, s71
	s_cselect_b32 s5, s76, s70
	s_ashr_i32 s63, s62, 31
	s_lshl_b64 s[6:7], s[62:63], 20
	v_readlane_b32 s8, v249, 19
	v_readlane_b32 s9, v249, 20
	s_add_u32 s72, s8, s6
	s_addc_u32 s73, s9, s7
	s_and_b64 s[6:7], s[38:39], exec
	s_cselect_b32 s6, s73, s47
	s_cselect_b32 s7, s72, s46
	s_add_u32 s8, s70, 0x80080
	s_addc_u32 s9, s71, 0
	v_lshl_add_u64 v[144:145], s[8:9], 0, v[140:141]
	v_lshl_add_u64 v[146:147], s[8:9], 0, v[142:143]
	s_mov_b32 s8, -2
	s_mov_b64 s[46:47], 0
	v_add_u32_e32 v186, 0x10000, v139
	v_add_u32_e32 v187, 0x14000, v139
	v_add_u32_e32 v198, 0x18000, v139
	v_add_u32_e32 v199, 0x1c000, v139
	s_add_u32 s9, s70, s46
	s_addc_u32 s10, s71, s47
	s_add_u32 s9, s9, 0x100
	s_addc_u32 s10, s10, 0
	s_add_u32 s100, s9, 0x7ff80
	s_addc_u32 s101, s10, 0
	s_add_u32 s11, s93, s46
	s_addc_u32 s12, s94, s47
	s_add_i32 s13, 0, 0x10000
	s_cmpk_eq_i32 s46, 0xf00
	s_cselect_b32 s85, s4, s10
	s_cselect_b32 s84, s5, s9
	s_cselect_b32 s81, s6, s12
	s_cselect_b32 s80, s7, s11
	s_add_i32 s9, 0, 0x14000
	ds_read_b128 v[148:151], v186
	ds_read_b128 v[152:155], v186 offset:1024
	ds_read_b128 v[156:159], v186 offset:2048
	ds_read_b128 v[160:163], v186 offset:3072
	ds_read_b128 v[166:169], v187
	ds_read_b128 v[170:173], v187 offset:1024
	ds_read_b128 v[174:177], v187 offset:2048
	ds_read_b128 v[178:181], v187 offset:3072
	s_add_i32 m0, s1, 0xc000
	ds_read_b128 v[182:185], v165
	ds_read_b128 v[206:209], v165 offset:1024
	ds_read_b128 v[210:213], v165 offset:2048
	ds_read_b128 v[214:217], v165 offset:3072
	ds_read_b128 v[218:221], v165 offset:4096
	ds_read_b128 v[236:239], v165 offset:5120
	ds_read_b128 v[240:243], v165 offset:6144
	ds_read_b128 v[244:247], v165 offset:7168
	global_load_lds_dwordx4 v140, s[100:101]
	s_add_i32 m0, s1, 0xe000
	s_nop 0
	global_load_lds_dwordx4 v142, s[100:101]
	s_waitcnt vmcnt(8)
	s_waitcnt lgkmcnt(0)
	s_barrier
	v_mfma_f32_16x16x32_bf16 v[126:129], v[148:151], v[182:185], 0
	v_mfma_f32_16x16x32_bf16 v[126:129], v[152:155], v[206:209], v[126:129]
	v_mfma_f32_16x16x32_bf16 v[118:121], v[148:151], v[210:213], 0
	v_mfma_f32_16x16x32_bf16 v[118:121], v[152:155], v[214:217], v[118:121]
	v_mfma_f32_16x16x32_bf16 v[114:117], v[156:159], v[210:213], 0
	v_mfma_f32_16x16x32_bf16 v[114:117], v[160:163], v[214:217], v[114:117]
	v_mfma_f32_16x16x32_bf16 v[122:125], v[156:159], v[182:185], 0
	v_mfma_f32_16x16x32_bf16 v[122:125], v[160:163], v[206:209], v[122:125]
	v_mfma_f32_16x16x32_bf16 v[106:109], v[156:159], v[218:221], 0
	v_mfma_f32_16x16x32_bf16 v[106:109], v[160:163], v[236:239], v[106:109]
	v_mfma_f32_16x16x32_bf16 v[98:101], v[156:159], v[240:243], 0
	v_mfma_f32_16x16x32_bf16 v[98:101], v[160:163], v[244:247], v[98:101]
	v_mfma_f32_16x16x32_bf16 v[102:105], v[148:151], v[240:243], 0
	v_mfma_f32_16x16x32_bf16 v[102:105], v[152:155], v[244:247], v[102:105]
	v_mfma_f32_16x16x32_bf16 v[110:113], v[148:151], v[218:221], 0
	v_mfma_f32_16x16x32_bf16 v[110:113], v[152:155], v[236:239], v[110:113]
	v_mfma_f32_16x16x32_bf16 v[94:97], v[166:169], v[182:185], 0
	v_mfma_f32_16x16x32_bf16 v[94:97], v[170:173], v[206:209], v[94:97]
	v_mfma_f32_16x16x32_bf16 v[86:89], v[166:169], v[210:213], 0
	v_mfma_f32_16x16x32_bf16 v[86:89], v[170:173], v[214:217], v[86:89]
	v_mfma_f32_16x16x32_bf16 v[82:85], v[174:177], v[210:213], 0
	v_mfma_f32_16x16x32_bf16 v[82:85], v[178:181], v[214:217], v[82:85]
	v_mfma_f32_16x16x32_bf16 v[90:93], v[174:177], v[182:185], 0
	v_mfma_f32_16x16x32_bf16 v[90:93], v[178:181], v[206:209], v[90:93]
	v_mfma_f32_16x16x32_bf16 v[74:77], v[174:177], v[218:221], 0
	v_mfma_f32_16x16x32_bf16 v[74:77], v[178:181], v[236:239], v[74:77]
	v_mfma_f32_16x16x32_bf16 v[66:69], v[174:177], v[240:243], 0
	v_mfma_f32_16x16x32_bf16 v[66:69], v[178:181], v[244:247], v[66:69]
	v_mfma_f32_16x16x32_bf16 v[70:73], v[166:169], v[240:243], 0
	v_mfma_f32_16x16x32_bf16 v[70:73], v[170:173], v[244:247], v[70:73]
	v_mfma_f32_16x16x32_bf16 v[78:81], v[166:169], v[218:221], 0
	v_mfma_f32_16x16x32_bf16 v[78:81], v[170:173], v[236:239], v[78:81]
	s_barrier
	s_add_i32 s10, s13, s0
	s_mov_b32 m0, s10
	ds_read_b128 v[182:185], v165 offset:16384
	ds_read_b128 v[206:209], v165 offset:17408
	ds_read_b128 v[210:213], v165 offset:18432
	ds_read_b128 v[214:217], v165 offset:19456
	ds_read_b128 v[218:221], v165 offset:20480
	ds_read_b128 v[236:239], v165 offset:21504
	ds_read_b128 v[240:243], v165 offset:22528
	ds_read_b128 v[244:247], v165 offset:23552
	global_load_lds_dwordx4 v132, s[80:81]
	s_add_i32 m0, s10, 0x2000
	s_add_u32 s10, s80, 0x20000
	s_addc_u32 s11, s81, 0
	s_add_i32 s9, s9, s0
	global_load_lds_dwordx4 v136, s[80:81]
	s_mov_b32 m0, s9
	s_nop 0
	global_load_lds_dwordx4 v132, s[10:11]
	s_add_i32 m0, s9, 0x2000
	s_nop 0
	global_load_lds_dwordx4 v136, s[10:11]
	s_mov_b32 m0, s1
	s_nop 0
	global_load_lds_dwordx4 v130, s[84:85]
	s_mov_b32 m0, s25
	s_nop 0
	global_load_lds_dwordx4 v134, s[84:85]
	s_waitcnt vmcnt(8)
	s_waitcnt lgkmcnt(0)
	s_barrier
; #define PG8_STAGE(bufoff, gbase, voff) do { _Pragma("unroll") for (int _i = 0; _i < 2; ++_i) \
;         __builtin_amdgcn_global_load_lds((const unsigned*)((const char*)(gbase) + (voff)[_i]), (PG8_LAS unsigned*)(lds + (bufoff) + ldsw + _i * 8192), 16, 0, 0); } while (0)
; #define PG8_LDA(dst, b, h) do { _Pragma("unroll") for (int m = 0; m < 4; ++m) _Pragma("unroll") for (int k = 0; k < 2; ++k) dst[m][k] = *(const PG8_LAS bf16x8*)(lds + PG8_SA(b, h) + aoff + m * 2048 + k * 1024); } while (0)
; #define PG8_LDB(dst, b, h) do { _Pragma("unroll") for (int n = 0; n < 2; ++n) _Pragma("unroll") for (int k = 0; k < 2; ++k) dst[n][k] = *(const PG8_LAS bf16x8*)(lds + PG8_SB(b, h) + boff + n * 2048 + k * 1024); } while (0)
; #define PG8_MMA(ai, bj, At, Bt) do { __builtin_amdgcn_s_setprio(1); _Pragma("unroll") for (int m = 0; m < 4; ++m) _Pragma("unroll") for (int n = 0; n < 2; ++n) _Pragma("unroll") for (int k = 0; k < 2; ++k) \
;         acc[ai][bj][m][n] = __builtin_amdgcn_mfma_f32_16x16x32_bf16(Bt[n][k], At[m][k], acc[ai][bj][m][n], 0, 0, 0); __builtin_amdgcn_s_setprio(0); } while (0)
; #define PG8_WAIT_V(n) asm volatile("s_waitcnt vmcnt(" #n ")" ::: "memory")
; #define PG8_WAIT_L(n) asm volatile("s_waitcnt lgkmcnt(" #n ")" ::: "memory")
; #define PG8_BAR __builtin_amdgcn_s_barrier()
; #define PG8_SCHED __builtin_amdgcn_sched_barrier(0)
; template <class Epi, class Sched, bool ALIGN_EPI = false, bool SP2 = false>
; __device__ __forceinline__ void gemm_phase(PG8_LAS unsigned char* lds, const Gemm g, const Sched& S, const Epi& E) {
;     ...
;             PG8_WAIT_V(8); PG8_WAIT_L(0); PG8_BAR; PG8_MMA(1, 0, At, B0); PG8_MMA(1, 1, At, B1); PG8_BAR; PG8_SCHED;
;             PG8_LDB(B0, 1, 0); PG8_LDB(B1, 1, 1); PG8_SCHED; PG8_LDA(At, 1, 0); PG8_STAGE(PG8_SA(0, 1), a2 + hstep, voffA);
;             PG8_WAIT_V(8); PG8_WAIT_L(0); PG8_BAR; PG8_MMA(0, 0, At, B0); PG8_MMA(0, 1, At, B1); PG8_BAR; PG8_SCHED;
	v_mfma_f32_16x16x32_bf16 v[62:65], v[148:151], v[182:185], 0
	v_mfma_f32_16x16x32_bf16 v[62:65], v[152:155], v[206:209], v[62:65]
	v_mfma_f32_16x16x32_bf16 v[54:57], v[148:151], v[210:213], 0
	v_mfma_f32_16x16x32_bf16 v[54:57], v[152:155], v[214:217], v[54:57]
	v_mfma_f32_16x16x32_bf16 v[50:53], v[156:159], v[210:213], 0
	v_mfma_f32_16x16x32_bf16 v[50:53], v[160:163], v[214:217], v[50:53]
	v_mfma_f32_16x16x32_bf16 v[58:61], v[156:159], v[182:185], 0
	v_mfma_f32_16x16x32_bf16 v[58:61], v[160:163], v[206:209], v[58:61]
	v_mfma_f32_16x16x32_bf16 v[42:45], v[156:159], v[218:221], 0
	v_mfma_f32_16x16x32_bf16 v[42:45], v[160:163], v[236:239], v[42:45]
	v_mfma_f32_16x16x32_bf16 v[34:37], v[156:159], v[240:243], 0
	v_mfma_f32_16x16x32_bf16 v[34:37], v[160:163], v[244:247], v[34:37]
	v_mfma_f32_16x16x32_bf16 v[38:41], v[148:151], v[240:243], 0
	v_mfma_f32_16x16x32_bf16 v[38:41], v[152:155], v[244:247], v[38:41]
	v_mfma_f32_16x16x32_bf16 v[46:49], v[148:151], v[218:221], 0
	v_mfma_f32_16x16x32_bf16 v[46:49], v[152:155], v[236:239], v[46:49]
	v_mfma_f32_16x16x32_bf16 v[30:33], v[166:169], v[182:185], 0
	v_mfma_f32_16x16x32_bf16 v[30:33], v[170:173], v[206:209], v[30:33]
	v_mfma_f32_16x16x32_bf16 v[22:25], v[166:169], v[210:213], 0
	v_mfma_f32_16x16x32_bf16 v[22:25], v[170:173], v[214:217], v[22:25]
	v_mfma_f32_16x16x32_bf16 v[18:21], v[174:177], v[210:213], 0
	v_mfma_f32_16x16x32_bf16 v[18:21], v[178:181], v[214:217], v[18:21]
	v_mfma_f32_16x16x32_bf16 v[26:29], v[174:177], v[182:185], 0
	v_mfma_f32_16x16x32_bf16 v[26:29], v[178:181], v[206:209], v[26:29]
	v_mfma_f32_16x16x32_bf16 v[10:13], v[174:177], v[218:221], 0
	v_mfma_f32_16x16x32_bf16 v[10:13], v[178:181], v[236:239], v[10:13]
	v_mfma_f32_16x16x32_bf16 v[2:5], v[174:177], v[240:243], 0
	v_mfma_f32_16x16x32_bf16 v[2:5], v[178:181], v[244:247], v[2:5]
	v_mfma_f32_16x16x32_bf16 v[6:9], v[166:169], v[240:243], 0
	v_mfma_f32_16x16x32_bf16 v[6:9], v[170:173], v[244:247], v[6:9]
	v_mfma_f32_16x16x32_bf16 v[14:17], v[166:169], v[218:221], 0
	v_mfma_f32_16x16x32_bf16 v[14:17], v[170:173], v[236:239], v[14:17]
	s_barrier
	s_add_i32 s9, 0, 0x18000
	s_add_i32 s12, 0, 0x1c000
	ds_read_b128 v[148:151], v198
	ds_read_b128 v[152:155], v198 offset:1024
	ds_read_b128 v[156:159], v198 offset:2048
	ds_read_b128 v[160:163], v198 offset:3072
	ds_read_b128 v[166:169], v199
	ds_read_b128 v[170:173], v199 offset:1024
	ds_read_b128 v[174:177], v199 offset:2048
	ds_read_b128 v[178:181], v199 offset:3072
	s_add_u32 s10, s84, 0x80000
	s_addc_u32 s11, s85, 0
	s_mov_b32 m0, s42
	ds_read_b128 v[182:185], v165 offset:32768
	ds_read_b128 v[206:209], v165 offset:33792
	ds_read_b128 v[210:213], v165 offset:34816
	ds_read_b128 v[214:217], v165 offset:35840
	ds_read_b128 v[218:221], v165 offset:36864
	ds_read_b128 v[236:239], v165 offset:37888
	ds_read_b128 v[240:243], v165 offset:38912
	ds_read_b128 v[244:247], v165 offset:39936
	global_load_lds_dwordx4 v130, s[10:11]
	s_mov_b32 m0, s51
	s_nop 0
	global_load_lds_dwordx4 v134, s[10:11]
	s_waitcnt vmcnt(8)
	s_waitcnt lgkmcnt(0)
	s_barrier
	v_mfma_f32_16x16x32_bf16 v[126:129], v[148:151], v[182:185], v[126:129]
	v_mfma_f32_16x16x32_bf16 v[126:129], v[152:155], v[206:209], v[126:129]
	v_mfma_f32_16x16x32_bf16 v[118:121], v[148:151], v[210:213], v[118:121]
	v_mfma_f32_16x16x32_bf16 v[118:121], v[152:155], v[214:217], v[118:121]
	v_mfma_f32_16x16x32_bf16 v[114:117], v[156:159], v[210:213], v[114:117]
	v_mfma_f32_16x16x32_bf16 v[114:117], v[160:163], v[214:217], v[114:117]
	v_mfma_f32_16x16x32_bf16 v[122:125], v[156:159], v[182:185], v[122:125]
	v_mfma_f32_16x16x32_bf16 v[122:125], v[160:163], v[206:209], v[122:125]
	v_mfma_f32_16x16x32_bf16 v[106:109], v[156:159], v[218:221], v[106:109]
	v_mfma_f32_16x16x32_bf16 v[106:109], v[160:163], v[236:239], v[106:109]
	v_mfma_f32_16x16x32_bf16 v[98:101], v[156:159], v[240:243], v[98:101]
	v_mfma_f32_16x16x32_bf16 v[98:101], v[160:163], v[244:247], v[98:101]
	v_mfma_f32_16x16x32_bf16 v[102:105], v[148:151], v[240:243], v[102:105]
	v_mfma_f32_16x16x32_bf16 v[102:105], v[152:155], v[244:247], v[102:105]
	v_mfma_f32_16x16x32_bf16 v[110:113], v[148:151], v[218:221], v[110:113]
	v_mfma_f32_16x16x32_bf16 v[110:113], v[152:155], v[236:239], v[110:113]
	v_mfma_f32_16x16x32_bf16 v[94:97], v[166:169], v[182:185], v[94:97]
	v_mfma_f32_16x16x32_bf16 v[94:97], v[170:173], v[206:209], v[94:97]
	v_mfma_f32_16x16x32_bf16 v[86:89], v[166:169], v[210:213], v[86:89]
	v_mfma_f32_16x16x32_bf16 v[86:89], v[170:173], v[214:217], v[86:89]
	v_mfma_f32_16x16x32_bf16 v[82:85], v[174:177], v[210:213], v[82:85]
	v_mfma_f32_16x16x32_bf16 v[82:85], v[178:181], v[214:217], v[82:85]
	v_mfma_f32_16x16x32_bf16 v[90:93], v[174:177], v[182:185], v[90:93]
	v_mfma_f32_16x16x32_bf16 v[90:93], v[178:181], v[206:209], v[90:93]
	v_mfma_f32_16x16x32_bf16 v[74:77], v[174:177], v[218:221], v[74:77]
	v_mfma_f32_16x16x32_bf16 v[74:77], v[178:181], v[236:239], v[74:77]
	v_mfma_f32_16x16x32_bf16 v[66:69], v[174:177], v[240:243], v[66:69]
	v_mfma_f32_16x16x32_bf16 v[66:69], v[178:181], v[244:247], v[66:69]
	v_mfma_f32_16x16x32_bf16 v[70:73], v[166:169], v[240:243], v[70:73]
	v_mfma_f32_16x16x32_bf16 v[70:73], v[170:173], v[244:247], v[70:73]
	v_mfma_f32_16x16x32_bf16 v[78:81], v[166:169], v[218:221], v[78:81]
	v_mfma_f32_16x16x32_bf16 v[78:81], v[170:173], v[236:239], v[78:81]
	s_barrier
; #define PG8_STAGE(bufoff, gbase, voff) do { _Pragma("unroll") for (int _i = 0; _i < 2; ++_i) \
;         __builtin_amdgcn_global_load_lds((const unsigned*)((const char*)(gbase) + (voff)[_i]), (PG8_LAS unsigned*)(lds + (bufoff) + ldsw + _i * 8192), 16, 0, 0); } while (0)
; #define PG8_LDA(dst, b, h) do { _Pragma("unroll") for (int m = 0; m < 4; ++m) _Pragma("unroll") for (int k = 0; k < 2; ++k) dst[m][k] = *(const PG8_LAS bf16x8*)(lds + PG8_SA(b, h) + aoff + m * 2048 + k * 1024); } while (0)
; #define PG8_LDB(dst, b, h) do { _Pragma("unroll") for (int n = 0; n < 2; ++n) _Pragma("unroll") for (int k = 0; k < 2; ++k) dst[n][k] = *(const PG8_LAS bf16x8*)(lds + PG8_SB(b, h) + boff + n * 2048 + k * 1024); } while (0)
; #define PG8_BAR __builtin_amdgcn_s_barrier()
; template <class Epi, class Sched, bool ALIGN_EPI = false, bool SP2 = false>
; __device__ __forceinline__ void gemm_phase(PG8_LAS unsigned char* lds, const Gemm g, const Sched& S, const Epi& E) {
;     ...
;             const bool last = (t == nt - 2);
;             const char* a1 = cA + (size_t)(t + 1) * kstep;
;             const char* a2 = last ? nA : cA + (size_t)(t + 2) * kstep; const char* b2 = last ? nB : cB + (size_t)(t + 2) * kstep;
;             const char* a3 = a2 + kstep; const char* b3 = b2 + kstep;
;             if (last && has_next) S.a_ready(nxt);
;             if constexpr (SP2) {
;             PG8_LDB(B0, 0, 0); PG8_LDB(B1, 0, 1); PG8_SCHED; PG8_LDA(At, 0, 0); PG8_STAGE(PG8_SA(1, 1), a1 + hstep, voffA);
;             PG8_WAIT_V(8); PG8_WAIT_L(0); PG8_BAR; PG8_MMA(0, 0, At, B0); PG8_MMA(0, 1, At, B1); PG8_BAR; PG8_SCHED;
;             PG8_LDA(At, 0, 1); PG8_STAGE(PG8_SB(0, 0), b2, voffB); PG8_STAGE(PG8_SB(0, 1), b2 + hstepB, voffB); PG8_STAGE(PG8_SA(0, 0), a2, voffA);
;             PG8_WAIT_V(8); PG8_WAIT_L(0); PG8_BAR; PG8_MMA(1, 0, At, B0); PG8_MMA(1, 1, At, B1); PG8_BAR; PG8_SCHED;
;             PG8_LDB(B0, 1, 0); PG8_LDB(B1, 1, 1); PG8_SCHED; PG8_LDA(At, 1, 0); PG8_STAGE(PG8_SA(0, 1), a2 + hstep, voffA);
;             PG8_WAIT_V(8); PG8_WAIT_L(0); PG8_BAR; PG8_MMA(0, 0, At, B0); PG8_MMA(0, 1, At, B1); PG8_BAR; PG8_SCHED;
;             PG8_LDA(At, 1, 1); PG8_STAGE(PG8_SB(1, 0), b3, voffB); PG8_STAGE(PG8_SB(1, 1), b3 + hstepB, voffB); PG8_STAGE(PG8_SA(1, 0), a3, voffA);
;             PG8_WAIT_V(8); PG8_WAIT_L(0); PG8_BAR; PG8_MMA(1, 0, At, B0); PG8_MMA(1, 1, At, B1); PG8_BAR; PG8_SCHED;
	s_add_i32 s9, s9, s0
	s_mov_b32 m0, s9
	ds_read_b128 v[182:185], v165 offset:49152
	ds_read_b128 v[206:209], v165 offset:50176
	ds_read_b128 v[210:213], v165 offset:51200
	ds_read_b128 v[214:217], v165 offset:52224
	ds_read_b128 v[218:221], v165 offset:53248
	ds_read_b128 v[236:239], v165 offset:54272
	ds_read_b128 v[240:243], v165 offset:55296
	ds_read_b128 v[244:247], v165 offset:56320
	s_add_u32 s100, s80, s60
	s_addc_u32 s101, s81, s61
	global_load_lds_dwordx4 v132, s[100:101]
	s_add_i32 m0, s9, 0x2000
	s_add_u32 s10, s80, 0x20080
	s_addc_u32 s11, s81, 0
	s_add_i32 s9, s12, s0
	global_load_lds_dwordx4 v136, s[100:101]
	s_mov_b32 m0, s9
	s_nop 0
	global_load_lds_dwordx4 v132, s[10:11]
	s_add_i32 m0, s9, 0x2000
	s_nop 0
	global_load_lds_dwordx4 v136, s[10:11]
	s_mov_b32 m0, s66
	s_add_u32 s100, s84, s60
	s_addc_u32 s101, s85, s61
	global_load_lds_dwordx4 v130, s[100:101]
	s_mov_b32 m0, s67
	s_nop 0
	global_load_lds_dwordx4 v134, s[100:101]
	s_waitcnt vmcnt(8)
	s_waitcnt lgkmcnt(0)
	s_barrier
	v_mfma_f32_16x16x32_bf16 v[62:65], v[148:151], v[182:185], v[62:65]
	v_mfma_f32_16x16x32_bf16 v[62:65], v[152:155], v[206:209], v[62:65]
	v_mfma_f32_16x16x32_bf16 v[54:57], v[148:151], v[210:213], v[54:57]
	v_mfma_f32_16x16x32_bf16 v[54:57], v[152:155], v[214:217], v[54:57]
	v_mfma_f32_16x16x32_bf16 v[50:53], v[156:159], v[210:213], v[50:53]
	v_mfma_f32_16x16x32_bf16 v[50:53], v[160:163], v[214:217], v[50:53]
	v_mfma_f32_16x16x32_bf16 v[58:61], v[156:159], v[182:185], v[58:61]
	v_mfma_f32_16x16x32_bf16 v[58:61], v[160:163], v[206:209], v[58:61]
	v_mfma_f32_16x16x32_bf16 v[42:45], v[156:159], v[218:221], v[42:45]
	v_mfma_f32_16x16x32_bf16 v[42:45], v[160:163], v[236:239], v[42:45]
	v_mfma_f32_16x16x32_bf16 v[34:37], v[156:159], v[240:243], v[34:37]
	v_mfma_f32_16x16x32_bf16 v[34:37], v[160:163], v[244:247], v[34:37]
	v_mfma_f32_16x16x32_bf16 v[38:41], v[148:151], v[240:243], v[38:41]
	v_mfma_f32_16x16x32_bf16 v[38:41], v[152:155], v[244:247], v[38:41]
	v_mfma_f32_16x16x32_bf16 v[46:49], v[148:151], v[218:221], v[46:49]
	v_mfma_f32_16x16x32_bf16 v[46:49], v[152:155], v[236:239], v[46:49]
	v_mfma_f32_16x16x32_bf16 v[30:33], v[166:169], v[182:185], v[30:33]
	v_mfma_f32_16x16x32_bf16 v[30:33], v[170:173], v[206:209], v[30:33]
	v_mfma_f32_16x16x32_bf16 v[22:25], v[166:169], v[210:213], v[22:25]
	v_mfma_f32_16x16x32_bf16 v[22:25], v[170:173], v[214:217], v[22:25]
	v_mfma_f32_16x16x32_bf16 v[18:21], v[174:177], v[210:213], v[18:21]
	v_mfma_f32_16x16x32_bf16 v[18:21], v[178:181], v[214:217], v[18:21]
	v_mfma_f32_16x16x32_bf16 v[26:29], v[174:177], v[182:185], v[26:29]
	v_mfma_f32_16x16x32_bf16 v[26:29], v[178:181], v[206:209], v[26:29]
	v_mfma_f32_16x16x32_bf16 v[10:13], v[174:177], v[218:221], v[10:13]
	v_mfma_f32_16x16x32_bf16 v[10:13], v[178:181], v[236:239], v[10:13]
	v_mfma_f32_16x16x32_bf16 v[2:5], v[174:177], v[240:243], v[2:5]
	v_mfma_f32_16x16x32_bf16 v[2:5], v[178:181], v[244:247], v[2:5]
	v_mfma_f32_16x16x32_bf16 v[6:9], v[166:169], v[240:243], v[6:9]
	v_mfma_f32_16x16x32_bf16 v[6:9], v[170:173], v[244:247], v[6:9]
	v_mfma_f32_16x16x32_bf16 v[14:17], v[166:169], v[218:221], v[14:17]
	v_mfma_f32_16x16x32_bf16 v[14:17], v[170:173], v[236:239], v[14:17]
	s_barrier
	s_add_i32 s8, s8, 2
	s_add_u32 s46, s46, 0x100
	s_addc_u32 s47, s47, 0
	s_cmp_gt_u32 s8, 29
.LBB0_170:
	s_add_u32 s9, s70, s46
	s_addc_u32 s10, s71, s47
	s_add_u32 s9, s9, 0x100
	s_addc_u32 s10, s10, 0
	s_add_u32 s100, s9, 0x7ff80
	s_addc_u32 s101, s10, 0
	s_add_u32 s11, s93, s46
	s_addc_u32 s12, s94, s47
	s_add_i32 s13, 0, 0x10000
	s_cmpk_eq_i32 s46, 0xf00
	s_cselect_b32 s85, s4, s10
	s_cselect_b32 s84, s5, s9
	s_cselect_b32 s81, s6, s12
	s_cselect_b32 s80, s7, s11
	s_add_i32 s9, 0, 0x14000
	ds_read_b128 v[148:151], v186
	ds_read_b128 v[152:155], v186 offset:1024
	ds_read_b128 v[156:159], v186 offset:2048
	ds_read_b128 v[160:163], v186 offset:3072
	ds_read_b128 v[166:169], v187
	ds_read_b128 v[170:173], v187 offset:1024
	ds_read_b128 v[174:177], v187 offset:2048
	ds_read_b128 v[178:181], v187 offset:3072
	s_add_i32 m0, s1, 0xc000
	ds_read_b128 v[182:185], v165
	ds_read_b128 v[206:209], v165 offset:1024
	ds_read_b128 v[210:213], v165 offset:2048
	ds_read_b128 v[214:217], v165 offset:3072
	ds_read_b128 v[218:221], v165 offset:4096
	ds_read_b128 v[236:239], v165 offset:5120
	ds_read_b128 v[240:243], v165 offset:6144
	ds_read_b128 v[244:247], v165 offset:7168
	global_load_lds_dwordx4 v140, s[100:101]
	s_add_i32 m0, s1, 0xe000
	s_nop 0
	global_load_lds_dwordx4 v142, s[100:101]
	s_waitcnt vmcnt(8)
	s_waitcnt lgkmcnt(0)
	s_barrier
; #define PG8_STAGE(bufoff, gbase, voff) do { _Pragma("unroll") for (int _i = 0; _i < 2; ++_i) \
;         __builtin_amdgcn_global_load_lds((const unsigned*)((const char*)(gbase) + (voff)[_i]), (PG8_LAS unsigned*)(lds + (bufoff) + ldsw + _i * 8192), 16, 0, 0); } while (0)
; #define PG8_LDA(dst, b, h) do { _Pragma("unroll") for (int m = 0; m < 4; ++m) _Pragma("unroll") for (int k = 0; k < 2; ++k) dst[m][k] = *(const PG8_LAS bf16x8*)(lds + PG8_SA(b, h) + aoff + m * 2048 + k * 1024); } while (0)
; #define PG8_LDB(dst, b, h) do { _Pragma("unroll") for (int n = 0; n < 2; ++n) _Pragma("unroll") for (int k = 0; k < 2; ++k) dst[n][k] = *(const PG8_LAS bf16x8*)(lds + PG8_SB(b, h) + boff + n * 2048 + k * 1024); } while (0)
; #define PG8_MMA(ai, bj, At, Bt) do { __builtin_amdgcn_s_setprio(1); _Pragma("unroll") for (int m = 0; m < 4; ++m) _Pragma("unroll") for (int n = 0; n < 2; ++n) _Pragma("unroll") for (int k = 0; k < 2; ++k) \
;         acc[ai][bj][m][n] = __builtin_amdgcn_mfma_f32_16x16x32_bf16(Bt[n][k], At[m][k], acc[ai][bj][m][n], 0, 0, 0); __builtin_amdgcn_s_setprio(0); } while (0)
; #define PG8_WAIT_V(n) asm volatile("s_waitcnt vmcnt(" #n ")" ::: "memory")
; #define PG8_WAIT_L(n) asm volatile("s_waitcnt lgkmcnt(" #n ")" ::: "memory")
; #define PG8_BAR __builtin_amdgcn_s_barrier()
; #define PG8_SCHED __builtin_amdgcn_sched_barrier(0)
; template <class Epi, class Sched, bool ALIGN_EPI = false, bool SP2 = false>
; __device__ __forceinline__ void gemm_phase(PG8_LAS unsigned char* lds, const Gemm g, const Sched& S, const Epi& E) {
;     ...
;             PG8_LDB(B0, 0, 0); PG8_LDB(B1, 0, 1); PG8_SCHED; PG8_LDA(At, 0, 0); PG8_STAGE(PG8_SA(1, 1), a1 + hstep, voffA);
;             PG8_WAIT_V(8); PG8_WAIT_L(0); PG8_BAR; PG8_MMA(0, 0, At, B0); PG8_MMA(0, 1, At, B1); PG8_BAR; PG8_SCHED;
;             PG8_LDA(At, 0, 1); PG8_STAGE(PG8_SB(0, 0), b2, voffB); PG8_STAGE(PG8_SB(0, 1), b2 + hstepB, voffB); PG8_STAGE(PG8_SA(0, 0), a2, voffA);
;             PG8_WAIT_V(8); PG8_WAIT_L(0); PG8_BAR; PG8_MMA(1, 0, At, B0); PG8_MMA(1, 1, At, B1); PG8_BAR; PG8_SCHED;
	v_mfma_f32_16x16x32_bf16 v[126:129], v[148:151], v[182:185], v[126:129]
	v_mfma_f32_16x16x32_bf16 v[126:129], v[152:155], v[206:209], v[126:129]
	v_mfma_f32_16x16x32_bf16 v[118:121], v[148:151], v[210:213], v[118:121]
	v_mfma_f32_16x16x32_bf16 v[118:121], v[152:155], v[214:217], v[118:121]
	v_mfma_f32_16x16x32_bf16 v[114:117], v[156:159], v[210:213], v[114:117]
	v_mfma_f32_16x16x32_bf16 v[114:117], v[160:163], v[214:217], v[114:117]
	v_mfma_f32_16x16x32_bf16 v[122:125], v[156:159], v[182:185], v[122:125]
	v_mfma_f32_16x16x32_bf16 v[122:125], v[160:163], v[206:209], v[122:125]
	v_mfma_f32_16x16x32_bf16 v[106:109], v[156:159], v[218:221], v[106:109]
	v_mfma_f32_16x16x32_bf16 v[106:109], v[160:163], v[236:239], v[106:109]
	v_mfma_f32_16x16x32_bf16 v[98:101], v[156:159], v[240:243], v[98:101]
	v_mfma_f32_16x16x32_bf16 v[98:101], v[160:163], v[244:247], v[98:101]
	v_mfma_f32_16x16x32_bf16 v[102:105], v[148:151], v[240:243], v[102:105]
	v_mfma_f32_16x16x32_bf16 v[102:105], v[152:155], v[244:247], v[102:105]
	v_mfma_f32_16x16x32_bf16 v[110:113], v[148:151], v[218:221], v[110:113]
	v_mfma_f32_16x16x32_bf16 v[110:113], v[152:155], v[236:239], v[110:113]
	v_mfma_f32_16x16x32_bf16 v[94:97], v[166:169], v[182:185], v[94:97]
	v_mfma_f32_16x16x32_bf16 v[94:97], v[170:173], v[206:209], v[94:97]
	v_mfma_f32_16x16x32_bf16 v[86:89], v[166:169], v[210:213], v[86:89]
	v_mfma_f32_16x16x32_bf16 v[86:89], v[170:173], v[214:217], v[86:89]
	v_mfma_f32_16x16x32_bf16 v[82:85], v[174:177], v[210:213], v[82:85]
	v_mfma_f32_16x16x32_bf16 v[82:85], v[178:181], v[214:217], v[82:85]
	v_mfma_f32_16x16x32_bf16 v[90:93], v[174:177], v[182:185], v[90:93]
	v_mfma_f32_16x16x32_bf16 v[90:93], v[178:181], v[206:209], v[90:93]
	v_mfma_f32_16x16x32_bf16 v[74:77], v[174:177], v[218:221], v[74:77]
	v_mfma_f32_16x16x32_bf16 v[74:77], v[178:181], v[236:239], v[74:77]
	v_mfma_f32_16x16x32_bf16 v[66:69], v[174:177], v[240:243], v[66:69]
	v_mfma_f32_16x16x32_bf16 v[66:69], v[178:181], v[244:247], v[66:69]
	v_mfma_f32_16x16x32_bf16 v[70:73], v[166:169], v[240:243], v[70:73]
	v_mfma_f32_16x16x32_bf16 v[70:73], v[170:173], v[244:247], v[70:73]
	v_mfma_f32_16x16x32_bf16 v[78:81], v[166:169], v[218:221], v[78:81]
	v_mfma_f32_16x16x32_bf16 v[78:81], v[170:173], v[236:239], v[78:81]
	s_barrier
	s_add_i32 s10, s13, s0
	s_mov_b32 m0, s10
	ds_read_b128 v[182:185], v165 offset:16384
	ds_read_b128 v[206:209], v165 offset:17408
	ds_read_b128 v[210:213], v165 offset:18432
	ds_read_b128 v[214:217], v165 offset:19456
	ds_read_b128 v[218:221], v165 offset:20480
	ds_read_b128 v[236:239], v165 offset:21504
	ds_read_b128 v[240:243], v165 offset:22528
	ds_read_b128 v[244:247], v165 offset:23552
	global_load_lds_dwordx4 v132, s[80:81]
	s_add_i32 m0, s10, 0x2000
	s_add_u32 s10, s80, 0x20000
	s_addc_u32 s11, s81, 0
	s_add_i32 s9, s9, s0
	global_load_lds_dwordx4 v136, s[80:81]
	s_mov_b32 m0, s9
	s_nop 0
	global_load_lds_dwordx4 v132, s[10:11]
	s_add_i32 m0, s9, 0x2000
	s_nop 0
	global_load_lds_dwordx4 v136, s[10:11]
	s_mov_b32 m0, s1
	s_nop 0
	global_load_lds_dwordx4 v130, s[84:85]
	s_mov_b32 m0, s25
	s_nop 0
	global_load_lds_dwordx4 v134, s[84:85]
	s_waitcnt vmcnt(8)
	s_waitcnt lgkmcnt(0)
	s_barrier
	v_mfma_f32_16x16x32_bf16 v[62:65], v[148:151], v[182:185], v[62:65]
	v_mfma_f32_16x16x32_bf16 v[62:65], v[152:155], v[206:209], v[62:65]
	v_mfma_f32_16x16x32_bf16 v[54:57], v[148:151], v[210:213], v[54:57]
	v_mfma_f32_16x16x32_bf16 v[54:57], v[152:155], v[214:217], v[54:57]
	v_mfma_f32_16x16x32_bf16 v[50:53], v[156:159], v[210:213], v[50:53]
	v_mfma_f32_16x16x32_bf16 v[50:53], v[160:163], v[214:217], v[50:53]
	v_mfma_f32_16x16x32_bf16 v[58:61], v[156:159], v[182:185], v[58:61]
	v_mfma_f32_16x16x32_bf16 v[58:61], v[160:163], v[206:209], v[58:61]
	v_mfma_f32_16x16x32_bf16 v[42:45], v[156:159], v[218:221], v[42:45]
	v_mfma_f32_16x16x32_bf16 v[42:45], v[160:163], v[236:239], v[42:45]
	v_mfma_f32_16x16x32_bf16 v[34:37], v[156:159], v[240:243], v[34:37]
	v_mfma_f32_16x16x32_bf16 v[34:37], v[160:163], v[244:247], v[34:37]
	v_mfma_f32_16x16x32_bf16 v[38:41], v[148:151], v[240:243], v[38:41]
	v_mfma_f32_16x16x32_bf16 v[38:41], v[152:155], v[244:247], v[38:41]
	v_mfma_f32_16x16x32_bf16 v[46:49], v[148:151], v[218:221], v[46:49]
	v_mfma_f32_16x16x32_bf16 v[46:49], v[152:155], v[236:239], v[46:49]
	v_mfma_f32_16x16x32_bf16 v[30:33], v[166:169], v[182:185], v[30:33]
	v_mfma_f32_16x16x32_bf16 v[30:33], v[170:173], v[206:209], v[30:33]
	v_mfma_f32_16x16x32_bf16 v[22:25], v[166:169], v[210:213], v[22:25]
	v_mfma_f32_16x16x32_bf16 v[22:25], v[170:173], v[214:217], v[22:25]
	v_mfma_f32_16x16x32_bf16 v[18:21], v[174:177], v[210:213], v[18:21]
	v_mfma_f32_16x16x32_bf16 v[18:21], v[178:181], v[214:217], v[18:21]
	v_mfma_f32_16x16x32_bf16 v[26:29], v[174:177], v[182:185], v[26:29]
	v_mfma_f32_16x16x32_bf16 v[26:29], v[178:181], v[206:209], v[26:29]
	v_mfma_f32_16x16x32_bf16 v[10:13], v[174:177], v[218:221], v[10:13]
	v_mfma_f32_16x16x32_bf16 v[10:13], v[178:181], v[236:239], v[10:13]
	v_mfma_f32_16x16x32_bf16 v[2:5], v[174:177], v[240:243], v[2:5]
	v_mfma_f32_16x16x32_bf16 v[2:5], v[178:181], v[244:247], v[2:5]
	v_mfma_f32_16x16x32_bf16 v[6:9], v[166:169], v[240:243], v[6:9]
	v_mfma_f32_16x16x32_bf16 v[6:9], v[170:173], v[244:247], v[6:9]
	v_mfma_f32_16x16x32_bf16 v[14:17], v[166:169], v[218:221], v[14:17]
	v_mfma_f32_16x16x32_bf16 v[14:17], v[170:173], v[236:239], v[14:17]
	s_barrier
; #define PG8_STAGE(bufoff, gbase, voff) do { _Pragma("unroll") for (int _i = 0; _i < 2; ++_i) \
;         __builtin_amdgcn_global_load_lds((const unsigned*)((const char*)(gbase) + (voff)[_i]), (PG8_LAS unsigned*)(lds + (bufoff) + ldsw + _i * 8192), 16, 0, 0); } while (0)
; #define PG8_LDA(dst, b, h) do { _Pragma("unroll") for (int m = 0; m < 4; ++m) _Pragma("unroll") for (int k = 0; k < 2; ++k) dst[m][k] = *(const PG8_LAS bf16x8*)(lds + PG8_SA(b, h) + aoff + m * 2048 + k * 1024); } while (0)
; #define PG8_LDB(dst, b, h) do { _Pragma("unroll") for (int n = 0; n < 2; ++n) _Pragma("unroll") for (int k = 0; k < 2; ++k) dst[n][k] = *(const PG8_LAS bf16x8*)(lds + PG8_SB(b, h) + boff + n * 2048 + k * 1024); } while (0)
; #define PG8_MMA(ai, bj, At, Bt) do { __builtin_amdgcn_s_setprio(1); _Pragma("unroll") for (int m = 0; m < 4; ++m) _Pragma("unroll") for (int n = 0; n < 2; ++n) _Pragma("unroll") for (int k = 0; k < 2; ++k) \
;         acc[ai][bj][m][n] = __builtin_amdgcn_mfma_f32_16x16x32_bf16(Bt[n][k], At[m][k], acc[ai][bj][m][n], 0, 0, 0); __builtin_amdgcn_s_setprio(0); } while (0)
; #define PG8_WAIT_V(n) asm volatile("s_waitcnt vmcnt(" #n ")" ::: "memory")
; #define PG8_WAIT_L(n) asm volatile("s_waitcnt lgkmcnt(" #n ")" ::: "memory")
; #define PG8_BAR __builtin_amdgcn_s_barrier()
; #define PG8_SCHED __builtin_amdgcn_sched_barrier(0)
; template <class Epi, class Sched, bool ALIGN_EPI = false, bool SP2 = false>
; __device__ __forceinline__ void gemm_phase(PG8_LAS unsigned char* lds, const Gemm g, const Sched& S, const Epi& E) {
;     ...
;             PG8_LDB(B0, 1, 0); PG8_LDB(B1, 1, 1); PG8_SCHED; PG8_LDA(At, 1, 0); PG8_STAGE(PG8_SA(0, 1), a2 + hstep, voffA);
;             PG8_WAIT_V(8); PG8_WAIT_L(0); PG8_BAR; PG8_MMA(0, 0, At, B0); PG8_MMA(0, 1, At, B1); PG8_BAR; PG8_SCHED;
;             PG8_LDA(At, 1, 1); PG8_STAGE(PG8_SB(1, 0), b3, voffB); PG8_STAGE(PG8_SB(1, 1), b3 + hstepB, voffB); PG8_STAGE(PG8_SA(1, 0), a3, voffA);
;             PG8_WAIT_V(8); PG8_WAIT_L(0); PG8_BAR; PG8_MMA(1, 0, At, B0); PG8_MMA(1, 1, At, B1); PG8_BAR; PG8_SCHED;
;     ...
;         if constexpr (ALIGN_EPI) { if (wr == 0) PG8_BAR; }
	s_add_i32 s9, 0, 0x18000
	s_add_i32 s12, 0, 0x1c000
	ds_read_b128 v[148:151], v198
	ds_read_b128 v[152:155], v198 offset:1024
	ds_read_b128 v[156:159], v198 offset:2048
	ds_read_b128 v[160:163], v198 offset:3072
	ds_read_b128 v[166:169], v199
	ds_read_b128 v[170:173], v199 offset:1024
	ds_read_b128 v[174:177], v199 offset:2048
	ds_read_b128 v[178:181], v199 offset:3072
	s_add_u32 s10, s84, 0x80000
	s_addc_u32 s11, s85, 0
	s_mov_b32 m0, s42
	ds_read_b128 v[182:185], v165 offset:32768
	ds_read_b128 v[206:209], v165 offset:33792
	ds_read_b128 v[210:213], v165 offset:34816
	ds_read_b128 v[214:217], v165 offset:35840
	ds_read_b128 v[218:221], v165 offset:36864
	ds_read_b128 v[236:239], v165 offset:37888
	ds_read_b128 v[240:243], v165 offset:38912
	ds_read_b128 v[244:247], v165 offset:39936
	global_load_lds_dwordx4 v130, s[10:11]
	s_mov_b32 m0, s51
	s_nop 0
	global_load_lds_dwordx4 v134, s[10:11]
	s_waitcnt vmcnt(8)
	s_waitcnt lgkmcnt(0)
	s_barrier
	v_mfma_f32_16x16x32_bf16 v[126:129], v[148:151], v[182:185], v[126:129]
	v_mfma_f32_16x16x32_bf16 v[126:129], v[152:155], v[206:209], v[126:129]
	v_mfma_f32_16x16x32_bf16 v[118:121], v[148:151], v[210:213], v[118:121]
	v_mfma_f32_16x16x32_bf16 v[118:121], v[152:155], v[214:217], v[118:121]
	v_mfma_f32_16x16x32_bf16 v[114:117], v[156:159], v[210:213], v[114:117]
	v_mfma_f32_16x16x32_bf16 v[114:117], v[160:163], v[214:217], v[114:117]
	v_mfma_f32_16x16x32_bf16 v[122:125], v[156:159], v[182:185], v[122:125]
	v_mfma_f32_16x16x32_bf16 v[122:125], v[160:163], v[206:209], v[122:125]
	v_mfma_f32_16x16x32_bf16 v[106:109], v[156:159], v[218:221], v[106:109]
	v_mfma_f32_16x16x32_bf16 v[106:109], v[160:163], v[236:239], v[106:109]
	v_mfma_f32_16x16x32_bf16 v[98:101], v[156:159], v[240:243], v[98:101]
	v_mfma_f32_16x16x32_bf16 v[98:101], v[160:163], v[244:247], v[98:101]
	v_mfma_f32_16x16x32_bf16 v[102:105], v[148:151], v[240:243], v[102:105]
	v_mfma_f32_16x16x32_bf16 v[102:105], v[152:155], v[244:247], v[102:105]
	v_mfma_f32_16x16x32_bf16 v[110:113], v[148:151], v[218:221], v[110:113]
	v_mfma_f32_16x16x32_bf16 v[110:113], v[152:155], v[236:239], v[110:113]
	v_mfma_f32_16x16x32_bf16 v[94:97], v[166:169], v[182:185], v[94:97]
	v_mfma_f32_16x16x32_bf16 v[94:97], v[170:173], v[206:209], v[94:97]
	v_mfma_f32_16x16x32_bf16 v[86:89], v[166:169], v[210:213], v[86:89]
	v_mfma_f32_16x16x32_bf16 v[86:89], v[170:173], v[214:217], v[86:89]
	v_mfma_f32_16x16x32_bf16 v[82:85], v[174:177], v[210:213], v[82:85]
	v_mfma_f32_16x16x32_bf16 v[82:85], v[178:181], v[214:217], v[82:85]
	v_mfma_f32_16x16x32_bf16 v[90:93], v[174:177], v[182:185], v[90:93]
	v_mfma_f32_16x16x32_bf16 v[90:93], v[178:181], v[206:209], v[90:93]
	v_mfma_f32_16x16x32_bf16 v[74:77], v[174:177], v[218:221], v[74:77]
	v_mfma_f32_16x16x32_bf16 v[74:77], v[178:181], v[236:239], v[74:77]
	v_mfma_f32_16x16x32_bf16 v[66:69], v[174:177], v[240:243], v[66:69]
	v_mfma_f32_16x16x32_bf16 v[66:69], v[178:181], v[244:247], v[66:69]
	v_mfma_f32_16x16x32_bf16 v[70:73], v[166:169], v[240:243], v[70:73]
	v_mfma_f32_16x16x32_bf16 v[70:73], v[170:173], v[244:247], v[70:73]
	v_mfma_f32_16x16x32_bf16 v[78:81], v[166:169], v[218:221], v[78:81]
	v_mfma_f32_16x16x32_bf16 v[78:81], v[170:173], v[236:239], v[78:81]
	s_barrier
	s_add_i32 s9, s9, s0
	s_mov_b32 m0, s9
	ds_read_b128 v[182:185], v165 offset:49152
	ds_read_b128 v[206:209], v165 offset:50176
	ds_read_b128 v[210:213], v165 offset:51200
	ds_read_b128 v[214:217], v165 offset:52224
	ds_read_b128 v[218:221], v165 offset:53248
	ds_read_b128 v[236:239], v165 offset:54272
	ds_read_b128 v[240:243], v165 offset:55296
	ds_read_b128 v[244:247], v165 offset:56320
	s_add_u32 s100, s80, s60
	s_addc_u32 s101, s81, s61
	global_load_lds_dwordx4 v132, s[100:101]
	s_add_i32 m0, s9, 0x2000
	s_add_u32 s10, s80, 0x20080
	s_addc_u32 s11, s81, 0
	s_add_i32 s9, s12, s0
	global_load_lds_dwordx4 v136, s[100:101]
	s_mov_b32 m0, s9
	s_nop 0
	global_load_lds_dwordx4 v132, s[10:11]
	s_add_i32 m0, s9, 0x2000
	s_nop 0
	global_load_lds_dwordx4 v136, s[10:11]
	s_mov_b32 m0, s66
	s_add_u32 s100, s84, s60
	s_addc_u32 s101, s85, s61
	global_load_lds_dwordx4 v130, s[100:101]
	s_mov_b32 m0, s67
	s_nop 0
	global_load_lds_dwordx4 v134, s[100:101]
	s_waitcnt vmcnt(8)
	s_waitcnt lgkmcnt(0)
	s_barrier
	v_mfma_f32_16x16x32_bf16 v[62:65], v[148:151], v[182:185], v[62:65]
	v_mfma_f32_16x16x32_bf16 v[62:65], v[152:155], v[206:209], v[62:65]
	v_mfma_f32_16x16x32_bf16 v[54:57], v[148:151], v[210:213], v[54:57]
	v_mfma_f32_16x16x32_bf16 v[54:57], v[152:155], v[214:217], v[54:57]
	v_mfma_f32_16x16x32_bf16 v[50:53], v[156:159], v[210:213], v[50:53]
	v_mfma_f32_16x16x32_bf16 v[50:53], v[160:163], v[214:217], v[50:53]
	v_mfma_f32_16x16x32_bf16 v[58:61], v[156:159], v[182:185], v[58:61]
	v_mfma_f32_16x16x32_bf16 v[58:61], v[160:163], v[206:209], v[58:61]
	v_mfma_f32_16x16x32_bf16 v[42:45], v[156:159], v[218:221], v[42:45]
	v_mfma_f32_16x16x32_bf16 v[42:45], v[160:163], v[236:239], v[42:45]
	v_mfma_f32_16x16x32_bf16 v[34:37], v[156:159], v[240:243], v[34:37]
	v_mfma_f32_16x16x32_bf16 v[34:37], v[160:163], v[244:247], v[34:37]
	v_mfma_f32_16x16x32_bf16 v[38:41], v[148:151], v[240:243], v[38:41]
	v_mfma_f32_16x16x32_bf16 v[38:41], v[152:155], v[244:247], v[38:41]
	v_mfma_f32_16x16x32_bf16 v[46:49], v[148:151], v[218:221], v[46:49]
	v_mfma_f32_16x16x32_bf16 v[46:49], v[152:155], v[236:239], v[46:49]
	v_mfma_f32_16x16x32_bf16 v[30:33], v[166:169], v[182:185], v[30:33]
	v_mfma_f32_16x16x32_bf16 v[30:33], v[170:173], v[206:209], v[30:33]
	v_mfma_f32_16x16x32_bf16 v[22:25], v[166:169], v[210:213], v[22:25]
	v_mfma_f32_16x16x32_bf16 v[22:25], v[170:173], v[214:217], v[22:25]
	v_mfma_f32_16x16x32_bf16 v[18:21], v[174:177], v[210:213], v[18:21]
	v_mfma_f32_16x16x32_bf16 v[18:21], v[178:181], v[214:217], v[18:21]
	v_mfma_f32_16x16x32_bf16 v[26:29], v[174:177], v[182:185], v[26:29]
	v_mfma_f32_16x16x32_bf16 v[26:29], v[178:181], v[206:209], v[26:29]
	v_mfma_f32_16x16x32_bf16 v[10:13], v[174:177], v[218:221], v[10:13]
	v_mfma_f32_16x16x32_bf16 v[10:13], v[178:181], v[236:239], v[10:13]
	v_mfma_f32_16x16x32_bf16 v[2:5], v[174:177], v[240:243], v[2:5]
	v_mfma_f32_16x16x32_bf16 v[2:5], v[178:181], v[244:247], v[2:5]
	v_mfma_f32_16x16x32_bf16 v[6:9], v[166:169], v[240:243], v[6:9]
	v_mfma_f32_16x16x32_bf16 v[6:9], v[170:173], v[244:247], v[6:9]
	v_mfma_f32_16x16x32_bf16 v[14:17], v[166:169], v[218:221], v[14:17]
	v_mfma_f32_16x16x32_bf16 v[14:17], v[170:173], v[236:239], v[14:17]
	s_barrier
	s_add_i32 s8, s8, 2
	s_add_u32 s46, s46, 0x100
	s_addc_u32 s47, s47, 0
	s_cmp_gt_u32 s8, 29
	s_cbranch_scc0 .LBB0_170
	s_and_b64 vcc, exec, s[54:55]
	s_cbranch_vccz .LBB0_173
	s_barrier

; #define PG8_STAGE(bufoff, gbase, voff) do { _Pragma("unroll") for (int _i = 0; _i < 2; ++_i) \
;         __builtin_amdgcn_global_load_lds((const unsigned*)((const char*)(gbase) + (voff)[_i]), (PG8_LAS unsigned*)(lds + (bufoff) + ldsw + _i * 8192), 16, 0, 0); } while (0)
; #define PG8_LDA(dst, b, h) do { _Pragma("unroll") for (int m = 0; m < 4; ++m) _Pragma("unroll") for (int k = 0; k < 2; ++k) dst[m][k] = *(const PG8_LAS bf16x8*)(lds + PG8_SA(b, h) + aoff + m * 2048 + k * 1024); } while (0)
; #define PG8_LDB(dst, b, h) do { _Pragma("unroll") for (int n = 0; n < 2; ++n) _Pragma("unroll") for (int k = 0; k < 2; ++k) dst[n][k] = *(const PG8_LAS bf16x8*)(lds + PG8_SB(b, h) + boff + n * 2048 + k * 1024); } while (0)
; #define PG8_WAIT_V(n) asm volatile("s_waitcnt vmcnt(" #n ")" ::: "memory")
; #define PG8_WAIT_L(n) asm volatile("s_waitcnt lgkmcnt(" #n ")" ::: "memory")
; #define PG8_BAR __builtin_amdgcn_s_barrier()
; #define PG8_SCHED __builtin_amdgcn_sched_barrier(0)
; template <class Epi, class Sched, bool ALIGN_EPI = false, bool SP2 = false>
; __device__ __forceinline__ void gemm_phase(PG8_LAS unsigned char* lds, const Gemm g, const Sched& S, const Epi& E) {
;     ...
;         const bool has_next = S.next(ui + 1, nxt);
;         const char* nA = has_next ? (const char*)g.A + (size_t)nxt.pm * tstep : cA; const char* nB = has_next ? (const char*)g.Bt + (size_t)nxt.pn * tstep : cB;
;         for (int t = 0; t < nt; t += 2) {
;             const bool last = (t == nt - 2);
;             const char* a1 = cA + (size_t)(t + 1) * kstep;
;             const char* a2 = last ? nA : cA + (size_t)(t + 2) * kstep; const char* b2 = last ? nB : cB + (size_t)(t + 2) * kstep;
;             const char* a3 = a2 + kstep; const char* b3 = b2 + kstep;
;             if (last && has_next) S.a_ready(nxt);
;             if constexpr (SP2) {
;             PG8_LDB(B0, 0, 0); PG8_LDB(B1, 0, 1); PG8_SCHED; PG8_LDA(At, 0, 0); PG8_STAGE(PG8_SA(1, 1), a1 + hstep, voffA);
;             PG8_WAIT_V(8); PG8_WAIT_L(0); PG8_BAR; PG8_MMA(0, 0, At, B0); PG8_MMA(0, 1, At, B1); PG8_BAR; PG8_SCHED;
;             PG8_LDA(At, 0, 1); PG8_STAGE(PG8_SB(0, 0), b2, voffB); PG8_STAGE(PG8_SB(0, 1), b2 + hstepB, voffB); PG8_STAGE(PG8_SA(0, 0), a2, voffA);
;             PG8_WAIT_V(8); PG8_WAIT_L(0); PG8_BAR; PG8_MMA(1, 0, At, B0); PG8_MMA(1, 1, At, B1); PG8_BAR; PG8_SCHED;
.LBB0_926:
	s_ashr_i32 s73, s72, 31
	s_lshl_b64 s[4:5], s[72:73], 20
	v_readlane_b32 s6, v249, 9
	v_readlane_b32 s7, v249, 10
	s_add_u32 s76, s6, s4
	s_addc_u32 s77, s7, s5
	s_and_b64 s[4:5], s[92:93], exec
	s_cselect_b32 s36, s77, s39
	s_cselect_b32 s37, s76, s38
	s_ashr_i32 s69, s68, 31
	s_lshl_b64 s[4:5], s[68:69], 20
	v_readlane_b32 s6, v249, 17
	v_readlane_b32 s7, v249, 18
	s_add_u32 s80, s6, s4
	s_addc_u32 s81, s7, s5
	s_and_b64 s[4:5], s[92:93], exec
	s_cselect_b32 s4, s81, s47
	s_cselect_b32 s5, s80, s46
	s_add_u32 s38, s38, 0x80080
	s_addc_u32 s39, s39, 0
	s_add_u32 s6, s46, 0x100
	v_mov_b32_e32 v2, 0
	s_addc_u32 s7, s47, 0
	s_mov_b32 s8, -2
	v_mov_b32_e32 v3, v2
	v_mov_b32_e32 v4, v2
	v_mov_b32_e32 v5, v2
	v_mov_b32_e32 v6, v2
	v_mov_b32_e32 v7, v2
	v_mov_b32_e32 v8, v2
	v_mov_b32_e32 v9, v2
	v_mov_b32_e32 v18, v2
	v_mov_b32_e32 v19, v2
	v_mov_b32_e32 v20, v2
	v_mov_b32_e32 v21, v2
	v_mov_b32_e32 v22, v2
	v_mov_b32_e32 v23, v2
	v_mov_b32_e32 v24, v2
	v_mov_b32_e32 v25, v2
	v_mov_b32_e32 v34, v2
	s_waitcnt lgkmcnt(0)
	v_add_u32_e32 v186, 0x10000, v193
	v_add_u32_e32 v187, 0x14000, v193
	v_add_u32_e32 v198, 0x18000, v193
	v_add_u32_e32 v199, 0x1c000, v193
	s_add_u32 s9, s38, 0xfff80080
	s_addc_u32 s10, s39, -1
	s_add_i32 s11, 0, 0x10000
	s_cmp_eq_u32 s8, 28
	s_cselect_b32 s95, s36, s10
	s_cselect_b32 s94, s37, s9
	s_cselect_b32 s47, s4, s7
	s_cselect_b32 s46, s5, s6
	s_add_i32 s9, 0, 0x14000
	ds_read_b128 v[66:69], v186
	ds_read_b128 v[70:73], v186 offset:1024
	ds_read_b128 v[78:81], v186 offset:2048
	ds_read_b128 v[86:89], v186 offset:3072
	ds_read_b128 v[146:149], v187
	ds_read_b128 v[150:153], v187 offset:1024
	ds_read_b128 v[154:157], v187 offset:2048
	ds_read_b128 v[158:161], v187 offset:3072
	s_add_i32 m0, s66, 0xc000
	ds_read_b128 v[162:165], v236
	ds_read_b128 v[166:169], v236 offset:1024
	ds_read_b128 v[170:173], v236 offset:2048
	ds_read_b128 v[174:177], v236 offset:3072
	ds_read_b128 v[178:181], v236 offset:4096
	ds_read_b128 v[182:185], v236 offset:5120
	ds_read_b128 v[216:219], v236 offset:6144
	ds_read_b128 v[220:223], v236 offset:7168
	global_load_lds_dwordx4 v212, s[38:39]
	s_add_i32 m0, s66, 0xe000
	s_nop 0
	global_load_lds_dwordx4 v214, s[38:39]
	s_waitcnt vmcnt(8)
	s_waitcnt lgkmcnt(0)
	s_barrier
	v_mfma_f32_16x16x32_bf16 v[142:145], v[66:69], v[162:165], 0
	v_mfma_f32_16x16x32_bf16 v[142:145], v[70:73], v[166:169], v[142:145]
	v_mfma_f32_16x16x32_bf16 v[126:129], v[66:69], v[170:173], 0
	v_mfma_f32_16x16x32_bf16 v[126:129], v[70:73], v[174:177], v[126:129]
	v_mfma_f32_16x16x32_bf16 v[122:125], v[78:81], v[170:173], 0
	v_mfma_f32_16x16x32_bf16 v[122:125], v[86:89], v[174:177], v[122:125]
	v_mfma_f32_16x16x32_bf16 v[138:141], v[78:81], v[162:165], 0
	v_mfma_f32_16x16x32_bf16 v[138:141], v[86:89], v[166:169], v[138:141]
	v_mfma_f32_16x16x32_bf16 v[106:109], v[78:81], v[178:181], 0
	v_mfma_f32_16x16x32_bf16 v[106:109], v[86:89], v[182:185], v[106:109]
	v_mfma_f32_16x16x32_bf16 v[90:93], v[78:81], v[216:219], 0
	v_mfma_f32_16x16x32_bf16 v[90:93], v[86:89], v[220:223], v[90:93]
	v_mfma_f32_16x16x32_bf16 v[94:97], v[66:69], v[216:219], 0
	v_mfma_f32_16x16x32_bf16 v[94:97], v[70:73], v[220:223], v[94:97]
	v_mfma_f32_16x16x32_bf16 v[110:113], v[66:69], v[178:181], 0
	v_mfma_f32_16x16x32_bf16 v[110:113], v[70:73], v[182:185], v[110:113]
	v_mfma_f32_16x16x32_bf16 v[134:137], v[146:149], v[162:165], 0
	v_mfma_f32_16x16x32_bf16 v[134:137], v[150:153], v[166:169], v[134:137]
	v_mfma_f32_16x16x32_bf16 v[118:121], v[146:149], v[170:173], 0
	v_mfma_f32_16x16x32_bf16 v[118:121], v[150:153], v[174:177], v[118:121]
	v_mfma_f32_16x16x32_bf16 v[114:117], v[154:157], v[170:173], 0
	v_mfma_f32_16x16x32_bf16 v[114:117], v[158:161], v[174:177], v[114:117]
	v_mfma_f32_16x16x32_bf16 v[130:133], v[154:157], v[162:165], 0
	v_mfma_f32_16x16x32_bf16 v[130:133], v[158:161], v[166:169], v[130:133]
	v_mfma_f32_16x16x32_bf16 v[98:101], v[154:157], v[178:181], 0
	v_mfma_f32_16x16x32_bf16 v[98:101], v[158:161], v[182:185], v[98:101]
	v_mfma_f32_16x16x32_bf16 v[74:77], v[154:157], v[216:219], 0
	v_mfma_f32_16x16x32_bf16 v[74:77], v[158:161], v[220:223], v[74:77]
	v_mfma_f32_16x16x32_bf16 v[82:85], v[146:149], v[216:219], 0
	v_mfma_f32_16x16x32_bf16 v[82:85], v[150:153], v[220:223], v[82:85]
	v_mfma_f32_16x16x32_bf16 v[102:105], v[146:149], v[178:181], 0
	v_mfma_f32_16x16x32_bf16 v[102:105], v[150:153], v[182:185], v[102:105]
	s_barrier
	s_add_i32 s10, s11, s25
	s_mov_b32 m0, s10
	ds_read_b128 v[162:165], v236 offset:16384
	ds_read_b128 v[166:169], v236 offset:17408
	ds_read_b128 v[170:173], v236 offset:18432
	ds_read_b128 v[174:177], v236 offset:19456
	ds_read_b128 v[178:181], v236 offset:20480
	ds_read_b128 v[182:185], v236 offset:21504
	ds_read_b128 v[216:219], v236 offset:22528
	ds_read_b128 v[220:223], v236 offset:23552
	global_load_lds_dwordx4 v190, s[46:47]
	s_add_i32 m0, s10, 0x2000
	s_add_u32 s10, s46, 0x20000
	s_addc_u32 s11, s47, 0
	s_add_i32 s9, s9, s25
	global_load_lds_dwordx4 v206, s[46:47]
	s_mov_b32 m0, s9
	s_nop 0
	global_load_lds_dwordx4 v190, s[10:11]
	s_add_i32 m0, s9, 0x2000
	s_nop 0
	global_load_lds_dwordx4 v206, s[10:11]
	s_mov_b32 m0, s66
	s_nop 0
	global_load_lds_dwordx4 v210, s[94:95]
	s_mov_b32 m0, s67
	s_nop 0
	global_load_lds_dwordx4 v208, s[94:95]
	s_waitcnt vmcnt(8)
	s_waitcnt lgkmcnt(0)
	s_barrier
; #define PG8_STAGE(bufoff, gbase, voff) do { _Pragma("unroll") for (int _i = 0; _i < 2; ++_i) \
;         __builtin_amdgcn_global_load_lds((const unsigned*)((const char*)(gbase) + (voff)[_i]), (PG8_LAS unsigned*)(lds + (bufoff) + ldsw + _i * 8192), 16, 0, 0); } while (0)
; #define PG8_LDA(dst, b, h) do { _Pragma("unroll") for (int m = 0; m < 4; ++m) _Pragma("unroll") for (int k = 0; k < 2; ++k) dst[m][k] = *(const PG8_LAS bf16x8*)(lds + PG8_SA(b, h) + aoff + m * 2048 + k * 1024); } while (0)
; #define PG8_LDB(dst, b, h) do { _Pragma("unroll") for (int n = 0; n < 2; ++n) _Pragma("unroll") for (int k = 0; k < 2; ++k) dst[n][k] = *(const PG8_LAS bf16x8*)(lds + PG8_SB(b, h) + boff + n * 2048 + k * 1024); } while (0)
; #define PG8_MMA(ai, bj, At, Bt) do { __builtin_amdgcn_s_setprio(1); _Pragma("unroll") for (int m = 0; m < 4; ++m) _Pragma("unroll") for (int n = 0; n < 2; ++n) _Pragma("unroll") for (int k = 0; k < 2; ++k) \
;         acc[ai][bj][m][n] = __builtin_amdgcn_mfma_f32_16x16x32_bf16(Bt[n][k], At[m][k], acc[ai][bj][m][n], 0, 0, 0); __builtin_amdgcn_s_setprio(0); } while (0)
; #define PG8_WAIT_V(n) asm volatile("s_waitcnt vmcnt(" #n ")" ::: "memory")
; #define PG8_WAIT_L(n) asm volatile("s_waitcnt lgkmcnt(" #n ")" ::: "memory")
; #define PG8_BAR __builtin_amdgcn_s_barrier()
; #define PG8_SCHED __builtin_amdgcn_sched_barrier(0)
; template <class Epi, class Sched, bool ALIGN_EPI = false, bool SP2 = false>
; __device__ __forceinline__ void gemm_phase(PG8_LAS unsigned char* lds, const Gemm g, const Sched& S, const Epi& E) {
;     ...
;             PG8_WAIT_V(8); PG8_WAIT_L(0); PG8_BAR; PG8_MMA(1, 0, At, B0); PG8_MMA(1, 1, At, B1); PG8_BAR; PG8_SCHED;
;             PG8_LDB(B0, 1, 0); PG8_LDB(B1, 1, 1); PG8_SCHED; PG8_LDA(At, 1, 0); PG8_STAGE(PG8_SA(0, 1), a2 + hstep, voffA);
;             PG8_WAIT_V(8); PG8_WAIT_L(0); PG8_BAR; PG8_MMA(0, 0, At, B0); PG8_MMA(0, 1, At, B1); PG8_BAR; PG8_SCHED;
	v_mfma_f32_16x16x32_bf16 v[62:65], v[66:69], v[162:165], 0
	v_mfma_f32_16x16x32_bf16 v[62:65], v[70:73], v[166:169], v[62:65]
	v_mfma_f32_16x16x32_bf16 v[46:49], v[66:69], v[170:173], 0
	v_mfma_f32_16x16x32_bf16 v[46:49], v[70:73], v[174:177], v[46:49]
	v_mfma_f32_16x16x32_bf16 v[42:45], v[78:81], v[170:173], 0
	v_mfma_f32_16x16x32_bf16 v[42:45], v[86:89], v[174:177], v[42:45]
	v_mfma_f32_16x16x32_bf16 v[58:61], v[78:81], v[162:165], 0
	v_mfma_f32_16x16x32_bf16 v[58:61], v[86:89], v[166:169], v[58:61]
	v_mfma_f32_16x16x32_bf16 v[26:29], v[78:81], v[178:181], 0
	v_mfma_f32_16x16x32_bf16 v[26:29], v[86:89], v[182:185], v[26:29]
	v_mfma_f32_16x16x32_bf16 v[10:13], v[78:81], v[216:219], 0
	v_mfma_f32_16x16x32_bf16 v[10:13], v[86:89], v[220:223], v[10:13]
	v_mfma_f32_16x16x32_bf16 v[14:17], v[66:69], v[216:219], 0
	v_mfma_f32_16x16x32_bf16 v[14:17], v[70:73], v[220:223], v[14:17]
	v_mfma_f32_16x16x32_bf16 v[30:33], v[66:69], v[178:181], 0
	v_mfma_f32_16x16x32_bf16 v[30:33], v[70:73], v[182:185], v[30:33]
	v_mfma_f32_16x16x32_bf16 v[54:57], v[146:149], v[162:165], 0
	v_mfma_f32_16x16x32_bf16 v[54:57], v[150:153], v[166:169], v[54:57]
	v_mfma_f32_16x16x32_bf16 v[38:41], v[146:149], v[170:173], 0
	v_mfma_f32_16x16x32_bf16 v[38:41], v[150:153], v[174:177], v[38:41]
	v_mfma_f32_16x16x32_bf16 v[34:37], v[154:157], v[170:173], 0
	v_mfma_f32_16x16x32_bf16 v[34:37], v[158:161], v[174:177], v[34:37]
	v_mfma_f32_16x16x32_bf16 v[50:53], v[154:157], v[162:165], 0
	v_mfma_f32_16x16x32_bf16 v[50:53], v[158:161], v[166:169], v[50:53]
	v_mfma_f32_16x16x32_bf16 v[18:21], v[154:157], v[178:181], 0
	v_mfma_f32_16x16x32_bf16 v[18:21], v[158:161], v[182:185], v[18:21]
	v_mfma_f32_16x16x32_bf16 v[2:5], v[154:157], v[216:219], 0
	v_mfma_f32_16x16x32_bf16 v[2:5], v[158:161], v[220:223], v[2:5]
	v_mfma_f32_16x16x32_bf16 v[6:9], v[146:149], v[216:219], 0
	v_mfma_f32_16x16x32_bf16 v[6:9], v[150:153], v[220:223], v[6:9]
	v_mfma_f32_16x16x32_bf16 v[22:25], v[146:149], v[178:181], 0
	v_mfma_f32_16x16x32_bf16 v[22:25], v[150:153], v[182:185], v[22:25]
	s_barrier
	s_add_i32 s9, 0, 0x18000
	s_add_i32 s12, 0, 0x1c000
	ds_read_b128 v[66:69], v198
	ds_read_b128 v[70:73], v198 offset:1024
	ds_read_b128 v[78:81], v198 offset:2048
	ds_read_b128 v[86:89], v198 offset:3072
	ds_read_b128 v[146:149], v199
	ds_read_b128 v[150:153], v199 offset:1024
	ds_read_b128 v[154:157], v199 offset:2048
	ds_read_b128 v[158:161], v199 offset:3072
	s_add_u32 s10, s94, 0x80000
	s_addc_u32 s11, s95, 0
	s_mov_b32 m0, s59
	ds_read_b128 v[162:165], v236 offset:32768
	ds_read_b128 v[166:169], v236 offset:33792
	ds_read_b128 v[170:173], v236 offset:34816
	ds_read_b128 v[174:177], v236 offset:35840
	ds_read_b128 v[178:181], v236 offset:36864
	ds_read_b128 v[182:185], v236 offset:37888
	ds_read_b128 v[216:219], v236 offset:38912
	ds_read_b128 v[220:223], v236 offset:39936
	global_load_lds_dwordx4 v210, s[10:11]
	s_mov_b32 m0, s74
	s_nop 0
	global_load_lds_dwordx4 v208, s[10:11]
	s_waitcnt vmcnt(8)
	s_waitcnt lgkmcnt(0)
	s_barrier
	v_mfma_f32_16x16x32_bf16 v[142:145], v[66:69], v[162:165], v[142:145]
	v_mfma_f32_16x16x32_bf16 v[142:145], v[70:73], v[166:169], v[142:145]
	v_mfma_f32_16x16x32_bf16 v[126:129], v[66:69], v[170:173], v[126:129]
	v_mfma_f32_16x16x32_bf16 v[126:129], v[70:73], v[174:177], v[126:129]
	v_mfma_f32_16x16x32_bf16 v[122:125], v[78:81], v[170:173], v[122:125]
	v_mfma_f32_16x16x32_bf16 v[122:125], v[86:89], v[174:177], v[122:125]
	v_mfma_f32_16x16x32_bf16 v[138:141], v[78:81], v[162:165], v[138:141]
	v_mfma_f32_16x16x32_bf16 v[138:141], v[86:89], v[166:169], v[138:141]
	v_mfma_f32_16x16x32_bf16 v[106:109], v[78:81], v[178:181], v[106:109]
	v_mfma_f32_16x16x32_bf16 v[106:109], v[86:89], v[182:185], v[106:109]
	v_mfma_f32_16x16x32_bf16 v[90:93], v[78:81], v[216:219], v[90:93]
	v_mfma_f32_16x16x32_bf16 v[90:93], v[86:89], v[220:223], v[90:93]
	v_mfma_f32_16x16x32_bf16 v[94:97], v[66:69], v[216:219], v[94:97]
	v_mfma_f32_16x16x32_bf16 v[94:97], v[70:73], v[220:223], v[94:97]
	v_mfma_f32_16x16x32_bf16 v[110:113], v[66:69], v[178:181], v[110:113]
	v_mfma_f32_16x16x32_bf16 v[110:113], v[70:73], v[182:185], v[110:113]
	v_mfma_f32_16x16x32_bf16 v[134:137], v[146:149], v[162:165], v[134:137]
	v_mfma_f32_16x16x32_bf16 v[134:137], v[150:153], v[166:169], v[134:137]
	v_mfma_f32_16x16x32_bf16 v[118:121], v[146:149], v[170:173], v[118:121]
	v_mfma_f32_16x16x32_bf16 v[118:121], v[150:153], v[174:177], v[118:121]
	v_mfma_f32_16x16x32_bf16 v[114:117], v[154:157], v[170:173], v[114:117]
	v_mfma_f32_16x16x32_bf16 v[114:117], v[158:161], v[174:177], v[114:117]
	v_mfma_f32_16x16x32_bf16 v[130:133], v[154:157], v[162:165], v[130:133]
	v_mfma_f32_16x16x32_bf16 v[130:133], v[158:161], v[166:169], v[130:133]
	v_mfma_f32_16x16x32_bf16 v[98:101], v[154:157], v[178:181], v[98:101]
	v_mfma_f32_16x16x32_bf16 v[98:101], v[158:161], v[182:185], v[98:101]
	v_mfma_f32_16x16x32_bf16 v[74:77], v[154:157], v[216:219], v[74:77]
	v_mfma_f32_16x16x32_bf16 v[74:77], v[158:161], v[220:223], v[74:77]
	v_mfma_f32_16x16x32_bf16 v[82:85], v[146:149], v[216:219], v[82:85]
	v_mfma_f32_16x16x32_bf16 v[82:85], v[150:153], v[220:223], v[82:85]
	v_mfma_f32_16x16x32_bf16 v[102:105], v[146:149], v[178:181], v[102:105]
	v_mfma_f32_16x16x32_bf16 v[102:105], v[150:153], v[182:185], v[102:105]
	s_barrier
; #define PG8_STAGE(bufoff, gbase, voff) do { _Pragma("unroll") for (int _i = 0; _i < 2; ++_i) \
;         __builtin_amdgcn_global_load_lds((const unsigned*)((const char*)(gbase) + (voff)[_i]), (PG8_LAS unsigned*)(lds + (bufoff) + ldsw + _i * 8192), 16, 0, 0); } while (0)
; #define PG8_LDA(dst, b, h) do { _Pragma("unroll") for (int m = 0; m < 4; ++m) _Pragma("unroll") for (int k = 0; k < 2; ++k) dst[m][k] = *(const PG8_LAS bf16x8*)(lds + PG8_SA(b, h) + aoff + m * 2048 + k * 1024); } while (0)
; #define PG8_LDB(dst, b, h) do { _Pragma("unroll") for (int n = 0; n < 2; ++n) _Pragma("unroll") for (int k = 0; k < 2; ++k) dst[n][k] = *(const PG8_LAS bf16x8*)(lds + PG8_SB(b, h) + boff + n * 2048 + k * 1024); } while (0)
; #define PG8_BAR __builtin_amdgcn_s_barrier()
; template <class Epi, class Sched, bool ALIGN_EPI = false, bool SP2 = false>
; __device__ __forceinline__ void gemm_phase(PG8_LAS unsigned char* lds, const Gemm g, const Sched& S, const Epi& E) {
;     ...
;             const bool last = (t == nt - 2);
;             const char* a1 = cA + (size_t)(t + 1) * kstep;
;             const char* a2 = last ? nA : cA + (size_t)(t + 2) * kstep; const char* b2 = last ? nB : cB + (size_t)(t + 2) * kstep;
;             const char* a3 = a2 + kstep; const char* b3 = b2 + kstep;
;             if (last && has_next) S.a_ready(nxt);
;             if constexpr (SP2) {
;             PG8_LDB(B0, 0, 0); PG8_LDB(B1, 0, 1); PG8_SCHED; PG8_LDA(At, 0, 0); PG8_STAGE(PG8_SA(1, 1), a1 + hstep, voffA);
;             PG8_WAIT_V(8); PG8_WAIT_L(0); PG8_BAR; PG8_MMA(0, 0, At, B0); PG8_MMA(0, 1, At, B1); PG8_BAR; PG8_SCHED;
;             PG8_LDA(At, 0, 1); PG8_STAGE(PG8_SB(0, 0), b2, voffB); PG8_STAGE(PG8_SB(0, 1), b2 + hstepB, voffB); PG8_STAGE(PG8_SA(0, 0), a2, voffA);
;             PG8_WAIT_V(8); PG8_WAIT_L(0); PG8_BAR; PG8_MMA(1, 0, At, B0); PG8_MMA(1, 1, At, B1); PG8_BAR; PG8_SCHED;
;             PG8_LDB(B0, 1, 0); PG8_LDB(B1, 1, 1); PG8_SCHED; PG8_LDA(At, 1, 0); PG8_STAGE(PG8_SA(0, 1), a2 + hstep, voffA);
;             PG8_WAIT_V(8); PG8_WAIT_L(0); PG8_BAR; PG8_MMA(0, 0, At, B0); PG8_MMA(0, 1, At, B1); PG8_BAR; PG8_SCHED;
;             PG8_LDA(At, 1, 1); PG8_STAGE(PG8_SB(1, 0), b3, voffB); PG8_STAGE(PG8_SB(1, 1), b3 + hstepB, voffB); PG8_STAGE(PG8_SA(1, 0), a3, voffA);
;             PG8_WAIT_V(8); PG8_WAIT_L(0); PG8_BAR; PG8_MMA(1, 0, At, B0); PG8_MMA(1, 1, At, B1); PG8_BAR; PG8_SCHED;
	s_add_i32 s9, s9, s25
	s_mov_b32 m0, s9
	ds_read_b128 v[162:165], v236 offset:49152
	ds_read_b128 v[166:169], v236 offset:50176
	ds_read_b128 v[170:173], v236 offset:51200
	ds_read_b128 v[174:177], v236 offset:52224
	ds_read_b128 v[178:181], v236 offset:53248
	ds_read_b128 v[182:185], v236 offset:54272
	ds_read_b128 v[216:219], v236 offset:55296
	ds_read_b128 v[220:223], v236 offset:56320
	s_add_u32 s100, s46, s60
	s_addc_u32 s101, s47, s61
	global_load_lds_dwordx4 v190, s[100:101]
	s_add_i32 m0, s9, 0x2000
	s_add_u32 s10, s46, 0x20080
	s_addc_u32 s11, s47, 0
	s_add_i32 s9, s12, s25
	global_load_lds_dwordx4 v206, s[100:101]
	s_mov_b32 m0, s9
	s_nop 0
	global_load_lds_dwordx4 v190, s[10:11]
	s_add_i32 m0, s9, 0x2000
	s_nop 0
	global_load_lds_dwordx4 v206, s[10:11]
	s_mov_b32 m0, s75
	s_add_u32 s100, s94, s60
	s_addc_u32 s101, s95, s61
	global_load_lds_dwordx4 v210, s[100:101]
	s_mov_b32 m0, s0
	s_nop 0
	global_load_lds_dwordx4 v208, s[100:101]
	s_waitcnt vmcnt(8)
	s_waitcnt lgkmcnt(0)
	s_barrier
	v_mfma_f32_16x16x32_bf16 v[62:65], v[66:69], v[162:165], v[62:65]
	v_mfma_f32_16x16x32_bf16 v[62:65], v[70:73], v[166:169], v[62:65]
	v_mfma_f32_16x16x32_bf16 v[46:49], v[66:69], v[170:173], v[46:49]
	v_mfma_f32_16x16x32_bf16 v[46:49], v[70:73], v[174:177], v[46:49]
	v_mfma_f32_16x16x32_bf16 v[42:45], v[78:81], v[170:173], v[42:45]
	v_mfma_f32_16x16x32_bf16 v[42:45], v[86:89], v[174:177], v[42:45]
	v_mfma_f32_16x16x32_bf16 v[58:61], v[78:81], v[162:165], v[58:61]
	v_mfma_f32_16x16x32_bf16 v[58:61], v[86:89], v[166:169], v[58:61]
	v_mfma_f32_16x16x32_bf16 v[26:29], v[78:81], v[178:181], v[26:29]
	v_mfma_f32_16x16x32_bf16 v[26:29], v[86:89], v[182:185], v[26:29]
	v_mfma_f32_16x16x32_bf16 v[10:13], v[78:81], v[216:219], v[10:13]
	v_mfma_f32_16x16x32_bf16 v[10:13], v[86:89], v[220:223], v[10:13]
	v_mfma_f32_16x16x32_bf16 v[14:17], v[66:69], v[216:219], v[14:17]
	v_mfma_f32_16x16x32_bf16 v[14:17], v[70:73], v[220:223], v[14:17]
	v_mfma_f32_16x16x32_bf16 v[30:33], v[66:69], v[178:181], v[30:33]
	v_mfma_f32_16x16x32_bf16 v[30:33], v[70:73], v[182:185], v[30:33]
	v_mfma_f32_16x16x32_bf16 v[54:57], v[146:149], v[162:165], v[54:57]
	v_mfma_f32_16x16x32_bf16 v[54:57], v[150:153], v[166:169], v[54:57]
	v_mfma_f32_16x16x32_bf16 v[38:41], v[146:149], v[170:173], v[38:41]
	v_mfma_f32_16x16x32_bf16 v[38:41], v[150:153], v[174:177], v[38:41]
	v_mfma_f32_16x16x32_bf16 v[34:37], v[154:157], v[170:173], v[34:37]
	v_mfma_f32_16x16x32_bf16 v[34:37], v[158:161], v[174:177], v[34:37]
	v_mfma_f32_16x16x32_bf16 v[50:53], v[154:157], v[162:165], v[50:53]
	v_mfma_f32_16x16x32_bf16 v[50:53], v[158:161], v[166:169], v[50:53]
	v_mfma_f32_16x16x32_bf16 v[18:21], v[154:157], v[178:181], v[18:21]
	v_mfma_f32_16x16x32_bf16 v[18:21], v[158:161], v[182:185], v[18:21]
	v_mfma_f32_16x16x32_bf16 v[2:5], v[154:157], v[216:219], v[2:5]
	v_mfma_f32_16x16x32_bf16 v[2:5], v[158:161], v[220:223], v[2:5]
	v_mfma_f32_16x16x32_bf16 v[6:9], v[146:149], v[216:219], v[6:9]
	v_mfma_f32_16x16x32_bf16 v[6:9], v[150:153], v[220:223], v[6:9]
	v_mfma_f32_16x16x32_bf16 v[22:25], v[146:149], v[178:181], v[22:25]
	v_mfma_f32_16x16x32_bf16 v[22:25], v[150:153], v[182:185], v[22:25]
	s_barrier
	s_add_i32 s8, s8, 2
	s_add_u32 s38, s38, 0x100
	s_addc_u32 s39, s39, 0
	s_add_u32 s6, s6, 0x100
	s_addc_u32 s7, s7, 0
	s_cmp_gt_u32 s8, 29
.LBB0_927:
	s_add_u32 s9, s38, 0xfff80080
	s_addc_u32 s10, s39, -1
	s_add_i32 s11, 0, 0x10000
	s_cmp_eq_u32 s8, 28
	s_cselect_b32 s95, s36, s10
	s_cselect_b32 s94, s37, s9
	s_cselect_b32 s47, s4, s7
	s_cselect_b32 s46, s5, s6
	s_add_i32 s9, 0, 0x14000
	ds_read_b128 v[66:69], v186
	ds_read_b128 v[70:73], v186 offset:1024
	ds_read_b128 v[78:81], v186 offset:2048
	ds_read_b128 v[86:89], v186 offset:3072
	ds_read_b128 v[146:149], v187
	ds_read_b128 v[150:153], v187 offset:1024
	ds_read_b128 v[154:157], v187 offset:2048
	ds_read_b128 v[158:161], v187 offset:3072
	s_add_i32 m0, s66, 0xc000
	ds_read_b128 v[162:165], v236
	ds_read_b128 v[166:169], v236 offset:1024
	ds_read_b128 v[170:173], v236 offset:2048
	ds_read_b128 v[174:177], v236 offset:3072
	ds_read_b128 v[178:181], v236 offset:4096
	ds_read_b128 v[182:185], v236 offset:5120
	ds_read_b128 v[216:219], v236 offset:6144
	ds_read_b128 v[220:223], v236 offset:7168
	global_load_lds_dwordx4 v212, s[38:39]
	s_add_i32 m0, s66, 0xe000
	s_nop 0
	global_load_lds_dwordx4 v214, s[38:39]
	s_waitcnt vmcnt(8)
	s_waitcnt lgkmcnt(0)
	s_barrier
	v_mfma_f32_16x16x32_bf16 v[142:145], v[66:69], v[162:165], v[142:145]
	v_mfma_f32_16x16x32_bf16 v[142:145], v[70:73], v[166:169], v[142:145]
	v_mfma_f32_16x16x32_bf16 v[126:129], v[66:69], v[170:173], v[126:129]
	v_mfma_f32_16x16x32_bf16 v[126:129], v[70:73], v[174:177], v[126:129]
	v_mfma_f32_16x16x32_bf16 v[122:125], v[78:81], v[170:173], v[122:125]
	v_mfma_f32_16x16x32_bf16 v[122:125], v[86:89], v[174:177], v[122:125]
	v_mfma_f32_16x16x32_bf16 v[138:141], v[78:81], v[162:165], v[138:141]
	v_mfma_f32_16x16x32_bf16 v[138:141], v[86:89], v[166:169], v[138:141]
	v_mfma_f32_16x16x32_bf16 v[106:109], v[78:81], v[178:181], v[106:109]
	v_mfma_f32_16x16x32_bf16 v[106:109], v[86:89], v[182:185], v[106:109]
	v_mfma_f32_16x16x32_bf16 v[90:93], v[78:81], v[216:219], v[90:93]
	v_mfma_f32_16x16x32_bf16 v[90:93], v[86:89], v[220:223], v[90:93]
	v_mfma_f32_16x16x32_bf16 v[94:97], v[66:69], v[216:219], v[94:97]
	v_mfma_f32_16x16x32_bf16 v[94:97], v[70:73], v[220:223], v[94:97]
	v_mfma_f32_16x16x32_bf16 v[110:113], v[66:69], v[178:181], v[110:113]
	v_mfma_f32_16x16x32_bf16 v[110:113], v[70:73], v[182:185], v[110:113]
	v_mfma_f32_16x16x32_bf16 v[134:137], v[146:149], v[162:165], v[134:137]
	v_mfma_f32_16x16x32_bf16 v[134:137], v[150:153], v[166:169], v[134:137]
	v_mfma_f32_16x16x32_bf16 v[118:121], v[146:149], v[170:173], v[118:121]
	v_mfma_f32_16x16x32_bf16 v[118:121], v[150:153], v[174:177], v[118:121]
	v_mfma_f32_16x16x32_bf16 v[114:117], v[154:157], v[170:173], v[114:117]
	v_mfma_f32_16x16x32_bf16 v[114:117], v[158:161], v[174:177], v[114:117]
	v_mfma_f32_16x16x32_bf16 v[130:133], v[154:157], v[162:165], v[130:133]
	v_mfma_f32_16x16x32_bf16 v[130:133], v[158:161], v[166:169], v[130:133]
	v_mfma_f32_16x16x32_bf16 v[98:101], v[154:157], v[178:181], v[98:101]
	v_mfma_f32_16x16x32_bf16 v[98:101], v[158:161], v[182:185], v[98:101]
	v_mfma_f32_16x16x32_bf16 v[74:77], v[154:157], v[216:219], v[74:77]
	v_mfma_f32_16x16x32_bf16 v[74:77], v[158:161], v[220:223], v[74:77]
	v_mfma_f32_16x16x32_bf16 v[82:85], v[146:149], v[216:219], v[82:85]
	v_mfma_f32_16x16x32_bf16 v[82:85], v[150:153], v[220:223], v[82:85]
	v_mfma_f32_16x16x32_bf16 v[102:105], v[146:149], v[178:181], v[102:105]
	v_mfma_f32_16x16x32_bf16 v[102:105], v[150:153], v[182:185], v[102:105]
	s_barrier
; #define PG8_STAGE(bufoff, gbase, voff) do { _Pragma("unroll") for (int _i = 0; _i < 2; ++_i) \
;         __builtin_amdgcn_global_load_lds((const unsigned*)((const char*)(gbase) + (voff)[_i]), (PG8_LAS unsigned*)(lds + (bufoff) + ldsw + _i * 8192), 16, 0, 0); } while (0)
; #define PG8_LDA(dst, b, h) do { _Pragma("unroll") for (int m = 0; m < 4; ++m) _Pragma("unroll") for (int k = 0; k < 2; ++k) dst[m][k] = *(const PG8_LAS bf16x8*)(lds + PG8_SA(b, h) + aoff + m * 2048 + k * 1024); } while (0)
; #define PG8_LDB(dst, b, h) do { _Pragma("unroll") for (int n = 0; n < 2; ++n) _Pragma("unroll") for (int k = 0; k < 2; ++k) dst[n][k] = *(const PG8_LAS bf16x8*)(lds + PG8_SB(b, h) + boff + n * 2048 + k * 1024); } while (0)
; #define PG8_MMA(ai, bj, At, Bt) do { __builtin_amdgcn_s_setprio(1); _Pragma("unroll") for (int m = 0; m < 4; ++m) _Pragma("unroll") for (int n = 0; n < 2; ++n) _Pragma("unroll") for (int k = 0; k < 2; ++k) \
;         acc[ai][bj][m][n] = __builtin_amdgcn_mfma_f32_16x16x32_bf16(Bt[n][k], At[m][k], acc[ai][bj][m][n], 0, 0, 0); __builtin_amdgcn_s_setprio(0); } while (0)
; #define PG8_WAIT_V(n) asm volatile("s_waitcnt vmcnt(" #n ")" ::: "memory")
; #define PG8_WAIT_L(n) asm volatile("s_waitcnt lgkmcnt(" #n ")" ::: "memory")
; #define PG8_BAR __builtin_amdgcn_s_barrier()
; #define PG8_SCHED __builtin_amdgcn_sched_barrier(0)
; template <class Epi, class Sched, bool ALIGN_EPI = false, bool SP2 = false>
; __device__ __forceinline__ void gemm_phase(PG8_LAS unsigned char* lds, const Gemm g, const Sched& S, const Epi& E) {
;     ...
;             PG8_LDA(At, 0, 1); PG8_STAGE(PG8_SB(0, 0), b2, voffB); PG8_STAGE(PG8_SB(0, 1), b2 + hstepB, voffB); PG8_STAGE(PG8_SA(0, 0), a2, voffA);
;             PG8_WAIT_V(8); PG8_WAIT_L(0); PG8_BAR; PG8_MMA(1, 0, At, B0); PG8_MMA(1, 1, At, B1); PG8_BAR; PG8_SCHED;
;             PG8_LDB(B0, 1, 0); PG8_LDB(B1, 1, 1); PG8_SCHED; PG8_LDA(At, 1, 0); PG8_STAGE(PG8_SA(0, 1), a2 + hstep, voffA);
	s_add_i32 s10, s11, s25
	s_mov_b32 m0, s10
	ds_read_b128 v[162:165], v236 offset:16384
	ds_read_b128 v[166:169], v236 offset:17408
	ds_read_b128 v[170:173], v236 offset:18432
	ds_read_b128 v[174:177], v236 offset:19456
	ds_read_b128 v[178:181], v236 offset:20480
	ds_read_b128 v[182:185], v236 offset:21504
	ds_read_b128 v[216:219], v236 offset:22528
	ds_read_b128 v[220:223], v236 offset:23552
	global_load_lds_dwordx4 v190, s[46:47]
	s_add_i32 m0, s10, 0x2000
	s_add_u32 s10, s46, 0x20000
	s_addc_u32 s11, s47, 0
	s_add_i32 s9, s9, s25
	global_load_lds_dwordx4 v206, s[46:47]
	s_mov_b32 m0, s9
	s_nop 0
	global_load_lds_dwordx4 v190, s[10:11]
	s_add_i32 m0, s9, 0x2000
	s_nop 0
	global_load_lds_dwordx4 v206, s[10:11]
	s_mov_b32 m0, s66
	s_nop 0
	global_load_lds_dwordx4 v210, s[94:95]
	s_mov_b32 m0, s67
	s_nop 0
	global_load_lds_dwordx4 v208, s[94:95]
	s_waitcnt vmcnt(8)
	s_waitcnt lgkmcnt(0)
	s_barrier
	v_mfma_f32_16x16x32_bf16 v[62:65], v[66:69], v[162:165], v[62:65]
	v_mfma_f32_16x16x32_bf16 v[62:65], v[70:73], v[166:169], v[62:65]
	v_mfma_f32_16x16x32_bf16 v[46:49], v[66:69], v[170:173], v[46:49]
	v_mfma_f32_16x16x32_bf16 v[46:49], v[70:73], v[174:177], v[46:49]
	v_mfma_f32_16x16x32_bf16 v[42:45], v[78:81], v[170:173], v[42:45]
	v_mfma_f32_16x16x32_bf16 v[42:45], v[86:89], v[174:177], v[42:45]
	v_mfma_f32_16x16x32_bf16 v[58:61], v[78:81], v[162:165], v[58:61]
	v_mfma_f32_16x16x32_bf16 v[58:61], v[86:89], v[166:169], v[58:61]
	v_mfma_f32_16x16x32_bf16 v[26:29], v[78:81], v[178:181], v[26:29]
	v_mfma_f32_16x16x32_bf16 v[26:29], v[86:89], v[182:185], v[26:29]
	v_mfma_f32_16x16x32_bf16 v[10:13], v[78:81], v[216:219], v[10:13]
	v_mfma_f32_16x16x32_bf16 v[10:13], v[86:89], v[220:223], v[10:13]
	v_mfma_f32_16x16x32_bf16 v[14:17], v[66:69], v[216:219], v[14:17]
	v_mfma_f32_16x16x32_bf16 v[14:17], v[70:73], v[220:223], v[14:17]
	v_mfma_f32_16x16x32_bf16 v[30:33], v[66:69], v[178:181], v[30:33]
	v_mfma_f32_16x16x32_bf16 v[30:33], v[70:73], v[182:185], v[30:33]
	v_mfma_f32_16x16x32_bf16 v[54:57], v[146:149], v[162:165], v[54:57]
	v_mfma_f32_16x16x32_bf16 v[54:57], v[150:153], v[166:169], v[54:57]
	v_mfma_f32_16x16x32_bf16 v[38:41], v[146:149], v[170:173], v[38:41]
	v_mfma_f32_16x16x32_bf16 v[38:41], v[150:153], v[174:177], v[38:41]
	v_mfma_f32_16x16x32_bf16 v[34:37], v[154:157], v[170:173], v[34:37]
	v_mfma_f32_16x16x32_bf16 v[34:37], v[158:161], v[174:177], v[34:37]
	v_mfma_f32_16x16x32_bf16 v[50:53], v[154:157], v[162:165], v[50:53]
	v_mfma_f32_16x16x32_bf16 v[50:53], v[158:161], v[166:169], v[50:53]
	v_mfma_f32_16x16x32_bf16 v[18:21], v[154:157], v[178:181], v[18:21]
	v_mfma_f32_16x16x32_bf16 v[18:21], v[158:161], v[182:185], v[18:21]
	v_mfma_f32_16x16x32_bf16 v[2:5], v[154:157], v[216:219], v[2:5]
	v_mfma_f32_16x16x32_bf16 v[2:5], v[158:161], v[220:223], v[2:5]
	v_mfma_f32_16x16x32_bf16 v[6:9], v[146:149], v[216:219], v[6:9]
	v_mfma_f32_16x16x32_bf16 v[6:9], v[150:153], v[220:223], v[6:9]
	v_mfma_f32_16x16x32_bf16 v[22:25], v[146:149], v[178:181], v[22:25]
	v_mfma_f32_16x16x32_bf16 v[22:25], v[150:153], v[182:185], v[22:25]
	s_barrier
	s_add_i32 s9, 0, 0x18000
	s_add_i32 s12, 0, 0x1c000
	ds_read_b128 v[66:69], v198
	ds_read_b128 v[70:73], v198 offset:1024
	ds_read_b128 v[78:81], v198 offset:2048
	ds_read_b128 v[86:89], v198 offset:3072
	ds_read_b128 v[146:149], v199
	ds_read_b128 v[150:153], v199 offset:1024
	ds_read_b128 v[154:157], v199 offset:2048
	ds_read_b128 v[158:161], v199 offset:3072
	s_add_u32 s10, s94, 0x80000
	s_addc_u32 s11, s95, 0
	s_mov_b32 m0, s59
	ds_read_b128 v[162:165], v236 offset:32768
	ds_read_b128 v[166:169], v236 offset:33792
	ds_read_b128 v[170:173], v236 offset:34816
	ds_read_b128 v[174:177], v236 offset:35840
	ds_read_b128 v[178:181], v236 offset:36864
	ds_read_b128 v[182:185], v236 offset:37888
	ds_read_b128 v[216:219], v236 offset:38912
	ds_read_b128 v[220:223], v236 offset:39936
	global_load_lds_dwordx4 v210, s[10:11]
	s_mov_b32 m0, s74
	s_nop 0
	global_load_lds_dwordx4 v208, s[10:11]
	s_waitcnt vmcnt(8)
	s_waitcnt lgkmcnt(0)
	s_barrier
; #define PG8_STAGE(bufoff, gbase, voff) do { _Pragma("unroll") for (int _i = 0; _i < 2; ++_i) \
;         __builtin_amdgcn_global_load_lds((const unsigned*)((const char*)(gbase) + (voff)[_i]), (PG8_LAS unsigned*)(lds + (bufoff) + ldsw + _i * 8192), 16, 0, 0); } while (0)
; #define PG8_LDA(dst, b, h) do { _Pragma("unroll") for (int m = 0; m < 4; ++m) _Pragma("unroll") for (int k = 0; k < 2; ++k) dst[m][k] = *(const PG8_LAS bf16x8*)(lds + PG8_SA(b, h) + aoff + m * 2048 + k * 1024); } while (0)
; #define PG8_MMA(ai, bj, At, Bt) do { __builtin_amdgcn_s_setprio(1); _Pragma("unroll") for (int m = 0; m < 4; ++m) _Pragma("unroll") for (int n = 0; n < 2; ++n) _Pragma("unroll") for (int k = 0; k < 2; ++k) \
;         acc[ai][bj][m][n] = __builtin_amdgcn_mfma_f32_16x16x32_bf16(Bt[n][k], At[m][k], acc[ai][bj][m][n], 0, 0, 0); __builtin_amdgcn_s_setprio(0); } while (0)
; #define PG8_WAIT_V(n) asm volatile("s_waitcnt vmcnt(" #n ")" ::: "memory")
; #define PG8_WAIT_L(n) asm volatile("s_waitcnt lgkmcnt(" #n ")" ::: "memory")
; #define PG8_BAR __builtin_amdgcn_s_barrier()
; #define PG8_SCHED __builtin_amdgcn_sched_barrier(0)
; template <class Epi, class Sched, bool ALIGN_EPI = false, bool SP2 = false>
; __device__ __forceinline__ void gemm_phase(PG8_LAS unsigned char* lds, const Gemm g, const Sched& S, const Epi& E) {
;     ...
;             PG8_WAIT_V(8); PG8_WAIT_L(0); PG8_BAR; PG8_MMA(0, 0, At, B0); PG8_MMA(0, 1, At, B1); PG8_BAR; PG8_SCHED;
;             PG8_LDA(At, 1, 1); PG8_STAGE(PG8_SB(1, 0), b3, voffB); PG8_STAGE(PG8_SB(1, 1), b3 + hstepB, voffB); PG8_STAGE(PG8_SA(1, 0), a3, voffA);
;             PG8_WAIT_V(8); PG8_WAIT_L(0); PG8_BAR; PG8_MMA(1, 0, At, B0); PG8_MMA(1, 1, At, B1); PG8_BAR; PG8_SCHED;
;     ...
;         if constexpr (ALIGN_EPI) { if (wr == 0) PG8_BAR; }
	v_mfma_f32_16x16x32_bf16 v[142:145], v[66:69], v[162:165], v[142:145]
	v_mfma_f32_16x16x32_bf16 v[142:145], v[70:73], v[166:169], v[142:145]
	v_mfma_f32_16x16x32_bf16 v[126:129], v[66:69], v[170:173], v[126:129]
	v_mfma_f32_16x16x32_bf16 v[126:129], v[70:73], v[174:177], v[126:129]
	v_mfma_f32_16x16x32_bf16 v[122:125], v[78:81], v[170:173], v[122:125]
	v_mfma_f32_16x16x32_bf16 v[122:125], v[86:89], v[174:177], v[122:125]
	v_mfma_f32_16x16x32_bf16 v[138:141], v[78:81], v[162:165], v[138:141]
	v_mfma_f32_16x16x32_bf16 v[138:141], v[86:89], v[166:169], v[138:141]
	v_mfma_f32_16x16x32_bf16 v[106:109], v[78:81], v[178:181], v[106:109]
	v_mfma_f32_16x16x32_bf16 v[106:109], v[86:89], v[182:185], v[106:109]
	v_mfma_f32_16x16x32_bf16 v[90:93], v[78:81], v[216:219], v[90:93]
	v_mfma_f32_16x16x32_bf16 v[90:93], v[86:89], v[220:223], v[90:93]
	v_mfma_f32_16x16x32_bf16 v[94:97], v[66:69], v[216:219], v[94:97]
	v_mfma_f32_16x16x32_bf16 v[94:97], v[70:73], v[220:223], v[94:97]
	v_mfma_f32_16x16x32_bf16 v[110:113], v[66:69], v[178:181], v[110:113]
	v_mfma_f32_16x16x32_bf16 v[110:113], v[70:73], v[182:185], v[110:113]
	v_mfma_f32_16x16x32_bf16 v[134:137], v[146:149], v[162:165], v[134:137]
	v_mfma_f32_16x16x32_bf16 v[134:137], v[150:153], v[166:169], v[134:137]
	v_mfma_f32_16x16x32_bf16 v[118:121], v[146:149], v[170:173], v[118:121]
	v_mfma_f32_16x16x32_bf16 v[118:121], v[150:153], v[174:177], v[118:121]
	v_mfma_f32_16x16x32_bf16 v[114:117], v[154:157], v[170:173], v[114:117]
	v_mfma_f32_16x16x32_bf16 v[114:117], v[158:161], v[174:177], v[114:117]
	v_mfma_f32_16x16x32_bf16 v[130:133], v[154:157], v[162:165], v[130:133]
	v_mfma_f32_16x16x32_bf16 v[130:133], v[158:161], v[166:169], v[130:133]
	v_mfma_f32_16x16x32_bf16 v[98:101], v[154:157], v[178:181], v[98:101]
	v_mfma_f32_16x16x32_bf16 v[98:101], v[158:161], v[182:185], v[98:101]
	v_mfma_f32_16x16x32_bf16 v[74:77], v[154:157], v[216:219], v[74:77]
	v_mfma_f32_16x16x32_bf16 v[74:77], v[158:161], v[220:223], v[74:77]
	v_mfma_f32_16x16x32_bf16 v[82:85], v[146:149], v[216:219], v[82:85]
	v_mfma_f32_16x16x32_bf16 v[82:85], v[150:153], v[220:223], v[82:85]
	v_mfma_f32_16x16x32_bf16 v[102:105], v[146:149], v[178:181], v[102:105]
	v_mfma_f32_16x16x32_bf16 v[102:105], v[150:153], v[182:185], v[102:105]
	s_barrier
	s_add_i32 s9, s9, s25
	s_mov_b32 m0, s9
	ds_read_b128 v[162:165], v236 offset:49152
	ds_read_b128 v[166:169], v236 offset:50176
	ds_read_b128 v[170:173], v236 offset:51200
	ds_read_b128 v[174:177], v236 offset:52224
	ds_read_b128 v[178:181], v236 offset:53248
	ds_read_b128 v[182:185], v236 offset:54272
	ds_read_b128 v[216:219], v236 offset:55296
	ds_read_b128 v[220:223], v236 offset:56320
	s_add_u32 s100, s46, s60
	s_addc_u32 s101, s47, s61
	global_load_lds_dwordx4 v190, s[100:101]
	s_add_i32 m0, s9, 0x2000
	s_add_u32 s10, s46, 0x20080
	s_addc_u32 s11, s47, 0
	s_add_i32 s9, s12, s25
	global_load_lds_dwordx4 v206, s[100:101]
	s_mov_b32 m0, s9
	s_nop 0
	global_load_lds_dwordx4 v190, s[10:11]
	s_add_i32 m0, s9, 0x2000
	s_nop 0
	global_load_lds_dwordx4 v206, s[10:11]
	s_mov_b32 m0, s75
	s_add_u32 s100, s94, s60
	s_addc_u32 s101, s95, s61
	global_load_lds_dwordx4 v210, s[100:101]
	s_mov_b32 m0, s0
	s_nop 0
	global_load_lds_dwordx4 v208, s[100:101]
	s_waitcnt vmcnt(8)
	s_waitcnt lgkmcnt(0)
	s_barrier
	v_mfma_f32_16x16x32_bf16 v[62:65], v[66:69], v[162:165], v[62:65]
	v_mfma_f32_16x16x32_bf16 v[62:65], v[70:73], v[166:169], v[62:65]
	v_mfma_f32_16x16x32_bf16 v[46:49], v[66:69], v[170:173], v[46:49]
	v_mfma_f32_16x16x32_bf16 v[46:49], v[70:73], v[174:177], v[46:49]
	v_mfma_f32_16x16x32_bf16 v[42:45], v[78:81], v[170:173], v[42:45]
	v_mfma_f32_16x16x32_bf16 v[42:45], v[86:89], v[174:177], v[42:45]
	v_mfma_f32_16x16x32_bf16 v[58:61], v[78:81], v[162:165], v[58:61]
	v_mfma_f32_16x16x32_bf16 v[58:61], v[86:89], v[166:169], v[58:61]
	v_mfma_f32_16x16x32_bf16 v[26:29], v[78:81], v[178:181], v[26:29]
	v_mfma_f32_16x16x32_bf16 v[26:29], v[86:89], v[182:185], v[26:29]
	v_mfma_f32_16x16x32_bf16 v[10:13], v[78:81], v[216:219], v[10:13]
	v_mfma_f32_16x16x32_bf16 v[10:13], v[86:89], v[220:223], v[10:13]
	v_mfma_f32_16x16x32_bf16 v[14:17], v[66:69], v[216:219], v[14:17]
	v_mfma_f32_16x16x32_bf16 v[14:17], v[70:73], v[220:223], v[14:17]
	v_mfma_f32_16x16x32_bf16 v[30:33], v[66:69], v[178:181], v[30:33]
	v_mfma_f32_16x16x32_bf16 v[30:33], v[70:73], v[182:185], v[30:33]
	v_mfma_f32_16x16x32_bf16 v[54:57], v[146:149], v[162:165], v[54:57]
	v_mfma_f32_16x16x32_bf16 v[54:57], v[150:153], v[166:169], v[54:57]
	v_mfma_f32_16x16x32_bf16 v[38:41], v[146:149], v[170:173], v[38:41]
	v_mfma_f32_16x16x32_bf16 v[38:41], v[150:153], v[174:177], v[38:41]
	v_mfma_f32_16x16x32_bf16 v[34:37], v[154:157], v[170:173], v[34:37]
	v_mfma_f32_16x16x32_bf16 v[34:37], v[158:161], v[174:177], v[34:37]
	v_mfma_f32_16x16x32_bf16 v[50:53], v[154:157], v[162:165], v[50:53]
	v_mfma_f32_16x16x32_bf16 v[50:53], v[158:161], v[166:169], v[50:53]
	v_mfma_f32_16x16x32_bf16 v[18:21], v[154:157], v[178:181], v[18:21]
	v_mfma_f32_16x16x32_bf16 v[18:21], v[158:161], v[182:185], v[18:21]
	v_mfma_f32_16x16x32_bf16 v[2:5], v[154:157], v[216:219], v[2:5]
	v_mfma_f32_16x16x32_bf16 v[2:5], v[158:161], v[220:223], v[2:5]
	v_mfma_f32_16x16x32_bf16 v[6:9], v[146:149], v[216:219], v[6:9]
	v_mfma_f32_16x16x32_bf16 v[6:9], v[150:153], v[220:223], v[6:9]
	v_mfma_f32_16x16x32_bf16 v[22:25], v[146:149], v[178:181], v[22:25]
	v_mfma_f32_16x16x32_bf16 v[22:25], v[150:153], v[182:185], v[22:25]
	s_barrier
	s_add_i32 s8, s8, 2
	s_add_u32 s38, s38, 0x100
	s_addc_u32 s39, s39, 0
	s_add_u32 s6, s6, 0x100
	s_addc_u32 s7, s7, 0
	s_cmp_gt_u32 s8, 29
	s_cbranch_scc0 .LBB0_927
	s_and_b64 vcc, exec, s[70:71]
	s_cbranch_vccz .LBB0_930
	s_barrier

; #define PG8_STAGE(bufoff, gbase, voff) do { _Pragma("unroll") for (int _i = 0; _i < 2; ++_i) \
;         __builtin_amdgcn_global_load_lds((const unsigned*)((const char*)(gbase) + (voff)[_i]), (PG8_LAS unsigned*)(lds + (bufoff) + ldsw + _i * 8192), 16, 0, 0); } while (0)
; #define PG8_LDA(dst, b, h) do { _Pragma("unroll") for (int m = 0; m < 4; ++m) _Pragma("unroll") for (int k = 0; k < 2; ++k) dst[m][k] = *(const PG8_LAS bf16x8*)(lds + PG8_SA(b, h) + aoff + m * 2048 + k * 1024); } while (0)
; #define PG8_LDB(dst, b, h) do { _Pragma("unroll") for (int n = 0; n < 2; ++n) _Pragma("unroll") for (int k = 0; k < 2; ++k) dst[n][k] = *(const PG8_LAS bf16x8*)(lds + PG8_SB(b, h) + boff + n * 2048 + k * 1024); } while (0)
; #define PG8_MMA(ai, bj, At, Bt) do { __builtin_amdgcn_s_setprio(1); _Pragma("unroll") for (int m = 0; m < 4; ++m) _Pragma("unroll") for (int n = 0; n < 2; ++n) _Pragma("unroll") for (int k = 0; k < 2; ++k) \
;         acc[ai][bj][m][n] = __builtin_amdgcn_mfma_f32_16x16x32_bf16(Bt[n][k], At[m][k], acc[ai][bj][m][n], 0, 0, 0); __builtin_amdgcn_s_setprio(0); } while (0)
; #define PG8_BAR __builtin_amdgcn_s_barrier()
; template <class Epi, class Sched, bool ALIGN_EPI = false, bool SP2 = false>
; __device__ __forceinline__ void gemm_phase(PG8_LAS unsigned char* lds, const Gemm g, const Sched& S, const Epi& E) {
;     ...
;         const bool has_next = S.next(ui + 1, nxt);
;         const char* nA = has_next ? (const char*)g.A + (size_t)nxt.pm * tstep : cA; const char* nB = has_next ? (const char*)g.Bt + (size_t)nxt.pn * tstep : cB;
;         for (int t = 0; t < nt; t += 2) {
;             const bool last = (t == nt - 2);
;             const char* a1 = cA + (size_t)(t + 1) * kstep;
;             const char* a2 = last ? nA : cA + (size_t)(t + 2) * kstep; const char* b2 = last ? nB : cB + (size_t)(t + 2) * kstep;
;             const char* a3 = a2 + kstep; const char* b3 = b2 + kstep;
;             if (last && has_next) S.a_ready(nxt);
;             if constexpr (SP2) {
;             PG8_LDB(B0, 0, 0); PG8_LDB(B1, 0, 1); PG8_SCHED; PG8_LDA(At, 0, 0); PG8_STAGE(PG8_SA(1, 1), a1 + hstep, voffA);
;             PG8_WAIT_V(8); PG8_WAIT_L(0); PG8_BAR; PG8_MMA(0, 0, At, B0); PG8_MMA(0, 1, At, B1); PG8_BAR; PG8_SCHED;
;             PG8_LDA(At, 0, 1); PG8_STAGE(PG8_SB(0, 0), b2, voffB); PG8_STAGE(PG8_SB(0, 1), b2 + hstepB, voffB); PG8_STAGE(PG8_SA(0, 0), a2, voffA);
.LBB0_1070:
	s_ashr_i32 s97, s96, 31
	s_lshl_b64 s[4:5], s[96:97], 22
	s_add_u32 s26, s0, s4
	s_addc_u32 s27, s1, s5
	s_and_b64 s[4:5], s[92:93], exec
	s_cselect_b32 s97, s27, s39
	s_cselect_b32 s4, s26, s38
	s_ashr_i32 s85, s84, 31
	s_lshl_b64 s[6:7], s[84:85], 22
	s_add_u32 s94, s56, s6
	s_addc_u32 s95, s57, s7
	s_and_b64 s[6:7], s[92:93], exec
	s_cselect_b32 s5, s95, s47
	s_cselect_b32 s6, s94, s46
	s_add_u32 s38, s38, 0x200080
	s_addc_u32 s39, s39, 0
	s_add_u32 s7, s46, 0x100
	s_addc_u32 s8, s47, 0
	s_mov_b32 s9, -2
	s_waitcnt lgkmcnt(0)
	v_add_u32_e32 v186, 0x10000, v164
	v_add_u32_e32 v187, 0x14000, v164
	v_add_u32_e32 v198, 0x18000, v164
	v_add_u32_e32 v199, 0x1c000, v164
	s_add_u32 s10, s38, 0xffe00080
	s_addc_u32 s11, s39, -1
	s_add_i32 s12, 0, 0x10000
	s_cmpk_eq_i32 s9, 0x7c
	s_cselect_b32 vcc_hi, s97, s11
	s_cselect_b32 vcc_lo, s4, s10
	s_cselect_b32 s47, s5, s8
	s_cselect_b32 s46, s6, s7
	s_add_i32 s13, 0, 0x14000
	ds_read_b128 v[130:133], v186
	ds_read_b128 v[134:137], v186 offset:1024
	ds_read_b128 v[138:141], v186 offset:2048
	ds_read_b128 v[152:155], v186 offset:3072
	ds_read_b128 v[156:159], v187
	ds_read_b128 v[160:163], v187 offset:1024
	ds_read_b128 v[168:171], v187 offset:2048
	ds_read_b128 v[172:175], v187 offset:3072
	s_add_i32 m0, s74, 0xc000
	ds_read_b128 v[176:179], v166
	ds_read_b128 v[180:183], v166 offset:1024
	ds_read_b128 v[206:209], v166 offset:2048
	ds_read_b128 v[210:213], v166 offset:3072
	ds_read_b128 v[214:217], v166 offset:4096
	ds_read_b128 v[218:221], v166 offset:5120
	ds_read_b128 v[236:239], v166 offset:6144
	ds_read_b128 v[240:243], v166 offset:7168
	global_load_lds_dwordx4 v148, s[38:39]
	s_add_i32 m0, s74, 0xe000
	s_nop 0
	global_load_lds_dwordx4 v150, s[38:39]
	s_waitcnt vmcnt(8)
	s_waitcnt lgkmcnt(0)
	s_barrier
	v_mfma_f32_16x16x32_bf16 v[126:129], v[130:133], v[176:179], 0
	v_mfma_f32_16x16x32_bf16 v[126:129], v[134:137], v[180:183], v[126:129]
	v_mfma_f32_16x16x32_bf16 v[110:113], v[130:133], v[206:209], 0
	v_mfma_f32_16x16x32_bf16 v[110:113], v[134:137], v[210:213], v[110:113]
	v_mfma_f32_16x16x32_bf16 v[106:109], v[138:141], v[206:209], 0
	v_mfma_f32_16x16x32_bf16 v[106:109], v[152:155], v[210:213], v[106:109]
	v_mfma_f32_16x16x32_bf16 v[122:125], v[138:141], v[176:179], 0
	v_mfma_f32_16x16x32_bf16 v[122:125], v[152:155], v[180:183], v[122:125]
	v_mfma_f32_16x16x32_bf16 v[90:93], v[138:141], v[214:217], 0
	v_mfma_f32_16x16x32_bf16 v[90:93], v[152:155], v[218:221], v[90:93]
	v_mfma_f32_16x16x32_bf16 v[74:77], v[138:141], v[236:239], 0
	v_mfma_f32_16x16x32_bf16 v[74:77], v[152:155], v[240:243], v[74:77]
	v_mfma_f32_16x16x32_bf16 v[78:81], v[130:133], v[236:239], 0
	v_mfma_f32_16x16x32_bf16 v[78:81], v[134:137], v[240:243], v[78:81]
	v_mfma_f32_16x16x32_bf16 v[94:97], v[130:133], v[214:217], 0
	v_mfma_f32_16x16x32_bf16 v[94:97], v[134:137], v[218:221], v[94:97]
	v_mfma_f32_16x16x32_bf16 v[118:121], v[156:159], v[176:179], 0
	v_mfma_f32_16x16x32_bf16 v[118:121], v[160:163], v[180:183], v[118:121]
	v_mfma_f32_16x16x32_bf16 v[102:105], v[156:159], v[206:209], 0
	v_mfma_f32_16x16x32_bf16 v[102:105], v[160:163], v[210:213], v[102:105]
	v_mfma_f32_16x16x32_bf16 v[98:101], v[168:171], v[206:209], 0
	v_mfma_f32_16x16x32_bf16 v[98:101], v[172:175], v[210:213], v[98:101]
	v_mfma_f32_16x16x32_bf16 v[114:117], v[168:171], v[176:179], 0
	v_mfma_f32_16x16x32_bf16 v[114:117], v[172:175], v[180:183], v[114:117]
	v_mfma_f32_16x16x32_bf16 v[82:85], v[168:171], v[214:217], 0
	v_mfma_f32_16x16x32_bf16 v[82:85], v[172:175], v[218:221], v[82:85]
	v_mfma_f32_16x16x32_bf16 v[66:69], v[168:171], v[236:239], 0
	v_mfma_f32_16x16x32_bf16 v[66:69], v[172:175], v[240:243], v[66:69]
	v_mfma_f32_16x16x32_bf16 v[70:73], v[156:159], v[236:239], 0
	v_mfma_f32_16x16x32_bf16 v[70:73], v[160:163], v[240:243], v[70:73]
	v_mfma_f32_16x16x32_bf16 v[86:89], v[156:159], v[214:217], 0
	v_mfma_f32_16x16x32_bf16 v[86:89], v[160:163], v[218:221], v[86:89]
	s_barrier
	s_add_i32 s10, s12, s67
	s_mov_b32 m0, s10
	ds_read_b128 v[176:179], v166 offset:16384
	ds_read_b128 v[180:183], v166 offset:17408
	ds_read_b128 v[206:209], v166 offset:18432
	ds_read_b128 v[210:213], v166 offset:19456
	ds_read_b128 v[214:217], v166 offset:20480
	ds_read_b128 v[218:221], v166 offset:21504
	ds_read_b128 v[236:239], v166 offset:22528
	ds_read_b128 v[240:243], v166 offset:23552
	global_load_lds_dwordx4 v146, s[46:47]
	s_add_i32 m0, s10, 0x2000
	s_add_u32 s10, s46, 0x80000
	s_addc_u32 s11, s47, 0
	s_add_i32 s12, s13, s67
	global_load_lds_dwordx4 v142, s[46:47]
	s_mov_b32 m0, s12
	s_nop 0
	global_load_lds_dwordx4 v146, s[10:11]
	s_add_i32 m0, s12, 0x2000
	s_nop 0
	global_load_lds_dwordx4 v142, s[10:11]
	s_mov_b32 m0, s74
	s_nop 0
	global_load_lds_dwordx4 v190, vcc
	s_mov_b32 m0, s75
	s_nop 0
	global_load_lds_dwordx4 v144, vcc
	s_waitcnt vmcnt(8)
	s_waitcnt lgkmcnt(0)
	s_barrier
; #define PG8_STAGE(bufoff, gbase, voff) do { _Pragma("unroll") for (int _i = 0; _i < 2; ++_i) \
;         __builtin_amdgcn_global_load_lds((const unsigned*)((const char*)(gbase) + (voff)[_i]), (PG8_LAS unsigned*)(lds + (bufoff) + ldsw + _i * 8192), 16, 0, 0); } while (0)
; #define PG8_LDA(dst, b, h) do { _Pragma("unroll") for (int m = 0; m < 4; ++m) _Pragma("unroll") for (int k = 0; k < 2; ++k) dst[m][k] = *(const PG8_LAS bf16x8*)(lds + PG8_SA(b, h) + aoff + m * 2048 + k * 1024); } while (0)
; #define PG8_LDB(dst, b, h) do { _Pragma("unroll") for (int n = 0; n < 2; ++n) _Pragma("unroll") for (int k = 0; k < 2; ++k) dst[n][k] = *(const PG8_LAS bf16x8*)(lds + PG8_SB(b, h) + boff + n * 2048 + k * 1024); } while (0)
; #define PG8_MMA(ai, bj, At, Bt) do { __builtin_amdgcn_s_setprio(1); _Pragma("unroll") for (int m = 0; m < 4; ++m) _Pragma("unroll") for (int n = 0; n < 2; ++n) _Pragma("unroll") for (int k = 0; k < 2; ++k) \
;         acc[ai][bj][m][n] = __builtin_amdgcn_mfma_f32_16x16x32_bf16(Bt[n][k], At[m][k], acc[ai][bj][m][n], 0, 0, 0); __builtin_amdgcn_s_setprio(0); } while (0)
; #define PG8_WAIT_V(n) asm volatile("s_waitcnt vmcnt(" #n ")" ::: "memory")
; #define PG8_WAIT_L(n) asm volatile("s_waitcnt lgkmcnt(" #n ")" ::: "memory")
; #define PG8_BAR __builtin_amdgcn_s_barrier()
; #define PG8_SCHED __builtin_amdgcn_sched_barrier(0)
; template <class Epi, class Sched, bool ALIGN_EPI = false, bool SP2 = false>
; __device__ __forceinline__ void gemm_phase(PG8_LAS unsigned char* lds, const Gemm g, const Sched& S, const Epi& E) {
;     ...
;             PG8_WAIT_V(8); PG8_WAIT_L(0); PG8_BAR; PG8_MMA(1, 0, At, B0); PG8_MMA(1, 1, At, B1); PG8_BAR; PG8_SCHED;
;             PG8_LDB(B0, 1, 0); PG8_LDB(B1, 1, 1); PG8_SCHED; PG8_LDA(At, 1, 0); PG8_STAGE(PG8_SA(0, 1), a2 + hstep, voffA);
;             PG8_WAIT_V(8); PG8_WAIT_L(0); PG8_BAR; PG8_MMA(0, 0, At, B0); PG8_MMA(0, 1, At, B1); PG8_BAR; PG8_SCHED;
	v_mfma_f32_16x16x32_bf16 v[62:65], v[130:133], v[176:179], 0
	v_mfma_f32_16x16x32_bf16 v[62:65], v[134:137], v[180:183], v[62:65]
	v_mfma_f32_16x16x32_bf16 v[46:49], v[130:133], v[206:209], 0
	v_mfma_f32_16x16x32_bf16 v[46:49], v[134:137], v[210:213], v[46:49]
	v_mfma_f32_16x16x32_bf16 v[42:45], v[138:141], v[206:209], 0
	v_mfma_f32_16x16x32_bf16 v[42:45], v[152:155], v[210:213], v[42:45]
	v_mfma_f32_16x16x32_bf16 v[58:61], v[138:141], v[176:179], 0
	v_mfma_f32_16x16x32_bf16 v[58:61], v[152:155], v[180:183], v[58:61]
	v_mfma_f32_16x16x32_bf16 v[26:29], v[138:141], v[214:217], 0
	v_mfma_f32_16x16x32_bf16 v[26:29], v[152:155], v[218:221], v[26:29]
	v_mfma_f32_16x16x32_bf16 v[10:13], v[138:141], v[236:239], 0
	v_mfma_f32_16x16x32_bf16 v[10:13], v[152:155], v[240:243], v[10:13]
	v_mfma_f32_16x16x32_bf16 v[14:17], v[130:133], v[236:239], 0
	v_mfma_f32_16x16x32_bf16 v[14:17], v[134:137], v[240:243], v[14:17]
	v_mfma_f32_16x16x32_bf16 v[30:33], v[130:133], v[214:217], 0
	v_mfma_f32_16x16x32_bf16 v[30:33], v[134:137], v[218:221], v[30:33]
	v_mfma_f32_16x16x32_bf16 v[54:57], v[156:159], v[176:179], 0
	v_mfma_f32_16x16x32_bf16 v[54:57], v[160:163], v[180:183], v[54:57]
	v_mfma_f32_16x16x32_bf16 v[38:41], v[156:159], v[206:209], 0
	v_mfma_f32_16x16x32_bf16 v[38:41], v[160:163], v[210:213], v[38:41]
	v_mfma_f32_16x16x32_bf16 v[34:37], v[168:171], v[206:209], 0
	v_mfma_f32_16x16x32_bf16 v[34:37], v[172:175], v[210:213], v[34:37]
	v_mfma_f32_16x16x32_bf16 v[50:53], v[168:171], v[176:179], 0
	v_mfma_f32_16x16x32_bf16 v[50:53], v[172:175], v[180:183], v[50:53]
	v_mfma_f32_16x16x32_bf16 v[18:21], v[168:171], v[214:217], 0
	v_mfma_f32_16x16x32_bf16 v[18:21], v[172:175], v[218:221], v[18:21]
	v_mfma_f32_16x16x32_bf16 v[2:5], v[168:171], v[236:239], 0
	v_mfma_f32_16x16x32_bf16 v[2:5], v[172:175], v[240:243], v[2:5]
	v_mfma_f32_16x16x32_bf16 v[6:9], v[156:159], v[236:239], 0
	v_mfma_f32_16x16x32_bf16 v[6:9], v[160:163], v[240:243], v[6:9]
	v_mfma_f32_16x16x32_bf16 v[22:25], v[156:159], v[214:217], 0
	v_mfma_f32_16x16x32_bf16 v[22:25], v[160:163], v[218:221], v[22:25]
	s_barrier
	s_add_i32 s12, 0, 0x18000
	s_add_i32 s13, 0, 0x1c000
	ds_read_b128 v[130:133], v198
	ds_read_b128 v[134:137], v198 offset:1024
	ds_read_b128 v[138:141], v198 offset:2048
	ds_read_b128 v[152:155], v198 offset:3072
	ds_read_b128 v[156:159], v199
	ds_read_b128 v[160:163], v199 offset:1024
	ds_read_b128 v[168:171], v199 offset:2048
	ds_read_b128 v[172:175], v199 offset:3072
	s_add_u32 s10, vcc_lo, 0x200000
	s_addc_u32 s11, vcc_hi, 0
	s_mov_b32 m0, s86
	ds_read_b128 v[176:179], v166 offset:32768
	ds_read_b128 v[180:183], v166 offset:33792
	ds_read_b128 v[206:209], v166 offset:34816
	ds_read_b128 v[210:213], v166 offset:35840
	ds_read_b128 v[214:217], v166 offset:36864
	ds_read_b128 v[218:221], v166 offset:37888
	ds_read_b128 v[236:239], v166 offset:38912
	ds_read_b128 v[240:243], v166 offset:39936
	global_load_lds_dwordx4 v190, s[10:11]
	s_mov_b32 m0, s87
	s_nop 0
	global_load_lds_dwordx4 v144, s[10:11]
	s_waitcnt vmcnt(8)
	s_waitcnt lgkmcnt(0)
	s_barrier
	v_mfma_f32_16x16x32_bf16 v[126:129], v[130:133], v[176:179], v[126:129]
	v_mfma_f32_16x16x32_bf16 v[126:129], v[134:137], v[180:183], v[126:129]
	v_mfma_f32_16x16x32_bf16 v[110:113], v[130:133], v[206:209], v[110:113]
	v_mfma_f32_16x16x32_bf16 v[110:113], v[134:137], v[210:213], v[110:113]
	v_mfma_f32_16x16x32_bf16 v[106:109], v[138:141], v[206:209], v[106:109]
	v_mfma_f32_16x16x32_bf16 v[106:109], v[152:155], v[210:213], v[106:109]
	v_mfma_f32_16x16x32_bf16 v[122:125], v[138:141], v[176:179], v[122:125]
	v_mfma_f32_16x16x32_bf16 v[122:125], v[152:155], v[180:183], v[122:125]
	v_mfma_f32_16x16x32_bf16 v[90:93], v[138:141], v[214:217], v[90:93]
	v_mfma_f32_16x16x32_bf16 v[90:93], v[152:155], v[218:221], v[90:93]
	v_mfma_f32_16x16x32_bf16 v[74:77], v[138:141], v[236:239], v[74:77]
	v_mfma_f32_16x16x32_bf16 v[74:77], v[152:155], v[240:243], v[74:77]
	v_mfma_f32_16x16x32_bf16 v[78:81], v[130:133], v[236:239], v[78:81]
	v_mfma_f32_16x16x32_bf16 v[78:81], v[134:137], v[240:243], v[78:81]
	v_mfma_f32_16x16x32_bf16 v[94:97], v[130:133], v[214:217], v[94:97]
	v_mfma_f32_16x16x32_bf16 v[94:97], v[134:137], v[218:221], v[94:97]
	v_mfma_f32_16x16x32_bf16 v[118:121], v[156:159], v[176:179], v[118:121]
	v_mfma_f32_16x16x32_bf16 v[118:121], v[160:163], v[180:183], v[118:121]
	v_mfma_f32_16x16x32_bf16 v[102:105], v[156:159], v[206:209], v[102:105]
	v_mfma_f32_16x16x32_bf16 v[102:105], v[160:163], v[210:213], v[102:105]
	v_mfma_f32_16x16x32_bf16 v[98:101], v[168:171], v[206:209], v[98:101]
	v_mfma_f32_16x16x32_bf16 v[98:101], v[172:175], v[210:213], v[98:101]
	v_mfma_f32_16x16x32_bf16 v[114:117], v[168:171], v[176:179], v[114:117]
	v_mfma_f32_16x16x32_bf16 v[114:117], v[172:175], v[180:183], v[114:117]
	v_mfma_f32_16x16x32_bf16 v[82:85], v[168:171], v[214:217], v[82:85]
	v_mfma_f32_16x16x32_bf16 v[82:85], v[172:175], v[218:221], v[82:85]
	v_mfma_f32_16x16x32_bf16 v[66:69], v[168:171], v[236:239], v[66:69]
	v_mfma_f32_16x16x32_bf16 v[66:69], v[172:175], v[240:243], v[66:69]
	v_mfma_f32_16x16x32_bf16 v[70:73], v[156:159], v[236:239], v[70:73]
	v_mfma_f32_16x16x32_bf16 v[70:73], v[160:163], v[240:243], v[70:73]
	v_mfma_f32_16x16x32_bf16 v[86:89], v[156:159], v[214:217], v[86:89]
	v_mfma_f32_16x16x32_bf16 v[86:89], v[160:163], v[218:221], v[86:89]
	s_barrier
; #define PG8_STAGE(bufoff, gbase, voff) do { _Pragma("unroll") for (int _i = 0; _i < 2; ++_i) \
;         __builtin_amdgcn_global_load_lds((const unsigned*)((const char*)(gbase) + (voff)[_i]), (PG8_LAS unsigned*)(lds + (bufoff) + ldsw + _i * 8192), 16, 0, 0); } while (0)
; #define PG8_LDA(dst, b, h) do { _Pragma("unroll") for (int m = 0; m < 4; ++m) _Pragma("unroll") for (int k = 0; k < 2; ++k) dst[m][k] = *(const PG8_LAS bf16x8*)(lds + PG8_SA(b, h) + aoff + m * 2048 + k * 1024); } while (0)
; #define PG8_LDB(dst, b, h) do { _Pragma("unroll") for (int n = 0; n < 2; ++n) _Pragma("unroll") for (int k = 0; k < 2; ++k) dst[n][k] = *(const PG8_LAS bf16x8*)(lds + PG8_SB(b, h) + boff + n * 2048 + k * 1024); } while (0)
; #define PG8_BAR __builtin_amdgcn_s_barrier()
; template <class Epi, class Sched, bool ALIGN_EPI = false, bool SP2 = false>
; __device__ __forceinline__ void gemm_phase(PG8_LAS unsigned char* lds, const Gemm g, const Sched& S, const Epi& E) {
;     ...
;             const bool last = (t == nt - 2);
;             const char* a1 = cA + (size_t)(t + 1) * kstep;
;             const char* a2 = last ? nA : cA + (size_t)(t + 2) * kstep; const char* b2 = last ? nB : cB + (size_t)(t + 2) * kstep;
;             const char* a3 = a2 + kstep; const char* b3 = b2 + kstep;
;             if (last && has_next) S.a_ready(nxt);
;             if constexpr (SP2) {
;             PG8_LDB(B0, 0, 0); PG8_LDB(B1, 0, 1); PG8_SCHED; PG8_LDA(At, 0, 0); PG8_STAGE(PG8_SA(1, 1), a1 + hstep, voffA);
;             PG8_WAIT_V(8); PG8_WAIT_L(0); PG8_BAR; PG8_MMA(0, 0, At, B0); PG8_MMA(0, 1, At, B1); PG8_BAR; PG8_SCHED;
;             PG8_LDA(At, 0, 1); PG8_STAGE(PG8_SB(0, 0), b2, voffB); PG8_STAGE(PG8_SB(0, 1), b2 + hstepB, voffB); PG8_STAGE(PG8_SA(0, 0), a2, voffA);
;             PG8_WAIT_V(8); PG8_WAIT_L(0); PG8_BAR; PG8_MMA(1, 0, At, B0); PG8_MMA(1, 1, At, B1); PG8_BAR; PG8_SCHED;
;             PG8_LDB(B0, 1, 0); PG8_LDB(B1, 1, 1); PG8_SCHED; PG8_LDA(At, 1, 0); PG8_STAGE(PG8_SA(0, 1), a2 + hstep, voffA);
;             PG8_WAIT_V(8); PG8_WAIT_L(0); PG8_BAR; PG8_MMA(0, 0, At, B0); PG8_MMA(0, 1, At, B1); PG8_BAR; PG8_SCHED;
;             PG8_LDA(At, 1, 1); PG8_STAGE(PG8_SB(1, 0), b3, voffB); PG8_STAGE(PG8_SB(1, 1), b3 + hstepB, voffB); PG8_STAGE(PG8_SA(1, 0), a3, voffA);
;             PG8_WAIT_V(8); PG8_WAIT_L(0); PG8_BAR; PG8_MMA(1, 0, At, B0); PG8_MMA(1, 1, At, B1); PG8_BAR; PG8_SCHED;
	s_add_i32 s10, s12, s67
	s_mov_b32 m0, s10
	ds_read_b128 v[176:179], v166 offset:49152
	ds_read_b128 v[180:183], v166 offset:50176
	ds_read_b128 v[206:209], v166 offset:51200
	ds_read_b128 v[210:213], v166 offset:52224
	ds_read_b128 v[214:217], v166 offset:53248
	ds_read_b128 v[218:221], v166 offset:54272
	ds_read_b128 v[236:239], v166 offset:55296
	ds_read_b128 v[240:243], v166 offset:56320
	s_add_u32 s100, s46, s60
	s_addc_u32 s101, s47, s61
	global_load_lds_dwordx4 v146, s[100:101]
	s_add_i32 m0, s10, 0x2000
	s_add_u32 s10, s46, 0x80080
	s_addc_u32 s11, s47, 0
	s_add_i32 s12, s13, s67
	global_load_lds_dwordx4 v142, s[100:101]
	s_mov_b32 m0, s12
	s_nop 0
	global_load_lds_dwordx4 v146, s[10:11]
	s_add_i32 m0, s12, 0x2000
	s_nop 0
	global_load_lds_dwordx4 v142, s[10:11]
	s_mov_b32 m0, s82
	s_add_u32 s100, vcc_lo, s60
	s_addc_u32 s101, vcc_hi, s61
	global_load_lds_dwordx4 v190, s[100:101]
	s_mov_b32 m0, s42
	s_nop 0
	global_load_lds_dwordx4 v144, s[100:101]
	s_waitcnt vmcnt(8)
	s_waitcnt lgkmcnt(0)
	s_barrier
	v_mfma_f32_16x16x32_bf16 v[62:65], v[130:133], v[176:179], v[62:65]
	v_mfma_f32_16x16x32_bf16 v[62:65], v[134:137], v[180:183], v[62:65]
	v_mfma_f32_16x16x32_bf16 v[46:49], v[130:133], v[206:209], v[46:49]
	v_mfma_f32_16x16x32_bf16 v[46:49], v[134:137], v[210:213], v[46:49]
	v_mfma_f32_16x16x32_bf16 v[42:45], v[138:141], v[206:209], v[42:45]
	v_mfma_f32_16x16x32_bf16 v[42:45], v[152:155], v[210:213], v[42:45]
	v_mfma_f32_16x16x32_bf16 v[58:61], v[138:141], v[176:179], v[58:61]
	v_mfma_f32_16x16x32_bf16 v[58:61], v[152:155], v[180:183], v[58:61]
	v_mfma_f32_16x16x32_bf16 v[26:29], v[138:141], v[214:217], v[26:29]
	v_mfma_f32_16x16x32_bf16 v[26:29], v[152:155], v[218:221], v[26:29]
	v_mfma_f32_16x16x32_bf16 v[10:13], v[138:141], v[236:239], v[10:13]
	v_mfma_f32_16x16x32_bf16 v[10:13], v[152:155], v[240:243], v[10:13]
	v_mfma_f32_16x16x32_bf16 v[14:17], v[130:133], v[236:239], v[14:17]
	v_mfma_f32_16x16x32_bf16 v[14:17], v[134:137], v[240:243], v[14:17]
	v_mfma_f32_16x16x32_bf16 v[30:33], v[130:133], v[214:217], v[30:33]
	v_mfma_f32_16x16x32_bf16 v[30:33], v[134:137], v[218:221], v[30:33]
	v_mfma_f32_16x16x32_bf16 v[54:57], v[156:159], v[176:179], v[54:57]
	v_mfma_f32_16x16x32_bf16 v[54:57], v[160:163], v[180:183], v[54:57]
	v_mfma_f32_16x16x32_bf16 v[38:41], v[156:159], v[206:209], v[38:41]
	v_mfma_f32_16x16x32_bf16 v[38:41], v[160:163], v[210:213], v[38:41]
	v_mfma_f32_16x16x32_bf16 v[34:37], v[168:171], v[206:209], v[34:37]
	v_mfma_f32_16x16x32_bf16 v[34:37], v[172:175], v[210:213], v[34:37]
	v_mfma_f32_16x16x32_bf16 v[50:53], v[168:171], v[176:179], v[50:53]
	v_mfma_f32_16x16x32_bf16 v[50:53], v[172:175], v[180:183], v[50:53]
	v_mfma_f32_16x16x32_bf16 v[18:21], v[168:171], v[214:217], v[18:21]
	v_mfma_f32_16x16x32_bf16 v[18:21], v[172:175], v[218:221], v[18:21]
	v_mfma_f32_16x16x32_bf16 v[2:5], v[168:171], v[236:239], v[2:5]
	v_mfma_f32_16x16x32_bf16 v[2:5], v[172:175], v[240:243], v[2:5]
	v_mfma_f32_16x16x32_bf16 v[6:9], v[156:159], v[236:239], v[6:9]
	v_mfma_f32_16x16x32_bf16 v[6:9], v[160:163], v[240:243], v[6:9]
	v_mfma_f32_16x16x32_bf16 v[22:25], v[156:159], v[214:217], v[22:25]
	v_mfma_f32_16x16x32_bf16 v[22:25], v[160:163], v[218:221], v[22:25]
	s_barrier
	s_add_i32 s9, s9, 2
	s_add_u32 s38, s38, 0x100
	s_addc_u32 s39, s39, 0
	s_add_u32 s7, s7, 0x100
	s_addc_u32 s8, s8, 0
	s_cmpk_gt_u32 s9, 0x7d
.LBB0_1071:
	s_add_u32 s10, s38, 0xffe00080
	s_addc_u32 s11, s39, -1
	s_add_i32 s12, 0, 0x10000
	s_cmpk_eq_i32 s9, 0x7c
	s_cselect_b32 vcc_hi, s97, s11
	s_cselect_b32 vcc_lo, s4, s10
	s_cselect_b32 s47, s5, s8
	s_cselect_b32 s46, s6, s7
	s_add_i32 s13, 0, 0x14000
	ds_read_b128 v[130:133], v186
	ds_read_b128 v[134:137], v186 offset:1024
	ds_read_b128 v[138:141], v186 offset:2048
	ds_read_b128 v[152:155], v186 offset:3072
	ds_read_b128 v[156:159], v187
	ds_read_b128 v[160:163], v187 offset:1024
	ds_read_b128 v[168:171], v187 offset:2048
	ds_read_b128 v[172:175], v187 offset:3072
	s_add_i32 m0, s74, 0xc000
	ds_read_b128 v[176:179], v166
	ds_read_b128 v[180:183], v166 offset:1024
	ds_read_b128 v[206:209], v166 offset:2048
	ds_read_b128 v[210:213], v166 offset:3072
	ds_read_b128 v[214:217], v166 offset:4096
	ds_read_b128 v[218:221], v166 offset:5120
	ds_read_b128 v[236:239], v166 offset:6144
	ds_read_b128 v[240:243], v166 offset:7168
	global_load_lds_dwordx4 v148, s[38:39]
	s_add_i32 m0, s74, 0xe000
	s_nop 0
	global_load_lds_dwordx4 v150, s[38:39]
	s_waitcnt vmcnt(8)
	s_waitcnt lgkmcnt(0)
	s_barrier
	v_mfma_f32_16x16x32_bf16 v[126:129], v[130:133], v[176:179], v[126:129]
	v_mfma_f32_16x16x32_bf16 v[126:129], v[134:137], v[180:183], v[126:129]
	v_mfma_f32_16x16x32_bf16 v[110:113], v[130:133], v[206:209], v[110:113]
	v_mfma_f32_16x16x32_bf16 v[110:113], v[134:137], v[210:213], v[110:113]
	v_mfma_f32_16x16x32_bf16 v[106:109], v[138:141], v[206:209], v[106:109]
	v_mfma_f32_16x16x32_bf16 v[106:109], v[152:155], v[210:213], v[106:109]
	v_mfma_f32_16x16x32_bf16 v[122:125], v[138:141], v[176:179], v[122:125]
	v_mfma_f32_16x16x32_bf16 v[122:125], v[152:155], v[180:183], v[122:125]
	v_mfma_f32_16x16x32_bf16 v[90:93], v[138:141], v[214:217], v[90:93]
	v_mfma_f32_16x16x32_bf16 v[90:93], v[152:155], v[218:221], v[90:93]
	v_mfma_f32_16x16x32_bf16 v[74:77], v[138:141], v[236:239], v[74:77]
	v_mfma_f32_16x16x32_bf16 v[74:77], v[152:155], v[240:243], v[74:77]
	v_mfma_f32_16x16x32_bf16 v[78:81], v[130:133], v[236:239], v[78:81]
	v_mfma_f32_16x16x32_bf16 v[78:81], v[134:137], v[240:243], v[78:81]
	v_mfma_f32_16x16x32_bf16 v[94:97], v[130:133], v[214:217], v[94:97]
	v_mfma_f32_16x16x32_bf16 v[94:97], v[134:137], v[218:221], v[94:97]
	v_mfma_f32_16x16x32_bf16 v[118:121], v[156:159], v[176:179], v[118:121]
	v_mfma_f32_16x16x32_bf16 v[118:121], v[160:163], v[180:183], v[118:121]
	v_mfma_f32_16x16x32_bf16 v[102:105], v[156:159], v[206:209], v[102:105]
	v_mfma_f32_16x16x32_bf16 v[102:105], v[160:163], v[210:213], v[102:105]
	v_mfma_f32_16x16x32_bf16 v[98:101], v[168:171], v[206:209], v[98:101]
	v_mfma_f32_16x16x32_bf16 v[98:101], v[172:175], v[210:213], v[98:101]
	v_mfma_f32_16x16x32_bf16 v[114:117], v[168:171], v[176:179], v[114:117]
	v_mfma_f32_16x16x32_bf16 v[114:117], v[172:175], v[180:183], v[114:117]
	v_mfma_f32_16x16x32_bf16 v[82:85], v[168:171], v[214:217], v[82:85]
	v_mfma_f32_16x16x32_bf16 v[82:85], v[172:175], v[218:221], v[82:85]
	v_mfma_f32_16x16x32_bf16 v[66:69], v[168:171], v[236:239], v[66:69]
	v_mfma_f32_16x16x32_bf16 v[66:69], v[172:175], v[240:243], v[66:69]
	v_mfma_f32_16x16x32_bf16 v[70:73], v[156:159], v[236:239], v[70:73]
	v_mfma_f32_16x16x32_bf16 v[70:73], v[160:163], v[240:243], v[70:73]
	v_mfma_f32_16x16x32_bf16 v[86:89], v[156:159], v[214:217], v[86:89]
	v_mfma_f32_16x16x32_bf16 v[86:89], v[160:163], v[218:221], v[86:89]
	s_barrier
; #define PG8_STAGE(bufoff, gbase, voff) do { _Pragma("unroll") for (int _i = 0; _i < 2; ++_i) \
;         __builtin_amdgcn_global_load_lds((const unsigned*)((const char*)(gbase) + (voff)[_i]), (PG8_LAS unsigned*)(lds + (bufoff) + ldsw + _i * 8192), 16, 0, 0); } while (0)
; #define PG8_LDA(dst, b, h) do { _Pragma("unroll") for (int m = 0; m < 4; ++m) _Pragma("unroll") for (int k = 0; k < 2; ++k) dst[m][k] = *(const PG8_LAS bf16x8*)(lds + PG8_SA(b, h) + aoff + m * 2048 + k * 1024); } while (0)
; #define PG8_LDB(dst, b, h) do { _Pragma("unroll") for (int n = 0; n < 2; ++n) _Pragma("unroll") for (int k = 0; k < 2; ++k) dst[n][k] = *(const PG8_LAS bf16x8*)(lds + PG8_SB(b, h) + boff + n * 2048 + k * 1024); } while (0)
; #define PG8_MMA(ai, bj, At, Bt) do { __builtin_amdgcn_s_setprio(1); _Pragma("unroll") for (int m = 0; m < 4; ++m) _Pragma("unroll") for (int n = 0; n < 2; ++n) _Pragma("unroll") for (int k = 0; k < 2; ++k) \
;         acc[ai][bj][m][n] = __builtin_amdgcn_mfma_f32_16x16x32_bf16(Bt[n][k], At[m][k], acc[ai][bj][m][n], 0, 0, 0); __builtin_amdgcn_s_setprio(0); } while (0)
; #define PG8_WAIT_V(n) asm volatile("s_waitcnt vmcnt(" #n ")" ::: "memory")
; #define PG8_WAIT_L(n) asm volatile("s_waitcnt lgkmcnt(" #n ")" ::: "memory")
; #define PG8_BAR __builtin_amdgcn_s_barrier()
; #define PG8_SCHED __builtin_amdgcn_sched_barrier(0)
; template <class Epi, class Sched, bool ALIGN_EPI = false, bool SP2 = false>
; __device__ __forceinline__ void gemm_phase(PG8_LAS unsigned char* lds, const Gemm g, const Sched& S, const Epi& E) {
;     ...
;             PG8_LDA(At, 0, 1); PG8_STAGE(PG8_SB(0, 0), b2, voffB); PG8_STAGE(PG8_SB(0, 1), b2 + hstepB, voffB); PG8_STAGE(PG8_SA(0, 0), a2, voffA);
;             PG8_WAIT_V(8); PG8_WAIT_L(0); PG8_BAR; PG8_MMA(1, 0, At, B0); PG8_MMA(1, 1, At, B1); PG8_BAR; PG8_SCHED;
;             PG8_LDB(B0, 1, 0); PG8_LDB(B1, 1, 1); PG8_SCHED; PG8_LDA(At, 1, 0); PG8_STAGE(PG8_SA(0, 1), a2 + hstep, voffA);
	s_add_i32 s10, s12, s67
	s_mov_b32 m0, s10
	ds_read_b128 v[176:179], v166 offset:16384
	ds_read_b128 v[180:183], v166 offset:17408
	ds_read_b128 v[206:209], v166 offset:18432
	ds_read_b128 v[210:213], v166 offset:19456
	ds_read_b128 v[214:217], v166 offset:20480
	ds_read_b128 v[218:221], v166 offset:21504
	ds_read_b128 v[236:239], v166 offset:22528
	ds_read_b128 v[240:243], v166 offset:23552
	global_load_lds_dwordx4 v146, s[46:47]
	s_add_i32 m0, s10, 0x2000
	s_add_u32 s10, s46, 0x80000
	s_addc_u32 s11, s47, 0
	s_add_i32 s12, s13, s67
	global_load_lds_dwordx4 v142, s[46:47]
	s_mov_b32 m0, s12
	s_nop 0
	global_load_lds_dwordx4 v146, s[10:11]
	s_add_i32 m0, s12, 0x2000
	s_nop 0
	global_load_lds_dwordx4 v142, s[10:11]
	s_mov_b32 m0, s74
	s_nop 0
	global_load_lds_dwordx4 v190, vcc
	s_mov_b32 m0, s75
	s_nop 0
	global_load_lds_dwordx4 v144, vcc
	s_waitcnt vmcnt(8)
	s_waitcnt lgkmcnt(0)
	s_barrier
	v_mfma_f32_16x16x32_bf16 v[62:65], v[130:133], v[176:179], v[62:65]
	v_mfma_f32_16x16x32_bf16 v[62:65], v[134:137], v[180:183], v[62:65]
	v_mfma_f32_16x16x32_bf16 v[46:49], v[130:133], v[206:209], v[46:49]
	v_mfma_f32_16x16x32_bf16 v[46:49], v[134:137], v[210:213], v[46:49]
	v_mfma_f32_16x16x32_bf16 v[42:45], v[138:141], v[206:209], v[42:45]
	v_mfma_f32_16x16x32_bf16 v[42:45], v[152:155], v[210:213], v[42:45]
	v_mfma_f32_16x16x32_bf16 v[58:61], v[138:141], v[176:179], v[58:61]
	v_mfma_f32_16x16x32_bf16 v[58:61], v[152:155], v[180:183], v[58:61]
	v_mfma_f32_16x16x32_bf16 v[26:29], v[138:141], v[214:217], v[26:29]
	v_mfma_f32_16x16x32_bf16 v[26:29], v[152:155], v[218:221], v[26:29]
	v_mfma_f32_16x16x32_bf16 v[10:13], v[138:141], v[236:239], v[10:13]
	v_mfma_f32_16x16x32_bf16 v[10:13], v[152:155], v[240:243], v[10:13]
	v_mfma_f32_16x16x32_bf16 v[14:17], v[130:133], v[236:239], v[14:17]
	v_mfma_f32_16x16x32_bf16 v[14:17], v[134:137], v[240:243], v[14:17]
	v_mfma_f32_16x16x32_bf16 v[30:33], v[130:133], v[214:217], v[30:33]
	v_mfma_f32_16x16x32_bf16 v[30:33], v[134:137], v[218:221], v[30:33]
	v_mfma_f32_16x16x32_bf16 v[54:57], v[156:159], v[176:179], v[54:57]
	v_mfma_f32_16x16x32_bf16 v[54:57], v[160:163], v[180:183], v[54:57]
	v_mfma_f32_16x16x32_bf16 v[38:41], v[156:159], v[206:209], v[38:41]
	v_mfma_f32_16x16x32_bf16 v[38:41], v[160:163], v[210:213], v[38:41]
	v_mfma_f32_16x16x32_bf16 v[34:37], v[168:171], v[206:209], v[34:37]
	v_mfma_f32_16x16x32_bf16 v[34:37], v[172:175], v[210:213], v[34:37]
	v_mfma_f32_16x16x32_bf16 v[50:53], v[168:171], v[176:179], v[50:53]
	v_mfma_f32_16x16x32_bf16 v[50:53], v[172:175], v[180:183], v[50:53]
	v_mfma_f32_16x16x32_bf16 v[18:21], v[168:171], v[214:217], v[18:21]
	v_mfma_f32_16x16x32_bf16 v[18:21], v[172:175], v[218:221], v[18:21]
	v_mfma_f32_16x16x32_bf16 v[2:5], v[168:171], v[236:239], v[2:5]
	v_mfma_f32_16x16x32_bf16 v[2:5], v[172:175], v[240:243], v[2:5]
	v_mfma_f32_16x16x32_bf16 v[6:9], v[156:159], v[236:239], v[6:9]
	v_mfma_f32_16x16x32_bf16 v[6:9], v[160:163], v[240:243], v[6:9]
	v_mfma_f32_16x16x32_bf16 v[22:25], v[156:159], v[214:217], v[22:25]
	v_mfma_f32_16x16x32_bf16 v[22:25], v[160:163], v[218:221], v[22:25]
	s_barrier
	s_add_i32 s12, 0, 0x18000
	s_add_i32 s13, 0, 0x1c000
	ds_read_b128 v[130:133], v198
	ds_read_b128 v[134:137], v198 offset:1024
	ds_read_b128 v[138:141], v198 offset:2048
	ds_read_b128 v[152:155], v198 offset:3072
	ds_read_b128 v[156:159], v199
	ds_read_b128 v[160:163], v199 offset:1024
	ds_read_b128 v[168:171], v199 offset:2048
	ds_read_b128 v[172:175], v199 offset:3072
	s_add_u32 s10, vcc_lo, 0x200000
	s_addc_u32 s11, vcc_hi, 0
	s_mov_b32 m0, s86
	ds_read_b128 v[176:179], v166 offset:32768
	ds_read_b128 v[180:183], v166 offset:33792
	ds_read_b128 v[206:209], v166 offset:34816
	ds_read_b128 v[210:213], v166 offset:35840
	ds_read_b128 v[214:217], v166 offset:36864
	ds_read_b128 v[218:221], v166 offset:37888
	ds_read_b128 v[236:239], v166 offset:38912
	ds_read_b128 v[240:243], v166 offset:39936
	global_load_lds_dwordx4 v190, s[10:11]
	s_mov_b32 m0, s87
	s_nop 0
	global_load_lds_dwordx4 v144, s[10:11]
	s_waitcnt vmcnt(8)
	s_waitcnt lgkmcnt(0)
	s_barrier
; #define PG8_STAGE(bufoff, gbase, voff) do { _Pragma("unroll") for (int _i = 0; _i < 2; ++_i) \
;         __builtin_amdgcn_global_load_lds((const unsigned*)((const char*)(gbase) + (voff)[_i]), (PG8_LAS unsigned*)(lds + (bufoff) + ldsw + _i * 8192), 16, 0, 0); } while (0)
; #define PG8_LDA(dst, b, h) do { _Pragma("unroll") for (int m = 0; m < 4; ++m) _Pragma("unroll") for (int k = 0; k < 2; ++k) dst[m][k] = *(const PG8_LAS bf16x8*)(lds + PG8_SA(b, h) + aoff + m * 2048 + k * 1024); } while (0)
; #define PG8_MMA(ai, bj, At, Bt) do { __builtin_amdgcn_s_setprio(1); _Pragma("unroll") for (int m = 0; m < 4; ++m) _Pragma("unroll") for (int n = 0; n < 2; ++n) _Pragma("unroll") for (int k = 0; k < 2; ++k) \
;         acc[ai][bj][m][n] = __builtin_amdgcn_mfma_f32_16x16x32_bf16(Bt[n][k], At[m][k], acc[ai][bj][m][n], 0, 0, 0); __builtin_amdgcn_s_setprio(0); } while (0)
; #define PG8_WAIT_V(n) asm volatile("s_waitcnt vmcnt(" #n ")" ::: "memory")
; #define PG8_WAIT_L(n) asm volatile("s_waitcnt lgkmcnt(" #n ")" ::: "memory")
; #define PG8_BAR __builtin_amdgcn_s_barrier()
; #define PG8_SCHED __builtin_amdgcn_sched_barrier(0)
; template <class Epi, class Sched, bool ALIGN_EPI = false, bool SP2 = false>
; __device__ __forceinline__ void gemm_phase(PG8_LAS unsigned char* lds, const Gemm g, const Sched& S, const Epi& E) {
;     ...
;             PG8_WAIT_V(8); PG8_WAIT_L(0); PG8_BAR; PG8_MMA(0, 0, At, B0); PG8_MMA(0, 1, At, B1); PG8_BAR; PG8_SCHED;
;             PG8_LDA(At, 1, 1); PG8_STAGE(PG8_SB(1, 0), b3, voffB); PG8_STAGE(PG8_SB(1, 1), b3 + hstepB, voffB); PG8_STAGE(PG8_SA(1, 0), a3, voffA);
;             PG8_WAIT_V(8); PG8_WAIT_L(0); PG8_BAR; PG8_MMA(1, 0, At, B0); PG8_MMA(1, 1, At, B1); PG8_BAR; PG8_SCHED;
;     ...
;         if constexpr (ALIGN_EPI) { if (wr == 0) PG8_BAR; }
	v_mfma_f32_16x16x32_bf16 v[126:129], v[130:133], v[176:179], v[126:129]
	v_mfma_f32_16x16x32_bf16 v[126:129], v[134:137], v[180:183], v[126:129]
	v_mfma_f32_16x16x32_bf16 v[110:113], v[130:133], v[206:209], v[110:113]
	v_mfma_f32_16x16x32_bf16 v[110:113], v[134:137], v[210:213], v[110:113]
	v_mfma_f32_16x16x32_bf16 v[106:109], v[138:141], v[206:209], v[106:109]
	v_mfma_f32_16x16x32_bf16 v[106:109], v[152:155], v[210:213], v[106:109]
	v_mfma_f32_16x16x32_bf16 v[122:125], v[138:141], v[176:179], v[122:125]
	v_mfma_f32_16x16x32_bf16 v[122:125], v[152:155], v[180:183], v[122:125]
	v_mfma_f32_16x16x32_bf16 v[90:93], v[138:141], v[214:217], v[90:93]
	v_mfma_f32_16x16x32_bf16 v[90:93], v[152:155], v[218:221], v[90:93]
	v_mfma_f32_16x16x32_bf16 v[74:77], v[138:141], v[236:239], v[74:77]
	v_mfma_f32_16x16x32_bf16 v[74:77], v[152:155], v[240:243], v[74:77]
	v_mfma_f32_16x16x32_bf16 v[78:81], v[130:133], v[236:239], v[78:81]
	v_mfma_f32_16x16x32_bf16 v[78:81], v[134:137], v[240:243], v[78:81]
	v_mfma_f32_16x16x32_bf16 v[94:97], v[130:133], v[214:217], v[94:97]
	v_mfma_f32_16x16x32_bf16 v[94:97], v[134:137], v[218:221], v[94:97]
	v_mfma_f32_16x16x32_bf16 v[118:121], v[156:159], v[176:179], v[118:121]
	v_mfma_f32_16x16x32_bf16 v[118:121], v[160:163], v[180:183], v[118:121]
	v_mfma_f32_16x16x32_bf16 v[102:105], v[156:159], v[206:209], v[102:105]
	v_mfma_f32_16x16x32_bf16 v[102:105], v[160:163], v[210:213], v[102:105]
	v_mfma_f32_16x16x32_bf16 v[98:101], v[168:171], v[206:209], v[98:101]
	v_mfma_f32_16x16x32_bf16 v[98:101], v[172:175], v[210:213], v[98:101]
	v_mfma_f32_16x16x32_bf16 v[114:117], v[168:171], v[176:179], v[114:117]
	v_mfma_f32_16x16x32_bf16 v[114:117], v[172:175], v[180:183], v[114:117]
	v_mfma_f32_16x16x32_bf16 v[82:85], v[168:171], v[214:217], v[82:85]
	v_mfma_f32_16x16x32_bf16 v[82:85], v[172:175], v[218:221], v[82:85]
	v_mfma_f32_16x16x32_bf16 v[66:69], v[168:171], v[236:239], v[66:69]
	v_mfma_f32_16x16x32_bf16 v[66:69], v[172:175], v[240:243], v[66:69]
	v_mfma_f32_16x16x32_bf16 v[70:73], v[156:159], v[236:239], v[70:73]
	v_mfma_f32_16x16x32_bf16 v[70:73], v[160:163], v[240:243], v[70:73]
	v_mfma_f32_16x16x32_bf16 v[86:89], v[156:159], v[214:217], v[86:89]
	v_mfma_f32_16x16x32_bf16 v[86:89], v[160:163], v[218:221], v[86:89]
	s_barrier
	s_add_i32 s10, s12, s67
	s_mov_b32 m0, s10
	ds_read_b128 v[176:179], v166 offset:49152
	ds_read_b128 v[180:183], v166 offset:50176
	ds_read_b128 v[206:209], v166 offset:51200
	ds_read_b128 v[210:213], v166 offset:52224
	ds_read_b128 v[214:217], v166 offset:53248
	ds_read_b128 v[218:221], v166 offset:54272
	ds_read_b128 v[236:239], v166 offset:55296
	ds_read_b128 v[240:243], v166 offset:56320
	s_add_u32 s100, s46, s60
	s_addc_u32 s101, s47, s61
	global_load_lds_dwordx4 v146, s[100:101]
	s_add_i32 m0, s10, 0x2000
	s_add_u32 s10, s46, 0x80080
	s_addc_u32 s11, s47, 0
	s_add_i32 s12, s13, s67
	global_load_lds_dwordx4 v142, s[100:101]
	s_mov_b32 m0, s12
	s_nop 0
	global_load_lds_dwordx4 v146, s[10:11]
	s_add_i32 m0, s12, 0x2000
	s_nop 0
	global_load_lds_dwordx4 v142, s[10:11]
	s_mov_b32 m0, s82
	s_add_u32 s100, vcc_lo, s60
	s_addc_u32 s101, vcc_hi, s61
	global_load_lds_dwordx4 v190, s[100:101]
	s_mov_b32 m0, s42
	s_nop 0
	global_load_lds_dwordx4 v144, s[100:101]
	s_waitcnt vmcnt(8)
	s_waitcnt lgkmcnt(0)
	s_barrier
	v_mfma_f32_16x16x32_bf16 v[62:65], v[130:133], v[176:179], v[62:65]
	v_mfma_f32_16x16x32_bf16 v[62:65], v[134:137], v[180:183], v[62:65]
	v_mfma_f32_16x16x32_bf16 v[46:49], v[130:133], v[206:209], v[46:49]
	v_mfma_f32_16x16x32_bf16 v[46:49], v[134:137], v[210:213], v[46:49]
	v_mfma_f32_16x16x32_bf16 v[42:45], v[138:141], v[206:209], v[42:45]
	v_mfma_f32_16x16x32_bf16 v[42:45], v[152:155], v[210:213], v[42:45]
	v_mfma_f32_16x16x32_bf16 v[58:61], v[138:141], v[176:179], v[58:61]
	v_mfma_f32_16x16x32_bf16 v[58:61], v[152:155], v[180:183], v[58:61]
	v_mfma_f32_16x16x32_bf16 v[26:29], v[138:141], v[214:217], v[26:29]
	v_mfma_f32_16x16x32_bf16 v[26:29], v[152:155], v[218:221], v[26:29]
	v_mfma_f32_16x16x32_bf16 v[10:13], v[138:141], v[236:239], v[10:13]
	v_mfma_f32_16x16x32_bf16 v[10:13], v[152:155], v[240:243], v[10:13]
	v_mfma_f32_16x16x32_bf16 v[14:17], v[130:133], v[236:239], v[14:17]
	v_mfma_f32_16x16x32_bf16 v[14:17], v[134:137], v[240:243], v[14:17]
	v_mfma_f32_16x16x32_bf16 v[30:33], v[130:133], v[214:217], v[30:33]
	v_mfma_f32_16x16x32_bf16 v[30:33], v[134:137], v[218:221], v[30:33]
	v_mfma_f32_16x16x32_bf16 v[54:57], v[156:159], v[176:179], v[54:57]
	v_mfma_f32_16x16x32_bf16 v[54:57], v[160:163], v[180:183], v[54:57]
	v_mfma_f32_16x16x32_bf16 v[38:41], v[156:159], v[206:209], v[38:41]
	v_mfma_f32_16x16x32_bf16 v[38:41], v[160:163], v[210:213], v[38:41]
	v_mfma_f32_16x16x32_bf16 v[34:37], v[168:171], v[206:209], v[34:37]
	v_mfma_f32_16x16x32_bf16 v[34:37], v[172:175], v[210:213], v[34:37]
	v_mfma_f32_16x16x32_bf16 v[50:53], v[168:171], v[176:179], v[50:53]
	v_mfma_f32_16x16x32_bf16 v[50:53], v[172:175], v[180:183], v[50:53]
	v_mfma_f32_16x16x32_bf16 v[18:21], v[168:171], v[214:217], v[18:21]
	v_mfma_f32_16x16x32_bf16 v[18:21], v[172:175], v[218:221], v[18:21]
	v_mfma_f32_16x16x32_bf16 v[2:5], v[168:171], v[236:239], v[2:5]
	v_mfma_f32_16x16x32_bf16 v[2:5], v[172:175], v[240:243], v[2:5]
	v_mfma_f32_16x16x32_bf16 v[6:9], v[156:159], v[236:239], v[6:9]
	v_mfma_f32_16x16x32_bf16 v[6:9], v[160:163], v[240:243], v[6:9]
	v_mfma_f32_16x16x32_bf16 v[22:25], v[156:159], v[214:217], v[22:25]
	v_mfma_f32_16x16x32_bf16 v[22:25], v[160:163], v[218:221], v[22:25]
	s_barrier
	s_add_i32 s9, s9, 2
	s_add_u32 s38, s38, 0x100
	s_addc_u32 s39, s39, 0
	s_add_u32 s7, s7, 0x100
	s_addc_u32 s8, s8, 0
	s_cmpk_gt_u32 s9, 0x7d
	s_cbranch_scc0 .LBB0_1071
	s_and_b64 vcc, exec, s[72:73]
	s_cbranch_vccz .LBB0_1074
	s_barrier

; #define PG8_STAGE(bufoff, gbase, voff) do { _Pragma("unroll") for (int _i = 0; _i < 2; ++_i) \
;         __builtin_amdgcn_global_load_lds((const unsigned*)((const char*)(gbase) + (voff)[_i]), (PG8_LAS unsigned*)(lds + (bufoff) + ldsw + _i * 8192), 16, 0, 0); } while (0)
; #define PG8_LDA(dst, b, h) do { _Pragma("unroll") for (int m = 0; m < 4; ++m) _Pragma("unroll") for (int k = 0; k < 2; ++k) dst[m][k] = *(const PG8_LAS bf16x8*)(lds + PG8_SA(b, h) + aoff + m * 2048 + k * 1024); } while (0)
; #define PG8_LDB(dst, b, h) do { _Pragma("unroll") for (int n = 0; n < 2; ++n) _Pragma("unroll") for (int k = 0; k < 2; ++k) dst[n][k] = *(const PG8_LAS bf16x8*)(lds + PG8_SB(b, h) + boff + n * 2048 + k * 1024); } while (0)
; #define PG8_MMA(ai, bj, At, Bt) do { __builtin_amdgcn_s_setprio(1); _Pragma("unroll") for (int m = 0; m < 4; ++m) _Pragma("unroll") for (int n = 0; n < 2; ++n) _Pragma("unroll") for (int k = 0; k < 2; ++k) \
;         acc[ai][bj][m][n] = __builtin_amdgcn_mfma_f32_16x16x32_bf16(Bt[n][k], At[m][k], acc[ai][bj][m][n], 0, 0, 0); __builtin_amdgcn_s_setprio(0); } while (0)
; #define PG8_BAR __builtin_amdgcn_s_barrier()
; template <class Epi, class Sched, bool ALIGN_EPI = false, bool SP2 = false>
; __device__ __forceinline__ void gemm_phase(PG8_LAS unsigned char* lds, const Gemm g, const Sched& S, const Epi& E) {
;     ...
;         const bool has_next = S.next(ui + 1, nxt);
;         const char* nA = has_next ? (const char*)g.A + (size_t)nxt.pm * tstep : cA; const char* nB = has_next ? (const char*)g.Bt + (size_t)nxt.pn * tstep : cB;
;         for (int t = 0; t < nt; t += 2) {
;             const bool last = (t == nt - 2);
;             const char* a1 = cA + (size_t)(t + 1) * kstep;
;             const char* a2 = last ? nA : cA + (size_t)(t + 2) * kstep; const char* b2 = last ? nB : cB + (size_t)(t + 2) * kstep;
;             const char* a3 = a2 + kstep; const char* b3 = b2 + kstep;
;             if (last && has_next) S.a_ready(nxt);
;             if constexpr (SP2) {
;             PG8_LDB(B0, 0, 0); PG8_LDB(B1, 0, 1); PG8_SCHED; PG8_LDA(At, 0, 0); PG8_STAGE(PG8_SA(1, 1), a1 + hstep, voffA);
;             PG8_WAIT_V(8); PG8_WAIT_L(0); PG8_BAR; PG8_MMA(0, 0, At, B0); PG8_MMA(0, 1, At, B1); PG8_BAR; PG8_SCHED;
;             PG8_LDA(At, 0, 1); PG8_STAGE(PG8_SB(0, 0), b2, voffB); PG8_STAGE(PG8_SB(0, 1), b2 + hstepB, voffB); PG8_STAGE(PG8_SA(0, 0), a2, voffA);
.LBB0_1232:
	s_add_u32 s36, s80, 0x100
	s_addc_u32 s37, s81, 0
	s_ashr_i32 s73, s72, 31
	s_lshl_b64 s[4:5], s[72:73], 20
	s_add_u32 s78, s0, s4
	s_addc_u32 s79, s1, s5
	s_and_b64 s[4:5], s[46:47], exec
	s_cselect_b32 s4, s79, s69
	s_cselect_b32 s5, s78, s68
	s_ashr_i32 s71, s70, 31
	s_lshl_b64 s[6:7], s[70:71], 20
	s_add_u32 s76, s34, s6
	s_addc_u32 s77, s35, s7
	s_and_b64 s[6:7], s[46:47], exec
	s_cselect_b32 s6, s77, s81
	s_cselect_b32 s7, s76, s80
	s_add_u32 s8, s68, 0x80080
	s_addc_u32 s9, s69, 0
	v_lshl_add_u64 v[140:141], s[8:9], 0, v[136:137]
	v_lshl_add_u64 v[142:143], s[8:9], 0, v[138:139]
	s_mov_b32 s8, -2
	s_mov_b64 s[80:81], 0
	v_add_u32_e32 v186, 0x10000, v145
	v_add_u32_e32 v187, 0x14000, v145
	v_add_u32_e32 v198, 0x18000, v145
	v_add_u32_e32 v199, 0x1c000, v145
	s_add_u32 s9, s68, s80
	s_addc_u32 s10, s69, s81
	s_add_u32 s9, s9, 0x100
	s_addc_u32 s10, s10, 0
	s_add_u32 s100, s9, 0x7ff80
	s_addc_u32 s101, s10, 0
	s_add_u32 s11, s36, s80
	s_addc_u32 s12, s37, s81
	s_add_i32 s13, 0, 0x10000
	s_cmpk_eq_i32 s80, 0xf00
	s_cselect_b32 s93, s4, s10
	s_cselect_b32 s92, s5, s9
	s_cselect_b32 s85, s6, s12
	s_cselect_b32 s84, s7, s11
	s_add_i32 s9, 0, 0x14000
	ds_read_b128 v[152:155], v186
	ds_read_b128 v[156:159], v186 offset:1024
	ds_read_b128 v[160:163], v186 offset:2048
	ds_read_b128 v[164:167], v186 offset:3072
	ds_read_b128 v[168:171], v187
	ds_read_b128 v[172:175], v187 offset:1024
	ds_read_b128 v[176:179], v187 offset:2048
	ds_read_b128 v[180:183], v187 offset:3072
	s_add_i32 m0, s51, 0xc000
	ds_read_b128 v[206:209], v151
	ds_read_b128 v[210:213], v151 offset:1024
	ds_read_b128 v[214:217], v151 offset:2048
	ds_read_b128 v[218:221], v151 offset:3072
	ds_read_b128 v[236:239], v151 offset:4096
	ds_read_b128 v[240:243], v151 offset:5120
	ds_read_b128 v[244:247], v151 offset:6144
	ds_read_b128 v[194:197], v151 offset:7168
	global_load_lds_dwordx4 v136, s[100:101]
	s_add_i32 m0, s51, 0xe000
	s_nop 0
	global_load_lds_dwordx4 v138, s[100:101]
	s_waitcnt vmcnt(8)
	s_waitcnt lgkmcnt(0)
	s_barrier
	v_mfma_f32_16x16x32_bf16 v[126:129], v[152:155], v[206:209], 0
	v_mfma_f32_16x16x32_bf16 v[126:129], v[156:159], v[210:213], v[126:129]
	v_mfma_f32_16x16x32_bf16 v[118:121], v[152:155], v[214:217], 0
	v_mfma_f32_16x16x32_bf16 v[118:121], v[156:159], v[218:221], v[118:121]
	v_mfma_f32_16x16x32_bf16 v[114:117], v[160:163], v[214:217], 0
	v_mfma_f32_16x16x32_bf16 v[114:117], v[164:167], v[218:221], v[114:117]
	v_mfma_f32_16x16x32_bf16 v[122:125], v[160:163], v[206:209], 0
	v_mfma_f32_16x16x32_bf16 v[122:125], v[164:167], v[210:213], v[122:125]
	v_mfma_f32_16x16x32_bf16 v[106:109], v[160:163], v[236:239], 0
	v_mfma_f32_16x16x32_bf16 v[106:109], v[164:167], v[240:243], v[106:109]
	v_mfma_f32_16x16x32_bf16 v[98:101], v[160:163], v[244:247], 0
	v_mfma_f32_16x16x32_bf16 v[98:101], v[164:167], v[194:197], v[98:101]
	v_mfma_f32_16x16x32_bf16 v[102:105], v[152:155], v[244:247], 0
	v_mfma_f32_16x16x32_bf16 v[102:105], v[156:159], v[194:197], v[102:105]
	v_mfma_f32_16x16x32_bf16 v[110:113], v[152:155], v[236:239], 0
	v_mfma_f32_16x16x32_bf16 v[110:113], v[156:159], v[240:243], v[110:113]
	v_mfma_f32_16x16x32_bf16 v[94:97], v[168:171], v[206:209], 0
	v_mfma_f32_16x16x32_bf16 v[94:97], v[172:175], v[210:213], v[94:97]
	v_mfma_f32_16x16x32_bf16 v[86:89], v[168:171], v[214:217], 0
	v_mfma_f32_16x16x32_bf16 v[86:89], v[172:175], v[218:221], v[86:89]
	v_mfma_f32_16x16x32_bf16 v[82:85], v[176:179], v[214:217], 0
	v_mfma_f32_16x16x32_bf16 v[82:85], v[180:183], v[218:221], v[82:85]
	v_mfma_f32_16x16x32_bf16 v[90:93], v[176:179], v[206:209], 0
	v_mfma_f32_16x16x32_bf16 v[90:93], v[180:183], v[210:213], v[90:93]
	v_mfma_f32_16x16x32_bf16 v[74:77], v[176:179], v[236:239], 0
	v_mfma_f32_16x16x32_bf16 v[74:77], v[180:183], v[240:243], v[74:77]
	v_mfma_f32_16x16x32_bf16 v[66:69], v[176:179], v[244:247], 0
	v_mfma_f32_16x16x32_bf16 v[66:69], v[180:183], v[194:197], v[66:69]
	v_mfma_f32_16x16x32_bf16 v[70:73], v[168:171], v[244:247], 0
	v_mfma_f32_16x16x32_bf16 v[70:73], v[172:175], v[194:197], v[70:73]
	v_mfma_f32_16x16x32_bf16 v[78:81], v[168:171], v[236:239], 0
	v_mfma_f32_16x16x32_bf16 v[78:81], v[172:175], v[240:243], v[78:81]
	s_barrier
	s_add_i32 s10, s13, s42
	s_mov_b32 m0, s10
	ds_read_b128 v[194:197], v151 offset:16384
	ds_read_b128 v[206:209], v151 offset:17408
	ds_read_b128 v[210:213], v151 offset:18432
	ds_read_b128 v[214:217], v151 offset:19456
	ds_read_b128 v[218:221], v151 offset:20480
	ds_read_b128 v[236:239], v151 offset:21504
	ds_read_b128 v[240:243], v151 offset:22528
	ds_read_b128 v[244:247], v151 offset:23552
	global_load_lds_dwordx4 v130, s[84:85]
	s_add_i32 m0, s10, 0x2000
	s_add_u32 s10, s84, 0x20000
	s_addc_u32 s11, s85, 0
	s_add_i32 s9, s9, s42
	global_load_lds_dwordx4 v134, s[84:85]
	s_mov_b32 m0, s9
	s_nop 0
	global_load_lds_dwordx4 v130, s[10:11]
	s_add_i32 m0, s9, 0x2000
	s_nop 0
	global_load_lds_dwordx4 v134, s[10:11]
	s_mov_b32 m0, s51
	s_nop 0
	global_load_lds_dwordx4 v190, s[92:93]
	s_mov_b32 m0, s67
	s_nop 0
	global_load_lds_dwordx4 v132, s[92:93]
	s_waitcnt vmcnt(8)
	s_waitcnt lgkmcnt(0)
	s_barrier
; #define PG8_STAGE(bufoff, gbase, voff) do { _Pragma("unroll") for (int _i = 0; _i < 2; ++_i) \
;         __builtin_amdgcn_global_load_lds((const unsigned*)((const char*)(gbase) + (voff)[_i]), (PG8_LAS unsigned*)(lds + (bufoff) + ldsw + _i * 8192), 16, 0, 0); } while (0)
; #define PG8_LDA(dst, b, h) do { _Pragma("unroll") for (int m = 0; m < 4; ++m) _Pragma("unroll") for (int k = 0; k < 2; ++k) dst[m][k] = *(const PG8_LAS bf16x8*)(lds + PG8_SA(b, h) + aoff + m * 2048 + k * 1024); } while (0)
; #define PG8_LDB(dst, b, h) do { _Pragma("unroll") for (int n = 0; n < 2; ++n) _Pragma("unroll") for (int k = 0; k < 2; ++k) dst[n][k] = *(const PG8_LAS bf16x8*)(lds + PG8_SB(b, h) + boff + n * 2048 + k * 1024); } while (0)
; #define PG8_MMA(ai, bj, At, Bt) do { __builtin_amdgcn_s_setprio(1); _Pragma("unroll") for (int m = 0; m < 4; ++m) _Pragma("unroll") for (int n = 0; n < 2; ++n) _Pragma("unroll") for (int k = 0; k < 2; ++k) \
;         acc[ai][bj][m][n] = __builtin_amdgcn_mfma_f32_16x16x32_bf16(Bt[n][k], At[m][k], acc[ai][bj][m][n], 0, 0, 0); __builtin_amdgcn_s_setprio(0); } while (0)
; #define PG8_WAIT_V(n) asm volatile("s_waitcnt vmcnt(" #n ")" ::: "memory")
; #define PG8_WAIT_L(n) asm volatile("s_waitcnt lgkmcnt(" #n ")" ::: "memory")
; #define PG8_BAR __builtin_amdgcn_s_barrier()
; #define PG8_SCHED __builtin_amdgcn_sched_barrier(0)
; template <class Epi, class Sched, bool ALIGN_EPI = false, bool SP2 = false>
; __device__ __forceinline__ void gemm_phase(PG8_LAS unsigned char* lds, const Gemm g, const Sched& S, const Epi& E) {
;     ...
;             PG8_WAIT_V(8); PG8_WAIT_L(0); PG8_BAR; PG8_MMA(1, 0, At, B0); PG8_MMA(1, 1, At, B1); PG8_BAR; PG8_SCHED;
;             PG8_LDB(B0, 1, 0); PG8_LDB(B1, 1, 1); PG8_SCHED; PG8_LDA(At, 1, 0); PG8_STAGE(PG8_SA(0, 1), a2 + hstep, voffA);
;             PG8_WAIT_V(8); PG8_WAIT_L(0); PG8_BAR; PG8_MMA(0, 0, At, B0); PG8_MMA(0, 1, At, B1); PG8_BAR; PG8_SCHED;
	v_mfma_f32_16x16x32_bf16 v[62:65], v[152:155], v[194:197], 0
	v_mfma_f32_16x16x32_bf16 v[62:65], v[156:159], v[206:209], v[62:65]
	v_mfma_f32_16x16x32_bf16 v[54:57], v[152:155], v[210:213], 0
	v_mfma_f32_16x16x32_bf16 v[54:57], v[156:159], v[214:217], v[54:57]
	v_mfma_f32_16x16x32_bf16 v[50:53], v[160:163], v[210:213], 0
	v_mfma_f32_16x16x32_bf16 v[50:53], v[164:167], v[214:217], v[50:53]
	v_mfma_f32_16x16x32_bf16 v[58:61], v[160:163], v[194:197], 0
	v_mfma_f32_16x16x32_bf16 v[58:61], v[164:167], v[206:209], v[58:61]
	v_mfma_f32_16x16x32_bf16 v[42:45], v[160:163], v[218:221], 0
	v_mfma_f32_16x16x32_bf16 v[42:45], v[164:167], v[236:239], v[42:45]
	v_mfma_f32_16x16x32_bf16 v[34:37], v[160:163], v[240:243], 0
	v_mfma_f32_16x16x32_bf16 v[34:37], v[164:167], v[244:247], v[34:37]
	v_mfma_f32_16x16x32_bf16 v[38:41], v[152:155], v[240:243], 0
	v_mfma_f32_16x16x32_bf16 v[38:41], v[156:159], v[244:247], v[38:41]
	v_mfma_f32_16x16x32_bf16 v[46:49], v[152:155], v[218:221], 0
	v_mfma_f32_16x16x32_bf16 v[46:49], v[156:159], v[236:239], v[46:49]
	v_mfma_f32_16x16x32_bf16 v[30:33], v[168:171], v[194:197], 0
	v_mfma_f32_16x16x32_bf16 v[30:33], v[172:175], v[206:209], v[30:33]
	v_mfma_f32_16x16x32_bf16 v[22:25], v[168:171], v[210:213], 0
	v_mfma_f32_16x16x32_bf16 v[22:25], v[172:175], v[214:217], v[22:25]
	v_mfma_f32_16x16x32_bf16 v[18:21], v[176:179], v[210:213], 0
	v_mfma_f32_16x16x32_bf16 v[18:21], v[180:183], v[214:217], v[18:21]
	v_mfma_f32_16x16x32_bf16 v[26:29], v[176:179], v[194:197], 0
	v_mfma_f32_16x16x32_bf16 v[26:29], v[180:183], v[206:209], v[26:29]
	v_mfma_f32_16x16x32_bf16 v[10:13], v[176:179], v[218:221], 0
	v_mfma_f32_16x16x32_bf16 v[10:13], v[180:183], v[236:239], v[10:13]
	v_mfma_f32_16x16x32_bf16 v[2:5], v[176:179], v[240:243], 0
	v_mfma_f32_16x16x32_bf16 v[2:5], v[180:183], v[244:247], v[2:5]
	v_mfma_f32_16x16x32_bf16 v[6:9], v[168:171], v[240:243], 0
	v_mfma_f32_16x16x32_bf16 v[6:9], v[172:175], v[244:247], v[6:9]
	v_mfma_f32_16x16x32_bf16 v[14:17], v[168:171], v[218:221], 0
	v_mfma_f32_16x16x32_bf16 v[14:17], v[172:175], v[236:239], v[14:17]
	s_barrier
	s_add_i32 s9, 0, 0x18000
	s_add_i32 s12, 0, 0x1c000
	ds_read_b128 v[152:155], v198
	ds_read_b128 v[156:159], v198 offset:1024
	ds_read_b128 v[160:163], v198 offset:2048
	ds_read_b128 v[164:167], v198 offset:3072
	ds_read_b128 v[168:171], v199
	ds_read_b128 v[172:175], v199 offset:1024
	ds_read_b128 v[176:179], v199 offset:2048
	ds_read_b128 v[180:183], v199 offset:3072
	s_add_u32 s10, s92, 0x80000
	s_addc_u32 s11, s93, 0
	s_mov_b32 m0, s74
	ds_read_b128 v[194:197], v151 offset:32768
	ds_read_b128 v[206:209], v151 offset:33792
	ds_read_b128 v[210:213], v151 offset:34816
	ds_read_b128 v[214:217], v151 offset:35840
	ds_read_b128 v[218:221], v151 offset:36864
	ds_read_b128 v[236:239], v151 offset:37888
	ds_read_b128 v[240:243], v151 offset:38912
	ds_read_b128 v[244:247], v151 offset:39936
	global_load_lds_dwordx4 v190, s[10:11]
	s_mov_b32 m0, s75
	s_nop 0
	global_load_lds_dwordx4 v132, s[10:11]
	s_waitcnt vmcnt(8)
	s_waitcnt lgkmcnt(0)
	s_barrier
	v_mfma_f32_16x16x32_bf16 v[126:129], v[152:155], v[194:197], v[126:129]
	v_mfma_f32_16x16x32_bf16 v[126:129], v[156:159], v[206:209], v[126:129]
	v_mfma_f32_16x16x32_bf16 v[118:121], v[152:155], v[210:213], v[118:121]
	v_mfma_f32_16x16x32_bf16 v[118:121], v[156:159], v[214:217], v[118:121]
	v_mfma_f32_16x16x32_bf16 v[114:117], v[160:163], v[210:213], v[114:117]
	v_mfma_f32_16x16x32_bf16 v[114:117], v[164:167], v[214:217], v[114:117]
	v_mfma_f32_16x16x32_bf16 v[122:125], v[160:163], v[194:197], v[122:125]
	v_mfma_f32_16x16x32_bf16 v[122:125], v[164:167], v[206:209], v[122:125]
	v_mfma_f32_16x16x32_bf16 v[106:109], v[160:163], v[218:221], v[106:109]
	v_mfma_f32_16x16x32_bf16 v[106:109], v[164:167], v[236:239], v[106:109]
	v_mfma_f32_16x16x32_bf16 v[98:101], v[160:163], v[240:243], v[98:101]
	v_mfma_f32_16x16x32_bf16 v[98:101], v[164:167], v[244:247], v[98:101]
	v_mfma_f32_16x16x32_bf16 v[102:105], v[152:155], v[240:243], v[102:105]
	v_mfma_f32_16x16x32_bf16 v[102:105], v[156:159], v[244:247], v[102:105]
	v_mfma_f32_16x16x32_bf16 v[110:113], v[152:155], v[218:221], v[110:113]
	v_mfma_f32_16x16x32_bf16 v[110:113], v[156:159], v[236:239], v[110:113]
	v_mfma_f32_16x16x32_bf16 v[94:97], v[168:171], v[194:197], v[94:97]
	v_mfma_f32_16x16x32_bf16 v[94:97], v[172:175], v[206:209], v[94:97]
	v_mfma_f32_16x16x32_bf16 v[86:89], v[168:171], v[210:213], v[86:89]
	v_mfma_f32_16x16x32_bf16 v[86:89], v[172:175], v[214:217], v[86:89]
	v_mfma_f32_16x16x32_bf16 v[82:85], v[176:179], v[210:213], v[82:85]
	v_mfma_f32_16x16x32_bf16 v[82:85], v[180:183], v[214:217], v[82:85]
	v_mfma_f32_16x16x32_bf16 v[90:93], v[176:179], v[194:197], v[90:93]
	v_mfma_f32_16x16x32_bf16 v[90:93], v[180:183], v[206:209], v[90:93]
	v_mfma_f32_16x16x32_bf16 v[74:77], v[176:179], v[218:221], v[74:77]
	v_mfma_f32_16x16x32_bf16 v[74:77], v[180:183], v[236:239], v[74:77]
	v_mfma_f32_16x16x32_bf16 v[66:69], v[176:179], v[240:243], v[66:69]
	v_mfma_f32_16x16x32_bf16 v[66:69], v[180:183], v[244:247], v[66:69]
	v_mfma_f32_16x16x32_bf16 v[70:73], v[168:171], v[240:243], v[70:73]
	v_mfma_f32_16x16x32_bf16 v[70:73], v[172:175], v[244:247], v[70:73]
	v_mfma_f32_16x16x32_bf16 v[78:81], v[168:171], v[218:221], v[78:81]
	v_mfma_f32_16x16x32_bf16 v[78:81], v[172:175], v[236:239], v[78:81]
	s_barrier
; #define PG8_STAGE(bufoff, gbase, voff) do { _Pragma("unroll") for (int _i = 0; _i < 2; ++_i) \
;         __builtin_amdgcn_global_load_lds((const unsigned*)((const char*)(gbase) + (voff)[_i]), (PG8_LAS unsigned*)(lds + (bufoff) + ldsw + _i * 8192), 16, 0, 0); } while (0)
; #define PG8_LDA(dst, b, h) do { _Pragma("unroll") for (int m = 0; m < 4; ++m) _Pragma("unroll") for (int k = 0; k < 2; ++k) dst[m][k] = *(const PG8_LAS bf16x8*)(lds + PG8_SA(b, h) + aoff + m * 2048 + k * 1024); } while (0)
; #define PG8_LDB(dst, b, h) do { _Pragma("unroll") for (int n = 0; n < 2; ++n) _Pragma("unroll") for (int k = 0; k < 2; ++k) dst[n][k] = *(const PG8_LAS bf16x8*)(lds + PG8_SB(b, h) + boff + n * 2048 + k * 1024); } while (0)
; template <class Epi, class Sched, bool ALIGN_EPI = false, bool SP2 = false>
; __device__ __forceinline__ void gemm_phase(PG8_LAS unsigned char* lds, const Gemm g, const Sched& S, const Epi& E) {
;     ...
;         for (int t = 0; t < nt; t += 2) {
;             const bool last = (t == nt - 2);
;             const char* a1 = cA + (size_t)(t + 1) * kstep;
;             const char* a2 = last ? nA : cA + (size_t)(t + 2) * kstep; const char* b2 = last ? nB : cB + (size_t)(t + 2) * kstep;
;             const char* a3 = a2 + kstep; const char* b3 = b2 + kstep;
;             if (last && has_next) S.a_ready(nxt);
;             if constexpr (SP2) {
;             PG8_LDB(B0, 0, 0); PG8_LDB(B1, 0, 1); PG8_SCHED; PG8_LDA(At, 0, 0); PG8_STAGE(PG8_SA(1, 1), a1 + hstep, voffA);
;             PG8_WAIT_V(8); PG8_WAIT_L(0); PG8_BAR; PG8_MMA(0, 0, At, B0); PG8_MMA(0, 1, At, B1); PG8_BAR; PG8_SCHED;
;             PG8_LDA(At, 0, 1); PG8_STAGE(PG8_SB(0, 0), b2, voffB); PG8_STAGE(PG8_SB(0, 1), b2 + hstepB, voffB); PG8_STAGE(PG8_SA(0, 0), a2, voffA);
;             PG8_WAIT_V(8); PG8_WAIT_L(0); PG8_BAR; PG8_MMA(1, 0, At, B0); PG8_MMA(1, 1, At, B1); PG8_BAR; PG8_SCHED;
;             PG8_LDB(B0, 1, 0); PG8_LDB(B1, 1, 1); PG8_SCHED; PG8_LDA(At, 1, 0); PG8_STAGE(PG8_SA(0, 1), a2 + hstep, voffA);
;             PG8_WAIT_V(8); PG8_WAIT_L(0); PG8_BAR; PG8_MMA(0, 0, At, B0); PG8_MMA(0, 1, At, B1); PG8_BAR; PG8_SCHED;
;             PG8_LDA(At, 1, 1); PG8_STAGE(PG8_SB(1, 0), b3, voffB); PG8_STAGE(PG8_SB(1, 1), b3 + hstepB, voffB); PG8_STAGE(PG8_SA(1, 0), a3, voffA);
;             PG8_WAIT_V(8); PG8_WAIT_L(0); PG8_BAR; PG8_MMA(1, 0, At, B0); PG8_MMA(1, 1, At, B1); PG8_BAR; PG8_SCHED;
	s_add_i32 s9, s9, s42
	s_mov_b32 m0, s9
	ds_read_b128 v[194:197], v151 offset:49152
	ds_read_b128 v[206:209], v151 offset:50176
	ds_read_b128 v[210:213], v151 offset:51200
	ds_read_b128 v[214:217], v151 offset:52224
	ds_read_b128 v[218:221], v151 offset:53248
	ds_read_b128 v[236:239], v151 offset:54272
	ds_read_b128 v[240:243], v151 offset:55296
	ds_read_b128 v[244:247], v151 offset:56320
	s_add_u32 s100, s84, s60
	s_addc_u32 s101, s85, s61
	global_load_lds_dwordx4 v130, s[100:101]
	s_add_i32 m0, s9, 0x2000
	s_add_u32 s10, s84, 0x20080
	s_addc_u32 s11, s85, 0
	s_add_i32 s9, s12, s42
	global_load_lds_dwordx4 v134, s[100:101]
	s_mov_b32 m0, s9
	s_nop 0
	global_load_lds_dwordx4 v130, s[10:11]
	s_add_i32 m0, s9, 0x2000
	s_nop 0
	global_load_lds_dwordx4 v134, s[10:11]
	s_mov_b32 m0, s82
	s_add_u32 s100, s92, s60
	s_addc_u32 s101, s93, s61
	global_load_lds_dwordx4 v190, s[100:101]
	s_mov_b32 m0, s86
	s_nop 0
	global_load_lds_dwordx4 v132, s[100:101]
	s_waitcnt vmcnt(8)
	s_waitcnt lgkmcnt(0)
	s_barrier
	v_mfma_f32_16x16x32_bf16 v[62:65], v[152:155], v[194:197], v[62:65]
	v_mfma_f32_16x16x32_bf16 v[62:65], v[156:159], v[206:209], v[62:65]
	v_mfma_f32_16x16x32_bf16 v[54:57], v[152:155], v[210:213], v[54:57]
	v_mfma_f32_16x16x32_bf16 v[54:57], v[156:159], v[214:217], v[54:57]
	v_mfma_f32_16x16x32_bf16 v[50:53], v[160:163], v[210:213], v[50:53]
	v_mfma_f32_16x16x32_bf16 v[50:53], v[164:167], v[214:217], v[50:53]
	v_mfma_f32_16x16x32_bf16 v[58:61], v[160:163], v[194:197], v[58:61]
	v_mfma_f32_16x16x32_bf16 v[58:61], v[164:167], v[206:209], v[58:61]
	v_mfma_f32_16x16x32_bf16 v[42:45], v[160:163], v[218:221], v[42:45]
	v_mfma_f32_16x16x32_bf16 v[42:45], v[164:167], v[236:239], v[42:45]
	v_mfma_f32_16x16x32_bf16 v[34:37], v[160:163], v[240:243], v[34:37]
	v_mfma_f32_16x16x32_bf16 v[34:37], v[164:167], v[244:247], v[34:37]
	v_mfma_f32_16x16x32_bf16 v[38:41], v[152:155], v[240:243], v[38:41]
	v_mfma_f32_16x16x32_bf16 v[38:41], v[156:159], v[244:247], v[38:41]
	v_mfma_f32_16x16x32_bf16 v[46:49], v[152:155], v[218:221], v[46:49]
	v_mfma_f32_16x16x32_bf16 v[46:49], v[156:159], v[236:239], v[46:49]
	v_mfma_f32_16x16x32_bf16 v[30:33], v[168:171], v[194:197], v[30:33]
	v_mfma_f32_16x16x32_bf16 v[30:33], v[172:175], v[206:209], v[30:33]
	v_mfma_f32_16x16x32_bf16 v[22:25], v[168:171], v[210:213], v[22:25]
	v_mfma_f32_16x16x32_bf16 v[22:25], v[172:175], v[214:217], v[22:25]
	v_mfma_f32_16x16x32_bf16 v[18:21], v[176:179], v[210:213], v[18:21]
	v_mfma_f32_16x16x32_bf16 v[18:21], v[180:183], v[214:217], v[18:21]
	v_mfma_f32_16x16x32_bf16 v[26:29], v[176:179], v[194:197], v[26:29]
	v_mfma_f32_16x16x32_bf16 v[26:29], v[180:183], v[206:209], v[26:29]
	v_mfma_f32_16x16x32_bf16 v[10:13], v[176:179], v[218:221], v[10:13]
	v_mfma_f32_16x16x32_bf16 v[10:13], v[180:183], v[236:239], v[10:13]
	v_mfma_f32_16x16x32_bf16 v[2:5], v[176:179], v[240:243], v[2:5]
	v_mfma_f32_16x16x32_bf16 v[2:5], v[180:183], v[244:247], v[2:5]
	v_mfma_f32_16x16x32_bf16 v[6:9], v[168:171], v[240:243], v[6:9]
	v_mfma_f32_16x16x32_bf16 v[6:9], v[172:175], v[244:247], v[6:9]
	v_mfma_f32_16x16x32_bf16 v[14:17], v[168:171], v[218:221], v[14:17]
	v_mfma_f32_16x16x32_bf16 v[14:17], v[172:175], v[236:239], v[14:17]
	s_barrier
	s_add_i32 s8, s8, 2
	s_add_u32 s80, s80, 0x100
	s_addc_u32 s81, s81, 0
	s_cmp_gt_u32 s8, 29
.LBB0_1233:
	s_add_u32 s9, s68, s80
	s_addc_u32 s10, s69, s81
	s_add_u32 s9, s9, 0x100
	s_addc_u32 s10, s10, 0
	s_add_u32 s100, s9, 0x7ff80
	s_addc_u32 s101, s10, 0
	s_add_u32 s11, s36, s80
	s_addc_u32 s12, s37, s81
	s_add_i32 s13, 0, 0x10000
	s_cmpk_eq_i32 s80, 0xf00
	s_cselect_b32 s93, s4, s10
	s_cselect_b32 s92, s5, s9
	s_cselect_b32 s85, s6, s12
	s_cselect_b32 s84, s7, s11
	s_add_i32 s9, 0, 0x14000
	ds_read_b128 v[152:155], v186
	ds_read_b128 v[156:159], v186 offset:1024
	ds_read_b128 v[160:163], v186 offset:2048
	ds_read_b128 v[164:167], v186 offset:3072
	ds_read_b128 v[168:171], v187
	ds_read_b128 v[172:175], v187 offset:1024
	ds_read_b128 v[176:179], v187 offset:2048
	ds_read_b128 v[180:183], v187 offset:3072
	s_add_i32 m0, s51, 0xc000
	ds_read_b128 v[206:209], v151
	ds_read_b128 v[210:213], v151 offset:1024
	ds_read_b128 v[214:217], v151 offset:2048
	ds_read_b128 v[218:221], v151 offset:3072
	ds_read_b128 v[236:239], v151 offset:4096
	ds_read_b128 v[240:243], v151 offset:5120
	ds_read_b128 v[244:247], v151 offset:6144
	ds_read_b128 v[194:197], v151 offset:7168
	global_load_lds_dwordx4 v136, s[100:101]
	s_add_i32 m0, s51, 0xe000
	s_nop 0
	global_load_lds_dwordx4 v138, s[100:101]
	s_waitcnt vmcnt(8)
	s_waitcnt lgkmcnt(0)
	s_barrier
; #define PG8_STAGE(bufoff, gbase, voff) do { _Pragma("unroll") for (int _i = 0; _i < 2; ++_i) \
;         __builtin_amdgcn_global_load_lds((const unsigned*)((const char*)(gbase) + (voff)[_i]), (PG8_LAS unsigned*)(lds + (bufoff) + ldsw + _i * 8192), 16, 0, 0); } while (0)
; #define PG8_LDA(dst, b, h) do { _Pragma("unroll") for (int m = 0; m < 4; ++m) _Pragma("unroll") for (int k = 0; k < 2; ++k) dst[m][k] = *(const PG8_LAS bf16x8*)(lds + PG8_SA(b, h) + aoff + m * 2048 + k * 1024); } while (0)
; #define PG8_LDB(dst, b, h) do { _Pragma("unroll") for (int n = 0; n < 2; ++n) _Pragma("unroll") for (int k = 0; k < 2; ++k) dst[n][k] = *(const PG8_LAS bf16x8*)(lds + PG8_SB(b, h) + boff + n * 2048 + k * 1024); } while (0)
; template <class Epi, class Sched, bool ALIGN_EPI = false, bool SP2 = false>
; __device__ __forceinline__ void gemm_phase(PG8_LAS unsigned char* lds, const Gemm g, const Sched& S, const Epi& E) {
;     ...
;         for (int t = 0; t < nt; t += 2) {
;             const bool last = (t == nt - 2);
;             const char* a1 = cA + (size_t)(t + 1) * kstep;
;             const char* a2 = last ? nA : cA + (size_t)(t + 2) * kstep; const char* b2 = last ? nB : cB + (size_t)(t + 2) * kstep;
;             const char* a3 = a2 + kstep; const char* b3 = b2 + kstep;
;             if (last && has_next) S.a_ready(nxt);
;             if constexpr (SP2) {
;             PG8_LDB(B0, 0, 0); PG8_LDB(B1, 0, 1); PG8_SCHED; PG8_LDA(At, 0, 0); PG8_STAGE(PG8_SA(1, 1), a1 + hstep, voffA);
;             PG8_WAIT_V(8); PG8_WAIT_L(0); PG8_BAR; PG8_MMA(0, 0, At, B0); PG8_MMA(0, 1, At, B1); PG8_BAR; PG8_SCHED;
;             PG8_LDA(At, 0, 1); PG8_STAGE(PG8_SB(0, 0), b2, voffB); PG8_STAGE(PG8_SB(0, 1), b2 + hstepB, voffB); PG8_STAGE(PG8_SA(0, 0), a2, voffA);
;             PG8_WAIT_V(8); PG8_WAIT_L(0); PG8_BAR; PG8_MMA(1, 0, At, B0); PG8_MMA(1, 1, At, B1); PG8_BAR; PG8_SCHED;
;             PG8_LDB(B0, 1, 0); PG8_LDB(B1, 1, 1); PG8_SCHED; PG8_LDA(At, 1, 0); PG8_STAGE(PG8_SA(0, 1), a2 + hstep, voffA);
;             PG8_WAIT_V(8); PG8_WAIT_L(0); PG8_BAR; PG8_MMA(0, 0, At, B0); PG8_MMA(0, 1, At, B1); PG8_BAR; PG8_SCHED;
;             PG8_LDA(At, 1, 1); PG8_STAGE(PG8_SB(1, 0), b3, voffB); PG8_STAGE(PG8_SB(1, 1), b3 + hstepB, voffB); PG8_STAGE(PG8_SA(1, 0), a3, voffA);
;             PG8_WAIT_V(8); PG8_WAIT_L(0); PG8_BAR; PG8_MMA(1, 0, At, B0); PG8_MMA(1, 1, At, B1); PG8_BAR; PG8_SCHED;
	v_mfma_f32_16x16x32_bf16 v[126:129], v[152:155], v[206:209], v[126:129]
	v_mfma_f32_16x16x32_bf16 v[126:129], v[156:159], v[210:213], v[126:129]
	v_mfma_f32_16x16x32_bf16 v[118:121], v[152:155], v[214:217], v[118:121]
	v_mfma_f32_16x16x32_bf16 v[118:121], v[156:159], v[218:221], v[118:121]
	v_mfma_f32_16x16x32_bf16 v[114:117], v[160:163], v[214:217], v[114:117]
	v_mfma_f32_16x16x32_bf16 v[114:117], v[164:167], v[218:221], v[114:117]
	v_mfma_f32_16x16x32_bf16 v[122:125], v[160:163], v[206:209], v[122:125]
	v_mfma_f32_16x16x32_bf16 v[122:125], v[164:167], v[210:213], v[122:125]
	v_mfma_f32_16x16x32_bf16 v[106:109], v[160:163], v[236:239], v[106:109]
	v_mfma_f32_16x16x32_bf16 v[106:109], v[164:167], v[240:243], v[106:109]
	v_mfma_f32_16x16x32_bf16 v[98:101], v[160:163], v[244:247], v[98:101]
	v_mfma_f32_16x16x32_bf16 v[98:101], v[164:167], v[194:197], v[98:101]
	v_mfma_f32_16x16x32_bf16 v[102:105], v[152:155], v[244:247], v[102:105]
	v_mfma_f32_16x16x32_bf16 v[102:105], v[156:159], v[194:197], v[102:105]
	v_mfma_f32_16x16x32_bf16 v[110:113], v[152:155], v[236:239], v[110:113]
	v_mfma_f32_16x16x32_bf16 v[110:113], v[156:159], v[240:243], v[110:113]
	v_mfma_f32_16x16x32_bf16 v[94:97], v[168:171], v[206:209], v[94:97]
	v_mfma_f32_16x16x32_bf16 v[94:97], v[172:175], v[210:213], v[94:97]
	v_mfma_f32_16x16x32_bf16 v[86:89], v[168:171], v[214:217], v[86:89]
	v_mfma_f32_16x16x32_bf16 v[86:89], v[172:175], v[218:221], v[86:89]
	v_mfma_f32_16x16x32_bf16 v[82:85], v[176:179], v[214:217], v[82:85]
	v_mfma_f32_16x16x32_bf16 v[82:85], v[180:183], v[218:221], v[82:85]
	v_mfma_f32_16x16x32_bf16 v[90:93], v[176:179], v[206:209], v[90:93]
	v_mfma_f32_16x16x32_bf16 v[90:93], v[180:183], v[210:213], v[90:93]
	v_mfma_f32_16x16x32_bf16 v[74:77], v[176:179], v[236:239], v[74:77]
	v_mfma_f32_16x16x32_bf16 v[74:77], v[180:183], v[240:243], v[74:77]
	v_mfma_f32_16x16x32_bf16 v[66:69], v[176:179], v[244:247], v[66:69]
	v_mfma_f32_16x16x32_bf16 v[66:69], v[180:183], v[194:197], v[66:69]
	v_mfma_f32_16x16x32_bf16 v[70:73], v[168:171], v[244:247], v[70:73]
	v_mfma_f32_16x16x32_bf16 v[70:73], v[172:175], v[194:197], v[70:73]
	v_mfma_f32_16x16x32_bf16 v[78:81], v[168:171], v[236:239], v[78:81]
	v_mfma_f32_16x16x32_bf16 v[78:81], v[172:175], v[240:243], v[78:81]
	s_barrier
	s_add_i32 s10, s13, s42
	s_mov_b32 m0, s10
	ds_read_b128 v[194:197], v151 offset:16384
	ds_read_b128 v[206:209], v151 offset:17408
	ds_read_b128 v[210:213], v151 offset:18432
	ds_read_b128 v[214:217], v151 offset:19456
	ds_read_b128 v[218:221], v151 offset:20480
	ds_read_b128 v[236:239], v151 offset:21504
	ds_read_b128 v[240:243], v151 offset:22528
	ds_read_b128 v[244:247], v151 offset:23552
	global_load_lds_dwordx4 v130, s[84:85]
	s_add_i32 m0, s10, 0x2000
	s_add_u32 s10, s84, 0x20000
	s_addc_u32 s11, s85, 0
	s_add_i32 s9, s9, s42
	global_load_lds_dwordx4 v134, s[84:85]
	s_mov_b32 m0, s9
	s_nop 0
	global_load_lds_dwordx4 v130, s[10:11]
	s_add_i32 m0, s9, 0x2000
	s_nop 0
	global_load_lds_dwordx4 v134, s[10:11]
	s_mov_b32 m0, s51
	s_nop 0
	global_load_lds_dwordx4 v190, s[92:93]
	s_mov_b32 m0, s67
	s_nop 0
	global_load_lds_dwordx4 v132, s[92:93]
	s_waitcnt vmcnt(8)
	s_waitcnt lgkmcnt(0)
	s_barrier
	v_mfma_f32_16x16x32_bf16 v[62:65], v[152:155], v[194:197], v[62:65]
	v_mfma_f32_16x16x32_bf16 v[62:65], v[156:159], v[206:209], v[62:65]
	v_mfma_f32_16x16x32_bf16 v[54:57], v[152:155], v[210:213], v[54:57]
	v_mfma_f32_16x16x32_bf16 v[54:57], v[156:159], v[214:217], v[54:57]
	v_mfma_f32_16x16x32_bf16 v[50:53], v[160:163], v[210:213], v[50:53]
	v_mfma_f32_16x16x32_bf16 v[50:53], v[164:167], v[214:217], v[50:53]
	v_mfma_f32_16x16x32_bf16 v[58:61], v[160:163], v[194:197], v[58:61]
	v_mfma_f32_16x16x32_bf16 v[58:61], v[164:167], v[206:209], v[58:61]
	v_mfma_f32_16x16x32_bf16 v[42:45], v[160:163], v[218:221], v[42:45]
	v_mfma_f32_16x16x32_bf16 v[42:45], v[164:167], v[236:239], v[42:45]
	v_mfma_f32_16x16x32_bf16 v[34:37], v[160:163], v[240:243], v[34:37]
	v_mfma_f32_16x16x32_bf16 v[34:37], v[164:167], v[244:247], v[34:37]
	v_mfma_f32_16x16x32_bf16 v[38:41], v[152:155], v[240:243], v[38:41]
	v_mfma_f32_16x16x32_bf16 v[38:41], v[156:159], v[244:247], v[38:41]
	v_mfma_f32_16x16x32_bf16 v[46:49], v[152:155], v[218:221], v[46:49]
	v_mfma_f32_16x16x32_bf16 v[46:49], v[156:159], v[236:239], v[46:49]
	v_mfma_f32_16x16x32_bf16 v[30:33], v[168:171], v[194:197], v[30:33]
	v_mfma_f32_16x16x32_bf16 v[30:33], v[172:175], v[206:209], v[30:33]
	v_mfma_f32_16x16x32_bf16 v[22:25], v[168:171], v[210:213], v[22:25]
	v_mfma_f32_16x16x32_bf16 v[22:25], v[172:175], v[214:217], v[22:25]
	v_mfma_f32_16x16x32_bf16 v[18:21], v[176:179], v[210:213], v[18:21]
	v_mfma_f32_16x16x32_bf16 v[18:21], v[180:183], v[214:217], v[18:21]
	v_mfma_f32_16x16x32_bf16 v[26:29], v[176:179], v[194:197], v[26:29]
	v_mfma_f32_16x16x32_bf16 v[26:29], v[180:183], v[206:209], v[26:29]
	v_mfma_f32_16x16x32_bf16 v[10:13], v[176:179], v[218:221], v[10:13]
	v_mfma_f32_16x16x32_bf16 v[10:13], v[180:183], v[236:239], v[10:13]
	v_mfma_f32_16x16x32_bf16 v[2:5], v[176:179], v[240:243], v[2:5]
	v_mfma_f32_16x16x32_bf16 v[2:5], v[180:183], v[244:247], v[2:5]
	v_mfma_f32_16x16x32_bf16 v[6:9], v[168:171], v[240:243], v[6:9]
	v_mfma_f32_16x16x32_bf16 v[6:9], v[172:175], v[244:247], v[6:9]
	v_mfma_f32_16x16x32_bf16 v[14:17], v[168:171], v[218:221], v[14:17]
	v_mfma_f32_16x16x32_bf16 v[14:17], v[172:175], v[236:239], v[14:17]
	s_barrier
; #define PG8_STAGE(bufoff, gbase, voff) do { _Pragma("unroll") for (int _i = 0; _i < 2; ++_i) \
;         __builtin_amdgcn_global_load_lds((const unsigned*)((const char*)(gbase) + (voff)[_i]), (PG8_LAS unsigned*)(lds + (bufoff) + ldsw + _i * 8192), 16, 0, 0); } while (0)
; #define PG8_LDA(dst, b, h) do { _Pragma("unroll") for (int m = 0; m < 4; ++m) _Pragma("unroll") for (int k = 0; k < 2; ++k) dst[m][k] = *(const PG8_LAS bf16x8*)(lds + PG8_SA(b, h) + aoff + m * 2048 + k * 1024); } while (0)
; #define PG8_LDB(dst, b, h) do { _Pragma("unroll") for (int n = 0; n < 2; ++n) _Pragma("unroll") for (int k = 0; k < 2; ++k) dst[n][k] = *(const PG8_LAS bf16x8*)(lds + PG8_SB(b, h) + boff + n * 2048 + k * 1024); } while (0)
; template <class Epi, class Sched, bool ALIGN_EPI = false, bool SP2 = false>
; __device__ __forceinline__ void gemm_phase(PG8_LAS unsigned char* lds, const Gemm g, const Sched& S, const Epi& E) {
;     ...
;         for (int t = 0; t < nt; t += 2) {
;             const bool last = (t == nt - 2);
;             const char* a1 = cA + (size_t)(t + 1) * kstep;
;             const char* a2 = last ? nA : cA + (size_t)(t + 2) * kstep; const char* b2 = last ? nB : cB + (size_t)(t + 2) * kstep;
;             const char* a3 = a2 + kstep; const char* b3 = b2 + kstep;
;             if (last && has_next) S.a_ready(nxt);
;             if constexpr (SP2) {
;             PG8_LDB(B0, 0, 0); PG8_LDB(B1, 0, 1); PG8_SCHED; PG8_LDA(At, 0, 0); PG8_STAGE(PG8_SA(1, 1), a1 + hstep, voffA);
;             PG8_WAIT_V(8); PG8_WAIT_L(0); PG8_BAR; PG8_MMA(0, 0, At, B0); PG8_MMA(0, 1, At, B1); PG8_BAR; PG8_SCHED;
;             PG8_LDA(At, 0, 1); PG8_STAGE(PG8_SB(0, 0), b2, voffB); PG8_STAGE(PG8_SB(0, 1), b2 + hstepB, voffB); PG8_STAGE(PG8_SA(0, 0), a2, voffA);
;             PG8_WAIT_V(8); PG8_WAIT_L(0); PG8_BAR; PG8_MMA(1, 0, At, B0); PG8_MMA(1, 1, At, B1); PG8_BAR; PG8_SCHED;
;             PG8_LDB(B0, 1, 0); PG8_LDB(B1, 1, 1); PG8_SCHED; PG8_LDA(At, 1, 0); PG8_STAGE(PG8_SA(0, 1), a2 + hstep, voffA);
;             PG8_WAIT_V(8); PG8_WAIT_L(0); PG8_BAR; PG8_MMA(0, 0, At, B0); PG8_MMA(0, 1, At, B1); PG8_BAR; PG8_SCHED;
;             PG8_LDA(At, 1, 1); PG8_STAGE(PG8_SB(1, 0), b3, voffB); PG8_STAGE(PG8_SB(1, 1), b3 + hstepB, voffB); PG8_STAGE(PG8_SA(1, 0), a3, voffA);
;             PG8_WAIT_V(8); PG8_WAIT_L(0); PG8_BAR; PG8_MMA(1, 0, At, B0); PG8_MMA(1, 1, At, B1); PG8_BAR; PG8_SCHED;
	s_add_i32 s9, 0, 0x18000
	s_add_i32 s12, 0, 0x1c000
	ds_read_b128 v[152:155], v198
	ds_read_b128 v[156:159], v198 offset:1024
	ds_read_b128 v[160:163], v198 offset:2048
	ds_read_b128 v[164:167], v198 offset:3072
	ds_read_b128 v[168:171], v199
	ds_read_b128 v[172:175], v199 offset:1024
	ds_read_b128 v[176:179], v199 offset:2048
	ds_read_b128 v[180:183], v199 offset:3072
	s_add_u32 s10, s92, 0x80000
	s_addc_u32 s11, s93, 0
	s_mov_b32 m0, s74
	ds_read_b128 v[194:197], v151 offset:32768
	ds_read_b128 v[206:209], v151 offset:33792
	ds_read_b128 v[210:213], v151 offset:34816
	ds_read_b128 v[214:217], v151 offset:35840
	ds_read_b128 v[218:221], v151 offset:36864
	ds_read_b128 v[236:239], v151 offset:37888
	ds_read_b128 v[240:243], v151 offset:38912
	ds_read_b128 v[244:247], v151 offset:39936
	global_load_lds_dwordx4 v190, s[10:11]
	s_mov_b32 m0, s75
	s_nop 0
	global_load_lds_dwordx4 v132, s[10:11]
	s_waitcnt vmcnt(8)
	s_waitcnt lgkmcnt(0)
	s_barrier
	v_mfma_f32_16x16x32_bf16 v[126:129], v[152:155], v[194:197], v[126:129]
	v_mfma_f32_16x16x32_bf16 v[126:129], v[156:159], v[206:209], v[126:129]
	v_mfma_f32_16x16x32_bf16 v[118:121], v[152:155], v[210:213], v[118:121]
	v_mfma_f32_16x16x32_bf16 v[118:121], v[156:159], v[214:217], v[118:121]
	v_mfma_f32_16x16x32_bf16 v[114:117], v[160:163], v[210:213], v[114:117]
	v_mfma_f32_16x16x32_bf16 v[114:117], v[164:167], v[214:217], v[114:117]
	v_mfma_f32_16x16x32_bf16 v[122:125], v[160:163], v[194:197], v[122:125]
	v_mfma_f32_16x16x32_bf16 v[122:125], v[164:167], v[206:209], v[122:125]
	v_mfma_f32_16x16x32_bf16 v[106:109], v[160:163], v[218:221], v[106:109]
	v_mfma_f32_16x16x32_bf16 v[106:109], v[164:167], v[236:239], v[106:109]
	v_mfma_f32_16x16x32_bf16 v[98:101], v[160:163], v[240:243], v[98:101]
	v_mfma_f32_16x16x32_bf16 v[98:101], v[164:167], v[244:247], v[98:101]
	v_mfma_f32_16x16x32_bf16 v[102:105], v[152:155], v[240:243], v[102:105]
	v_mfma_f32_16x16x32_bf16 v[102:105], v[156:159], v[244:247], v[102:105]
	v_mfma_f32_16x16x32_bf16 v[110:113], v[152:155], v[218:221], v[110:113]
	v_mfma_f32_16x16x32_bf16 v[110:113], v[156:159], v[236:239], v[110:113]
	v_mfma_f32_16x16x32_bf16 v[94:97], v[168:171], v[194:197], v[94:97]
	v_mfma_f32_16x16x32_bf16 v[94:97], v[172:175], v[206:209], v[94:97]
	v_mfma_f32_16x16x32_bf16 v[86:89], v[168:171], v[210:213], v[86:89]
	v_mfma_f32_16x16x32_bf16 v[86:89], v[172:175], v[214:217], v[86:89]
	v_mfma_f32_16x16x32_bf16 v[82:85], v[176:179], v[210:213], v[82:85]
	v_mfma_f32_16x16x32_bf16 v[82:85], v[180:183], v[214:217], v[82:85]
	v_mfma_f32_16x16x32_bf16 v[90:93], v[176:179], v[194:197], v[90:93]
	v_mfma_f32_16x16x32_bf16 v[90:93], v[180:183], v[206:209], v[90:93]
	v_mfma_f32_16x16x32_bf16 v[74:77], v[176:179], v[218:221], v[74:77]
	v_mfma_f32_16x16x32_bf16 v[74:77], v[180:183], v[236:239], v[74:77]
	v_mfma_f32_16x16x32_bf16 v[66:69], v[176:179], v[240:243], v[66:69]
	v_mfma_f32_16x16x32_bf16 v[66:69], v[180:183], v[244:247], v[66:69]
	v_mfma_f32_16x16x32_bf16 v[70:73], v[168:171], v[240:243], v[70:73]
	v_mfma_f32_16x16x32_bf16 v[70:73], v[172:175], v[244:247], v[70:73]
	v_mfma_f32_16x16x32_bf16 v[78:81], v[168:171], v[218:221], v[78:81]
	v_mfma_f32_16x16x32_bf16 v[78:81], v[172:175], v[236:239], v[78:81]
	s_barrier
	s_add_i32 s9, s9, s42
	s_mov_b32 m0, s9
	ds_read_b128 v[194:197], v151 offset:49152
	ds_read_b128 v[206:209], v151 offset:50176
	ds_read_b128 v[210:213], v151 offset:51200
	ds_read_b128 v[214:217], v151 offset:52224
	ds_read_b128 v[218:221], v151 offset:53248
	ds_read_b128 v[236:239], v151 offset:54272
	ds_read_b128 v[240:243], v151 offset:55296
	ds_read_b128 v[244:247], v151 offset:56320
	s_add_u32 s100, s84, s60
	s_addc_u32 s101, s85, s61
	global_load_lds_dwordx4 v130, s[100:101]
	s_add_i32 m0, s9, 0x2000
	s_add_u32 s10, s84, 0x20080
	s_addc_u32 s11, s85, 0
	s_add_i32 s9, s12, s42
	global_load_lds_dwordx4 v134, s[100:101]
	s_mov_b32 m0, s9
	s_nop 0
	global_load_lds_dwordx4 v130, s[10:11]
	s_add_i32 m0, s9, 0x2000
	s_nop 0
	global_load_lds_dwordx4 v134, s[10:11]
	s_mov_b32 m0, s82
	s_add_u32 s100, s92, s60
	s_addc_u32 s101, s93, s61
	global_load_lds_dwordx4 v190, s[100:101]
	s_mov_b32 m0, s86
	s_nop 0
	global_load_lds_dwordx4 v132, s[100:101]
	s_waitcnt vmcnt(8)
	s_waitcnt lgkmcnt(0)
	s_barrier
	v_mfma_f32_16x16x32_bf16 v[62:65], v[152:155], v[194:197], v[62:65]
	v_mfma_f32_16x16x32_bf16 v[62:65], v[156:159], v[206:209], v[62:65]
	v_mfma_f32_16x16x32_bf16 v[54:57], v[152:155], v[210:213], v[54:57]
	v_mfma_f32_16x16x32_bf16 v[54:57], v[156:159], v[214:217], v[54:57]
	v_mfma_f32_16x16x32_bf16 v[50:53], v[160:163], v[210:213], v[50:53]
	v_mfma_f32_16x16x32_bf16 v[50:53], v[164:167], v[214:217], v[50:53]
	v_mfma_f32_16x16x32_bf16 v[58:61], v[160:163], v[194:197], v[58:61]
	v_mfma_f32_16x16x32_bf16 v[58:61], v[164:167], v[206:209], v[58:61]
	v_mfma_f32_16x16x32_bf16 v[42:45], v[160:163], v[218:221], v[42:45]
	v_mfma_f32_16x16x32_bf16 v[42:45], v[164:167], v[236:239], v[42:45]
	v_mfma_f32_16x16x32_bf16 v[34:37], v[160:163], v[240:243], v[34:37]
	v_mfma_f32_16x16x32_bf16 v[34:37], v[164:167], v[244:247], v[34:37]
	v_mfma_f32_16x16x32_bf16 v[38:41], v[152:155], v[240:243], v[38:41]
	v_mfma_f32_16x16x32_bf16 v[38:41], v[156:159], v[244:247], v[38:41]
	v_mfma_f32_16x16x32_bf16 v[46:49], v[152:155], v[218:221], v[46:49]
	v_mfma_f32_16x16x32_bf16 v[46:49], v[156:159], v[236:239], v[46:49]
	v_mfma_f32_16x16x32_bf16 v[30:33], v[168:171], v[194:197], v[30:33]
	v_mfma_f32_16x16x32_bf16 v[30:33], v[172:175], v[206:209], v[30:33]
	v_mfma_f32_16x16x32_bf16 v[22:25], v[168:171], v[210:213], v[22:25]
	v_mfma_f32_16x16x32_bf16 v[22:25], v[172:175], v[214:217], v[22:25]
	v_mfma_f32_16x16x32_bf16 v[18:21], v[176:179], v[210:213], v[18:21]
	v_mfma_f32_16x16x32_bf16 v[18:21], v[180:183], v[214:217], v[18:21]
	v_mfma_f32_16x16x32_bf16 v[26:29], v[176:179], v[194:197], v[26:29]
	v_mfma_f32_16x16x32_bf16 v[26:29], v[180:183], v[206:209], v[26:29]
	v_mfma_f32_16x16x32_bf16 v[10:13], v[176:179], v[218:221], v[10:13]
	v_mfma_f32_16x16x32_bf16 v[10:13], v[180:183], v[236:239], v[10:13]
	v_mfma_f32_16x16x32_bf16 v[2:5], v[176:179], v[240:243], v[2:5]
	v_mfma_f32_16x16x32_bf16 v[2:5], v[180:183], v[244:247], v[2:5]
	v_mfma_f32_16x16x32_bf16 v[6:9], v[168:171], v[240:243], v[6:9]
	v_mfma_f32_16x16x32_bf16 v[6:9], v[172:175], v[244:247], v[6:9]
	v_mfma_f32_16x16x32_bf16 v[14:17], v[168:171], v[218:221], v[14:17]
	v_mfma_f32_16x16x32_bf16 v[14:17], v[172:175], v[236:239], v[14:17]
	s_barrier
	s_add_i32 s8, s8, 2
	s_add_u32 s80, s80, 0x100
	s_addc_u32 s81, s81, 0
	s_cmp_gt_u32 s8, 29
	s_cbranch_scc0 .LBB0_1233
	s_and_b64 vcc, exec, s[62:63]
	s_cbranch_vccz .LBB0_1236
	s_barrier
